# pipeline rebuilt without the chain post-X read hoist (neutral) and with the stage-H token-block read hoist distance raised to 90 instructions
# speedup vs baseline: 1.0004x; 1.0004x over previous
.LBB0_356:
	s_and_b32 s27, s26, 1
	v_lshl_add_u32 v0, s27, 13, v232
	ds_read2_b64 v[36:39], v0 offset1:32
	v_mad_u32_u24 v2, s27, v165, v233
	s_waitcnt lgkmcnt(0)
	v_pk_mul_f32 v[66:67], v[36:37], v[38:39]
	v_xor_b32_e32 v90, 16, v0
	ds_read2_b64 v[38:41], v90 offset0:64 offset1:96
	s_waitcnt lgkmcnt(0)
	v_pk_mul_f32 v[64:65], v[66:67], v[38:39]
	s_nop 0
	v_pk_mul_f32 v[60:61], v[64:65], v[40:41]
	v_xor_b32_e32 v91, 32, v0
	ds_read2_b64 v[38:41], v91 offset0:128 offset1:160
	s_waitcnt lgkmcnt(0)
	v_pk_mul_f32 v[54:55], v[60:61], v[38:39]
	s_nop 0
	v_pk_mul_f32 v[48:49], v[54:55], v[40:41]
	v_xor_b32_e32 v92, 48, v0
	ds_read2_b64 v[38:41], v92 offset0:192 offset1:224
	v_add_u32_e32 v0, 0x800, v0
	v_xor_b32_e32 v91, 32, v0
	ds_read2_b64 v[68:71], v91 offset0:128 offset1:160
	s_waitcnt lgkmcnt(1)
	v_pk_mul_f32 v[44:45], v[48:49], v[38:39]
	s_nop 0
	v_pk_mul_f32 v[38:39], v[44:45], v[40:41]
	ds_read2_b64 v[40:43], v0 offset1:32
	s_waitcnt lgkmcnt(0)
	v_pk_mul_f32 v[58:59], v[38:39], v[40:41]
	s_nop 0
	v_pk_mul_f32 v[50:51], v[58:59], v[42:43]
	v_xor_b32_e32 v90, 16, v0
	ds_read2_b64 v[40:43], v90 offset0:64 offset1:96
	s_waitcnt lgkmcnt(0)
	v_pk_mul_f32 v[46:47], v[50:51], v[40:41]
	s_nop 0
	v_pk_mul_f32 v[42:43], v[46:47], v[42:43]
	v_rcp_f32_e32 v40, v38
	v_pk_mul_f32 v[62:63], v[42:43], v[68:69]
	v_rcp_f32_e32 v41, v39
	v_pk_mul_f32 v[56:57], v[62:63], v[70:71]
	v_xor_b32_e32 v92, 48, v0
	ds_read2_b64 v[68:71], v92 offset0:192 offset1:224
	s_waitcnt lgkmcnt(0)
	v_pk_mul_f32 v[52:53], v[56:57], v[68:69]
	s_nop 0
	v_pk_mul_f32 v[0:1], v[52:53], v[70:71]
	s_and_saveexec_b64 s[28:29], s[4:5]
	s_cbranch_execz .LBB0_358
	v_lshl_add_u32 v253, v177, 1, v2
	v_lshl_add_u32 v252, v184, 1, v2
	ds_read2st64_b32 v[72:73], v253 offset0:96 offset1:112
	ds_read2st64_b32 v[68:69], v253 offset0:64 offset1:80
	ds_read_b32 v84, v253 offset:32768
	ds_read2st64_b32 v[128:129], v252 offset0:64 offset1:80
	ds_read2st64_b32 v[130:131], v252 offset0:96 offset1:112
	v_lshl_add_u32 v74, v177, 1, v2
	s_nop 0
	s_nop 0
	v_rcp_f32_e32 v70, v36
	v_rcp_f32_e32 v71, v37
	s_waitcnt lgkmcnt(4)
	v_cvt_f32_f16_e32 v78, v73
	v_cvt_f32_f16_sdwa v79, v73 dst_sel:DWORD dst_unused:UNUSED_PAD src0_sel:WORD_1
	s_waitcnt lgkmcnt(3)
	v_cvt_f32_f16_e32 v74, v68
	v_cvt_f32_f16_sdwa v75, v68 dst_sel:DWORD dst_unused:UNUSED_PAD src0_sel:WORD_1
	v_cvt_f32_f16_e32 v76, v72
	v_cvt_f32_f16_sdwa v77, v72 dst_sel:DWORD dst_unused:UNUSED_PAD src0_sel:WORD_1
	v_cvt_f32_f16_e32 v72, v69
	v_cvt_f32_f16_sdwa v73, v69 dst_sel:DWORD dst_unused:UNUSED_PAD src0_sel:WORD_1
	v_pk_mul_f32 v[78:79], v[36:37], v[78:79]
	v_pk_mul_f32 v[76:77], v[70:71], v[76:77]
	v_pk_mul_f32 v[70:71], v[70:71], v[74:75]
	v_pk_mul_f32 v[72:73], v[40:41], v[72:73]
	v_pk_mul_f32 v[74:75], v[40:41], v[78:79]
	v_cvt_pk_f16_f32 v68, v78, v79
	v_pk_mul_f32 v[80:81], v[38:39], v[76:77]
	v_pk_mul_f32 v[82:83], v[38:39], v[70:71]
	ds_write2st64_b32 v183, v69, v68 offset1:18
	v_cvt_pk_f16_f32 v68, v72, v73
	v_cvt_pk_f16_f32 v69, v74, v75
	v_pk_mul_f32 v[76:77], v[0:1], v[76:77]
	ds_write2st64_b32 v183, v68, v69 offset0:36 offset1:54
	v_cvt_pk_f16_f32 v68, v80, v81
	v_cvt_pk_f16_f32 v69, v82, v83
	v_lshl_add_u32 v253, v186, 1, v2
	ds_read_b32 v82, v252 offset:32768
	ds_read2st64_b32 v[132:133], v253 offset0:64 offset1:80
	ds_read2st64_b32 v[134:135], v253 offset0:96 offset1:112
	ds_write2st64_b32 v183, v68, v69 offset0:72 offset1:90
	v_cvt_f16_f32_e32 v68, v76
	v_pk_mul_f32 v[70:71], v[0:1], v[70:71]
	v_cvt_f16_f32_e32 v69, v77
	v_cvt_f16_f32_e32 v70, v70
	v_cvt_f16_f32_e32 v71, v71
	ds_write_b16 v178, v68
	ds_write_b16 v178, v69 offset:40
	ds_write_b16 v178, v70 offset:5120
	ds_write_b16 v178, v71 offset:5160
	s_waitcnt lgkmcnt(12)
	ds_write_b16 v178, v84 offset:10240
	v_lshl_add_u32 v74, v184, 1, v2
	v_rcp_f32_e32 v70, v66
	v_rcp_f32_e32 v71, v67
	s_waitcnt lgkmcnt(12)
	v_cvt_f32_f16_e32 v76, v129
	v_cvt_f32_f16_sdwa v77, v129 dst_sel:DWORD dst_unused:UNUSED_PAD src0_sel:WORD_1
	s_waitcnt lgkmcnt(11)
	v_cvt_f32_f16_e32 v80, v131
	v_cvt_f32_f16_sdwa v81, v131 dst_sel:DWORD dst_unused:UNUSED_PAD src0_sel:WORD_1
	v_cvt_f32_f16_e32 v74, v128
	v_cvt_f32_f16_e32 v78, v130
	v_cvt_f32_f16_sdwa v79, v130 dst_sel:DWORD dst_unused:UNUSED_PAD src0_sel:WORD_1
	v_cvt_f32_f16_sdwa v75, v128 dst_sel:DWORD dst_unused:UNUSED_PAD src0_sel:WORD_1
	v_pk_mul_f32 v[36:37], v[36:37], v[76:77]
	v_pk_mul_f32 v[68:69], v[66:67], v[80:81]
	v_pk_mul_f32 v[72:73], v[70:71], v[78:79]
	v_pk_mul_f32 v[70:71], v[70:71], v[74:75]
	v_pk_mul_f32 v[74:75], v[40:41], v[36:37]
	v_pk_mul_f32 v[76:77], v[40:41], v[68:69]
	v_cvt_pk_f16_f32 v36, v36, v37
	v_cvt_pk_f16_f32 v37, v68, v69
	v_pk_mul_f32 v[78:79], v[38:39], v[72:73]
	v_pk_mul_f32 v[80:81], v[38:39], v[70:71]
	ds_write2st64_b32 v185, v36, v37 offset1:18
	v_cvt_pk_f16_f32 v36, v74, v75
	v_cvt_pk_f16_f32 v37, v76, v77
	v_pk_mul_f32 v[72:73], v[0:1], v[72:73]
	ds_write2st64_b32 v185, v36, v37 offset0:36 offset1:54
	v_cvt_pk_f16_f32 v36, v78, v79
	v_cvt_pk_f16_f32 v37, v80, v81
	v_lshl_add_u32 v252, v188, 1, v2
	ds_read_b32 v80, v253 offset:32768
	ds_read2st64_b32 v[136:137], v252 offset0:64 offset1:80
	s_waitcnt lgkmcnt(14)
	ds_read2st64_b32 v[138:139], v252 offset0:96 offset1:112
	s_waitcnt lgkmcnt(14)
	ds_write2st64_b32 v185, v36, v37 offset0:72 offset1:90
	v_cvt_f16_f32_e32 v36, v72
	v_pk_mul_f32 v[70:71], v[0:1], v[70:71]
	v_cvt_f16_f32_e32 v37, v73
	v_cvt_f16_f32_e32 v68, v70
	v_cvt_f16_f32_e32 v69, v71
	s_waitcnt lgkmcnt(14)
	ds_write_b16 v178, v36 offset:2
	s_waitcnt lgkmcnt(14)
	ds_write_b16 v178, v37 offset:42
	s_waitcnt lgkmcnt(14)
	ds_write_b16 v178, v68 offset:5122
	s_waitcnt lgkmcnt(14)
	ds_write_b16 v178, v69 offset:5162
	s_waitcnt lgkmcnt(14)
	ds_write_b16 v178, v82 offset:10242
	v_lshl_add_u32 v72, v186, 1, v2
	v_rcp_f32_e32 v68, v64
	v_rcp_f32_e32 v69, v65
	v_cvt_f32_f16_e32 v74, v133
	v_cvt_f32_f16_sdwa v75, v133 dst_sel:DWORD dst_unused:UNUSED_PAD src0_sel:WORD_1
	v_cvt_f32_f16_e32 v78, v135
	v_cvt_f32_f16_sdwa v79, v135 dst_sel:DWORD dst_unused:UNUSED_PAD src0_sel:WORD_1
	v_cvt_f32_f16_e32 v72, v132
	v_cvt_f32_f16_e32 v76, v134
	v_cvt_f32_f16_sdwa v77, v134 dst_sel:DWORD dst_unused:UNUSED_PAD src0_sel:WORD_1
	v_cvt_f32_f16_sdwa v73, v132 dst_sel:DWORD dst_unused:UNUSED_PAD src0_sel:WORD_1
	v_pk_mul_f32 v[36:37], v[66:67], v[74:75]
	v_pk_mul_f32 v[66:67], v[64:65], v[78:79]
	v_pk_mul_f32 v[70:71], v[68:69], v[76:77]
	v_pk_mul_f32 v[68:69], v[68:69], v[72:73]
	v_pk_mul_f32 v[72:73], v[40:41], v[36:37]
	v_pk_mul_f32 v[74:75], v[40:41], v[66:67]
	v_cvt_pk_f16_f32 v36, v36, v37
	v_cvt_pk_f16_f32 v37, v66, v67
	v_pk_mul_f32 v[76:77], v[38:39], v[70:71]
	v_pk_mul_f32 v[78:79], v[38:39], v[68:69]
	s_waitcnt lgkmcnt(14)
	ds_write2st64_b32 v187, v36, v37 offset1:18
	v_cvt_pk_f16_f32 v36, v72, v73
	v_cvt_pk_f16_f32 v37, v74, v75
	v_pk_mul_f32 v[70:71], v[0:1], v[70:71]
	s_waitcnt lgkmcnt(14)
	ds_write2st64_b32 v187, v36, v37 offset0:36 offset1:54
	v_cvt_pk_f16_f32 v36, v76, v77
	v_cvt_pk_f16_f32 v37, v78, v79
	s_waitcnt lgkmcnt(14)
	ds_read_b32 v78, v252 offset:32768
	s_waitcnt lgkmcnt(14)
	ds_write2st64_b32 v187, v36, v37 offset0:72 offset1:90
	v_cvt_f16_f32_e32 v36, v70
	v_pk_mul_f32 v[68:69], v[0:1], v[68:69]
	v_cvt_f16_f32_e32 v37, v71
	v_cvt_f16_f32_e32 v66, v68
	v_cvt_f16_f32_e32 v67, v69
	s_waitcnt lgkmcnt(14)
	ds_write_b16 v178, v36 offset:4
	s_waitcnt lgkmcnt(14)
	ds_write_b16 v178, v37 offset:44
	s_waitcnt lgkmcnt(14)
	ds_write_b16 v178, v66 offset:5124
	s_waitcnt lgkmcnt(14)
	ds_write_b16 v178, v67 offset:5164
	s_waitcnt lgkmcnt(14)
	ds_write_b16 v178, v80 offset:10244
	v_lshl_add_u32 v70, v188, 1, v2
	v_rcp_f32_e32 v66, v60
	v_rcp_f32_e32 v67, v61
	v_cvt_f32_f16_e32 v72, v137
	v_cvt_f32_f16_sdwa v73, v137 dst_sel:DWORD dst_unused:UNUSED_PAD src0_sel:WORD_1
	v_cvt_f32_f16_e32 v76, v139
	v_cvt_f32_f16_sdwa v77, v139 dst_sel:DWORD dst_unused:UNUSED_PAD src0_sel:WORD_1
	v_cvt_f32_f16_e32 v70, v136
	v_cvt_f32_f16_e32 v74, v138
	v_cvt_f32_f16_sdwa v75, v138 dst_sel:DWORD dst_unused:UNUSED_PAD src0_sel:WORD_1
	v_cvt_f32_f16_sdwa v71, v136 dst_sel:DWORD dst_unused:UNUSED_PAD src0_sel:WORD_1
	v_pk_mul_f32 v[36:37], v[64:65], v[72:73]
	v_pk_mul_f32 v[64:65], v[60:61], v[76:77]
	v_pk_mul_f32 v[68:69], v[66:67], v[74:75]
	v_pk_mul_f32 v[66:67], v[66:67], v[70:71]
	v_pk_mul_f32 v[70:71], v[40:41], v[36:37]
	v_pk_mul_f32 v[72:73], v[40:41], v[64:65]
	v_cvt_pk_f16_f32 v36, v36, v37
	v_cvt_pk_f16_f32 v37, v64, v65
	v_pk_mul_f32 v[74:75], v[38:39], v[68:69]
	v_pk_mul_f32 v[76:77], v[38:39], v[66:67]
	s_waitcnt lgkmcnt(14)
	ds_write2st64_b32 v189, v36, v37 offset1:18
	v_cvt_pk_f16_f32 v36, v70, v71
	v_cvt_pk_f16_f32 v37, v72, v73
	v_pk_mul_f32 v[68:69], v[0:1], v[68:69]
	s_waitcnt lgkmcnt(14)
	ds_write2st64_b32 v189, v36, v37 offset0:36 offset1:54
	v_cvt_pk_f16_f32 v36, v74, v75
	v_cvt_pk_f16_f32 v37, v76, v77
	s_waitcnt lgkmcnt(14)
	ds_write2st64_b32 v189, v36, v37 offset0:72 offset1:90
	v_cvt_f16_f32_e32 v36, v68
	v_pk_mul_f32 v[66:67], v[0:1], v[66:67]
	v_cvt_f16_f32_e32 v37, v69
	v_cvt_f16_f32_e32 v64, v66
	v_cvt_f16_f32_e32 v65, v67
	s_waitcnt lgkmcnt(14)
	ds_write_b16 v178, v36 offset:6
	s_waitcnt lgkmcnt(14)
	ds_write_b16 v178, v37 offset:46
	s_waitcnt lgkmcnt(14)
	ds_write_b16 v178, v64 offset:5126
	s_waitcnt lgkmcnt(14)
	ds_write_b16 v178, v65 offset:5166
	s_nop 0
	s_waitcnt lgkmcnt(13)
	ds_write_b16 v178, v78 offset:10246
	v_perm_b32 v36, v82, v84, s82
	v_perm_b32 v37, v78, v80, s82
	ds_write_b64 v178, v[36:37] offset:10280

.LBB0_362:
	s_or_b64 exec, exec, s[28:29]
	s_waitcnt lgkmcnt(0)
	s_barrier
	ds_read_b128 v[36:39], v214 offset:18432
	ds_read_b128 v[40:43], v214 offset:9216
	ds_read_b128 v[48:51], v214 offset:18496
	s_waitcnt lgkmcnt(1)
	v_mfma_f32_16x16x32_f16 v[52:55], v[40:43], v[36:39], 0
	ds_read_b128 v[56:59], v214 offset:9280
	ds_read_b128 v[60:63], v214 offset:23040
	ds_read_b128 v[64:67], v214 offset:13824
	ds_read_b128 v[68:71], v214 offset:13888
	ds_read_b128 v[72:75], v214 offset:23104
	v_add_u32_e32 v80, 0x1000, v220
	s_waitcnt lgkmcnt(4)
	v_mfma_f32_16x16x32_f16 v[52:55], v[56:59], v[48:51], v[52:55]
	s_nop 0
	s_nop 0
	s_nop 0
	v_mfma_f32_16x16x32_f16 v[44:47], v[36:39], v[40:43], 0
	s_nop 3
	v_cvt_f16_f32_e32 v0, v52
	v_cvt_f16_f32_e32 v1, v54
	v_cvt_f16_f32_e32 v2, v55
	v_mfma_f32_16x16x32_f16 v[44:47], v[48:51], v[56:59], v[44:47]
	v_cndmask_b32_e64 v79, 0, v0, s[12:13]
	v_cvt_f16_f32_e32 v0, v53
	v_cndmask_b32_e64 v54, 0, v1, s[18:19]
	s_waitcnt lgkmcnt(3)
	v_mfma_f32_16x16x32_f16 v[40:43], v[60:63], v[40:43], 0
	v_cndmask_b32_e64 v55, 0, v2, s[22:23]
	s_nop 1
	v_cndmask_b32_e64 v76, 0, v44, s[10:11]
	v_cndmask_b32_e64 v77, 0, v45, s[14:15]
	s_waitcnt lgkmcnt(2)
	v_mfma_f32_16x16x32_f16 v[36:39], v[36:39], v[64:67], 0
	v_cndmask_b32_e64 v52, 0, v46, s[16:17]
	v_cndmask_b32_e64 v78, 0, v47, s[20:21]
	v_cndmask_b32_e64 v53, v0, 0, s[10:11]
	v_mfma_f32_16x16x32_f16 v[44:47], v[60:63], v[64:67], 0
	v_cvt_pk_f16_f32 v1, v52, v78
	v_cvt_pk_f16_f32 v0, v76, v77
	s_nop 0
	s_waitcnt lgkmcnt(0)
	v_mfma_f32_16x16x32_f16 v[60:63], v[72:75], v[56:59], v[40:43]
	v_add_f32_e32 v56, v215, v76
	v_add_f32_e32 v57, v217, v77
	v_add_f32_e32 v58, v218, v52
	v_mfma_f32_16x16x32_f16 v[40:43], v[48:51], v[68:71], v[36:39]
	v_add_f32_e32 v59, v219, v78
	v_cvt_pk_f16_f32 v67, v26, v27
	v_cvt_pk_f16_f32 v66, v24, v25
	v_pack_b32_f16 v37, v54, v55
	v_pack_b32_f16 v36, v79, v53
	s_nop 0
	s_nop 0
	v_mfma_f32_16x16x32_f16 v[52:55], v[72:75], v[68:71], v[44:47]
	ds_read2_b64 v[68:71], v220 offset0:8 offset1:12
	v_cvt_pk_f16_f32 v65, v30, v31
	v_cvt_pk_f16_f32 v64, v28, v29
	v_mfma_f32_16x16x16_f16 v[48:51], v[0:1], v[36:37], 0
	v_cvt_pk_f16_f32 v45, v58, v59
	v_cvt_pk_f16_f32 v44, v56, v57
	s_nop 0
	v_mfma_f32_16x16x16_f16 v[36:39], v[36:37], v[0:1], 0
	s_nop 0
	s_nop 2
	v_cvt_pk_f16_f32 v1, v50, v51
	v_cvt_pk_f16_f32 v0, v48, v49
	s_nop 0
	s_nop 0
	v_cvt_pk_f16_f32 v49, v38, v39
	v_cvt_pk_f16_f32 v48, v36, v37
	v_mfma_f32_16x16x16_f16 v[44:47], v[0:1], v[44:45], v[56:59]
	s_nop 0
	s_nop 0
	s_nop 0
	v_mfma_f32_16x16x16_f16 v[36:39], v[48:49], v[0:1], 0
	v_cvt_pk_f16_f32 v59, v34, v35
	v_cvt_pk_f16_f32 v58, v32, v33
	v_cvt_pk_f16_f32 v57, v22, v23
	v_mfma_f32_16x16x16_f16 v[48:51], v[0:1], v[48:49], 0
	v_cvt_pk_f16_f32 v56, v20, v21
	s_nop 2
	v_cvt_pk_f16_f32 v1, v38, v39
	v_cvt_pk_f16_f32 v0, v36, v37
	v_cvt_pk_f16_f32 v37, v46, v47
	v_cvt_pk_f16_f32 v36, v44, v45
	s_nop 0
	s_nop 0
	v_cvt_f16_f32_e32 v52, v52
	s_add_i32 s27, s26, 1
	v_mfma_f32_16x16x16_f16 v[44:47], v[0:1], v[36:37], v[44:47]
	v_cvt_pk_f16_f32 v37, v50, v51
	v_cvt_pk_f16_f32 v36, v48, v49
	s_nop 0
	s_nop 0
	v_mfma_f32_16x16x16_f16 v[36:39], v[36:37], v[0:1], 0
	s_nop 2
	v_cvt_pk_f16_f32 v1, v46, v47
	v_cvt_pk_f16_f32 v0, v44, v45
	s_nop 2
	v_cvt_pk_f16_f32 v49, v38, v39
	v_cvt_pk_f16_f32 v48, v36, v37
	ds_read2_b64 v[36:39], v220 offset1:4
	s_waitcnt lgkmcnt(0)
	v_mfma_f32_16x16x32_f16 v[36:39], v[36:39], v[56:59], 0
	v_mfma_f32_16x16x16_f16 v[44:47], v[48:49], v[0:1], v[44:47]
	v_cvt_f16_f32_e32 v0, v60
	v_cvt_f16_f32_e32 v1, v61
	v_cvt_f16_f32_e32 v2, v62
	v_cvt_f16_f32_e32 v48, v63
	v_mfma_f32_16x16x32_f16 v[76:79], v[68:71], v[64:67], v[36:39]
	ds_read2_b64 v[72:75], v80 offset0:64 offset1:68
	ds_read2_b64 v[68:71], v80 offset0:72 offset1:76
	s_nop 0
	ds_read2st64_b64 v[36:39], v221 offset0:20 offset1:25
	v_cndmask_b32_e64 v0, 0, v0, s[10:11]
	v_cndmask_b32_e64 v49, 0, v1, s[14:15]
	v_cndmask_b32_e64 v1, 0, v2, s[16:17]
	v_cndmask_b32_e64 v2, 0, v48, s[20:21]
	v_pack_b32_f16 v1, v1, v2
	v_pack_b32_f16 v0, v0, v49
	s_nop 0
	s_waitcnt lgkmcnt(0)
	v_mov_b32_e32 v60, v36
	v_mov_b32_e32 v61, v37
	s_nop 0
	s_nop 0
	v_cvt_f16_f32_e32 v36, v40
	v_cvt_f16_f32_e32 v40, v42
	v_mfma_f32_16x16x16_f16 v[48:51], v[0:1], v[60:61], v[76:79]
	v_cvt_pk_f16_f32 v1, v46, v47
	v_cvt_pk_f16_f32 v0, v44, v45
	v_cvt_f16_f32_e32 v37, v41
	s_nop 0
	s_nop 0
	s_nop 2
	v_cvt_pk_f16_f32 v77, v50, v51
	v_cvt_pk_f16_f32 v76, v48, v49
	v_cndmask_b32_e64 v88, v40, 0, s[18:19]
	v_mfma_f32_16x16x32_f16 v[56:59], v[72:75], v[56:59], 0
	v_cndmask_b32_e64 v36, v36, 0, s[12:13]
	v_cndmask_b32_e64 v37, 0, v37, s[10:11]
	s_nop 0
	v_mfma_f32_16x16x16_f16 v[44:47], v[0:1], v[76:77], 0
	s_nop 0
	v_mfma_f32_16x16x32_f16 v[56:59], v[68:71], v[64:67], v[56:59]
	s_nop 5
	v_cvt_pk_f16_f32 v1, v46, v47
	v_cvt_pk_f16_f32 v0, v44, v45
	ds_read2_b64 v[44:47], v236 offset1:80
	ds_read_b128 v[48:51], v180
	ds_read_b64 v[76:77], v222 offset:5120
	s_waitcnt lgkmcnt(2)
	v_mov_b32_e32 v80, v44
	v_mov_b32_e32 v81, v45
	s_waitcnt lgkmcnt(1)
	v_pk_mul_f32 v[50:51], v[22:23], v[50:51]
	v_pk_mul_f32 v[48:49], v[20:21], v[48:49]
	s_nop 1
	v_mfma_f32_16x16x16_f16 v[48:51], v[80:81], v[0:1], v[48:51]
	v_cvt_f16_f32_e32 v80, v43
	v_cndmask_b32_e64 v89, v80, 0, s[22:23]
	s_waitcnt lgkmcnt(0)
	v_mfma_f32_16x16x16_f16 v[40:43], v[76:77], v[60:61], v[48:51]
	s_nop 3
	ds_read_b128 v[48:51], v180 offset:64
	ds_read_b64 v[44:45], v223 offset:5120
	v_mov_b32_e32 v76, v46
	v_mov_b32_e32 v77, v47
	s_nop 0
	s_waitcnt lgkmcnt(1)
	v_pk_mul_f32 v[50:51], v[34:35], v[50:51]
	v_pk_mul_f32 v[48:49], v[32:33], v[48:49]
	s_nop 0
	s_nop 0
	v_mfma_f32_16x16x16_f16 v[48:51], v[76:77], v[0:1], v[48:51]
	ds_read2_b64 v[76:79], v236 offset0:160 offset1:240
	s_waitcnt lgkmcnt(0)
	v_mov_b32_e32 v84, v76
	v_mfma_f32_16x16x16_f16 v[48:51], v[44:45], v[60:61], v[48:51]
	ds_read_b128 v[44:47], v180 offset:128
	ds_read_b64 v[80:81], v224 offset:5120
	v_mov_b32_e32 v85, v77
	v_pack_b32_f16 v77, v88, v89
	v_mov_b32_e32 v88, v78
	s_waitcnt lgkmcnt(1)
	v_pk_mul_f32 v[46:47], v[30:31], v[46:47]
	v_pk_mul_f32 v[44:45], v[28:29], v[44:45]
	v_mov_b32_e32 v89, v79
	v_pack_b32_f16 v76, v36, v37
	v_mfma_f32_16x16x16_f16 v[44:47], v[84:85], v[0:1], v[44:47]
	v_cndmask_b32_e64 v36, v52, 0, s[12:13]
	v_cvt_f16_f32_e32 v37, v53
	v_cndmask_b32_e64 v37, 0, v37, s[10:11]
	s_waitcnt lgkmcnt(0)
	v_mfma_f32_16x16x16_f16 v[44:47], v[80:81], v[60:61], v[44:47]
	ds_read_b128 v[80:83], v180 offset:192
	ds_read_b64 v[84:85], v225 offset:5120
	v_pack_b32_f16 v72, v36, v37
	ds_read_b128 v[68:71], v226 offset:9216
	ds_read_b128 v[94:97], v226 offset:9280
	s_waitcnt lgkmcnt(3)
	v_pk_mul_f32 v[82:83], v[26:27], v[82:83]
	v_pk_mul_f32 v[80:81], v[24:25], v[80:81]
	ds_read_b128 v[64:67], v226 offset:18432
	ds_read_b128 v[98:101], v226 offset:23104
	v_mfma_f32_16x16x16_f16 v[78:81], v[88:89], v[0:1], v[80:83]
	ds_read_b128 v[90:93], v226 offset:18496
	s_nop 1
	v_cvt_f16_f32_e32 v82, v54
	v_cvt_f16_f32_e32 v83, v55
	s_waitcnt lgkmcnt(5)
	v_mfma_f32_16x16x16_f16 v[52:55], v[84:85], v[60:61], v[78:81]
	ds_read_b128 v[86:89], v226 offset:13824
	s_nop 1
	v_cndmask_b32_e64 v78, v82, 0, s[18:19]
	v_cndmask_b32_e64 v79, v83, 0, s[22:23]
	v_pack_b32_f16 v73, v78, v79
	s_nop 0
	s_nop 0
	v_add_u32_e32 v80, s77, v122
	v_add_u32_e32 v81, s76, v235
	v_mfma_f32_16x16x16_f16 v[56:59], v[76:77], v[0:1], v[56:59]
	ds_read_b128 v[76:79], v226 offset:23040
	v_subrev_u32_e32 v102, 64, v80
	v_add_u32_e32 v0, 0xff, v81
	v_mfma_f32_16x16x16_f16 v[58:61], v[72:73], v[60:61], v[56:59]
	v_cndmask_b32_e64 v0, v0, v102, s[2:3]
	v_add_u32_e32 v0, v0, v173
	v_mad_i64_i32 v[0:1], s[28:29], v0, s91, v[126:127]
	s_waitcnt lgkmcnt(4)
	v_mfma_f32_16x16x32_f16 v[82:85], v[68:71], v[64:67], 0
	s_nop 2
	v_cvt_f16_f32_e32 v2, v58
	v_cvt_f16_f32_e32 v60, v60
	global_store_short v[0:1], v2, off
	v_subrev_u32_e32 v0, 63, v80
	v_xad_u32 v1, v102, -2, v166
	v_cvt_f16_f32_e32 v2, v59
	ds_read_b128 v[56:59], v226 offset:13888
	v_mfma_f32_16x16x32_f16 v[72:75], v[64:67], v[68:71], 0
	v_cndmask_b32_e64 v0, v1, v0, s[2:3]
	v_add_u32_e32 v0, v0, v173
	v_mad_i64_i32 v[0:1], s[28:29], v0, s91, v[126:127]
	s_waitcnt lgkmcnt(2)
	v_mfma_f32_16x16x32_f16 v[62:65], v[64:67], v[86:89], 0
	global_store_short v[0:1], v2, off
	v_subrev_u32_e32 v0, 62, v80
	v_xad_u32 v1, v102, -3, v166
	v_mfma_f32_16x16x32_f16 v[82:85], v[94:97], v[90:93], v[82:85]
	v_cndmask_b32_e64 v36, v1, v0, s[2:3]
	v_add_u32_e32 v36, v36, v173
	s_waitcnt lgkmcnt(1)
	v_mfma_f32_16x16x32_f16 v[68:71], v[76:79], v[68:71], 0
	v_mfma_f32_16x16x32_f16 v[86:89], v[76:79], v[86:89], 0
	s_nop 2
	v_cvt_f16_f32_e32 v1, v82
	v_cvt_f16_f32_e32 v2, v83
	v_cvt_f16_f32_e32 v66, v85
	v_mfma_f32_16x16x32_f16 v[72:75], v[90:93], v[94:97], v[72:75]
	s_nop 0
	v_cndmask_b32_e64 v66, 0, v66, s[22:23]
	s_waitcnt lgkmcnt(0)
	v_mfma_f32_16x16x32_f16 v[76:79], v[90:93], v[56:59], v[62:65]
	s_nop 0
	s_nop 2
	v_cndmask_b32_e64 v0, 0, v72, s[10:11]
	v_cndmask_b32_e64 v37, 0, v73, s[14:15]
	v_cvt_f16_f32_e32 v63, v84
	v_mfma_f32_16x16x32_f16 v[94:97], v[98:101], v[94:97], v[68:71]
	v_cndmask_b32_e64 v64, 0, v74, s[16:17]
	v_cndmask_b32_e64 v65, 0, v75, s[20:21]
	v_cndmask_b32_e64 v63, 0, v63, s[18:19]
	v_cndmask_b32_e64 v68, 0, v1, s[12:13]
	v_cndmask_b32_e64 v69, v2, 0, s[10:11]
	v_add_f32_e32 v62, v215, v0
	v_cvt_pk_f16_f32 v1, v64, v65
	v_cvt_pk_f16_f32 v0, v0, v37
	s_nop 0
	v_pack_b32_f16 v67, v63, v66
	v_pack_b32_f16 v66, v68, v69
	s_nop 0
	s_nop 0
	v_add_f32_e32 v63, v217, v37
	v_add_f32_e32 v64, v218, v64
	v_mfma_f32_16x16x16_f16 v[70:73], v[0:1], v[66:67], 0
	v_add_f32_e32 v65, v219, v65
	v_cvt_pk_f16_f32 v83, v64, v65
	v_cvt_pk_f16_f32 v82, v62, v63
	v_mfma_f32_16x16x16_f16 v[66:69], v[66:67], v[0:1], 0
	s_nop 0
	s_nop 2
	v_cvt_pk_f16_f32 v0, v70, v71
	s_nop 0
	s_nop 0
	v_cvt_pk_f16_f32 v1, v72, v73
	v_cvt_pk_f16_f32 v69, v68, v69
	v_cvt_pk_f16_f32 v68, v66, v67
	v_mfma_f32_16x16x16_f16 v[62:65], v[0:1], v[82:83], v[62:65]
	v_mad_i64_i32 v[36:37], s[28:29], v36, s91, v[126:127]
	global_store_short v[36:37], v60, off
	v_mfma_f32_16x16x16_f16 v[72:75], v[68:69], v[0:1], 0
	v_cvt_f16_f32_e32 v82, v61
	v_subrev_u32_e32 v36, 61, v80
	v_xad_u32 v37, v102, -4, v166
	v_mfma_f32_16x16x16_f16 v[66:69], v[0:1], v[68:69], 0
	s_nop 0
	v_cvt_pk_f16_f32 v71, v64, v65
	s_nop 1
	v_cvt_pk_f16_f32 v1, v74, v75
	v_cvt_pk_f16_f32 v0, v72, v73
	v_mfma_f32_16x16x32_f16 v[56:59], v[98:101], v[56:59], v[86:89]
	v_cvt_pk_f16_f32 v70, v62, v63
	s_nop 0
	s_nop 0
	v_cvt_pk_f16_f32 v85, v68, v69
	v_cvt_pk_f16_f32 v84, v66, v67
	s_nop 0
	s_nop 0
	v_mfma_f32_16x16x16_f16 v[88:91], v[0:1], v[70:71], v[62:65]
	ds_read2_b64 v[68:71], v227 offset1:4
	ds_read2_b64 v[72:75], v227 offset0:8 offset1:12
	v_cndmask_b32_e64 v36, v37, v36, s[2:3]
	v_mfma_f32_16x16x16_f16 v[60:63], v[84:85], v[0:1], 0
	v_add_u32_e32 v83, v36, v173
	s_nop 2
	v_cvt_pk_f16_f32 v1, v90, v91
	v_cvt_pk_f16_f32 v0, v88, v89
	v_cvt_pk_f16_f32 v67, v54, v55
	v_cvt_pk_f16_f32 v66, v52, v53
	v_cvt_pk_f16_f32 v85, v62, v63
	v_cvt_pk_f16_f32 v84, v60, v61
	v_cvt_pk_f16_f32 v63, v50, v51
	v_cvt_pk_f16_f32 v62, v48, v49
	v_cvt_pk_f16_f32 v61, v42, v43
	v_cvt_pk_f16_f32 v60, v40, v41
	v_cvt_pk_f16_f32 v65, v46, v47
	v_cvt_pk_f16_f32 v64, v44, v45
	s_waitcnt lgkmcnt(1)
	v_mfma_f32_16x16x32_f16 v[68:71], v[68:71], v[60:63], 0
	v_add_u32_e32 v36, 0x1000, v227
	s_nop 0
	v_cvt_f16_f32_e32 v76, v76
	s_waitcnt lgkmcnt(0)
	v_mfma_f32_16x16x32_f16 v[98:101], v[72:75], v[64:67], v[68:71]
	ds_read2_b64 v[72:75], v36 offset0:64 offset1:68
	s_nop 1
	ds_read2_b64 v[68:71], v36 offset0:72 offset1:76
	v_cvt_f16_f32_e32 v36, v97
	v_cvt_f16_f32_e32 v97, v77
	v_mfma_f32_16x16x16_f16 v[84:87], v[84:85], v[0:1], v[88:91]
	v_cvt_f16_f32_e32 v0, v94
	v_cvt_f16_f32_e32 v1, v95
	v_cvt_f16_f32_e32 v2, v96
	v_cndmask_b32_e64 v96, v76, 0, s[12:13]
	v_cndmask_b32_e64 v0, 0, v0, s[10:11]
	v_cndmask_b32_e64 v37, 0, v1, s[14:15]
	v_cndmask_b32_e64 v1, 0, v2, s[16:17]
	v_cndmask_b32_e64 v2, 0, v36, s[20:21]
	v_pack_b32_f16 v1, v1, v2
	v_pack_b32_f16 v0, v0, v37
	s_nop 0
	v_mov_b32_e32 v36, v38
	v_mov_b32_e32 v37, v39
	s_nop 0
	s_nop 0
	v_mov_b32_e32 v94, v3
	v_mov_b32_e32 v95, v3
	v_mfma_f32_16x16x16_f16 v[88:91], v[0:1], v[36:37], v[98:101]
	v_cvt_pk_f16_f32 v1, v86, v87
	v_cvt_pk_f16_f32 v0, v84, v85
	v_cvt_f16_f32_e32 v56, v56
	v_cvt_f16_f32_e32 v98, v78
	v_cvt_f16_f32_e32 v99, v79
	s_nop 2
	v_cvt_pk_f16_f32 v91, v90, v91
	v_cvt_pk_f16_f32 v90, v88, v89
	v_cndmask_b32_e64 v97, 0, v97, s[10:11]
	v_cndmask_b32_e64 v98, v98, 0, s[18:19]
	v_mfma_f32_16x16x16_f16 v[84:87], v[0:1], v[90:91], 0
	v_add_u32_e32 v2, 0x800, v236
	v_mov_b32_e32 v90, v3
	v_mov_b32_e32 v91, v3
	v_cndmask_b32_e64 v99, v99, 0, s[22:23]
	s_nop 3
	v_cvt_pk_f16_f32 v1, v86, v87
	v_cvt_pk_f16_f32 v0, v84, v85
	ds_read2_b64 v[84:87], v2 offset0:64 offset1:144
	ds_read_b128 v[76:79], v180 offset:256
	ds_read_b64 v[88:89], v228 offset:5120
	s_nop 0
	s_waitcnt lgkmcnt(2)
	v_mov_b32_e32 v92, v84
	v_mov_b32_e32 v93, v85
	s_waitcnt lgkmcnt(1)
	v_pk_mul_f32 v[42:43], v[42:43], v[78:79]
	v_pk_mul_f32 v[40:41], v[40:41], v[76:77]
	ds_read_b128 v[76:79], v180 offset:320
	ds_read_b64 v[84:85], v229 offset:5120
	v_mfma_f32_16x16x16_f16 v[40:43], v[92:93], v[0:1], v[40:43]
	s_waitcnt lgkmcnt(1)
	v_pk_mul_f32 v[48:49], v[48:49], v[76:77]
	v_add_u32_e32 v76, 0xc00, v236
	v_mfma_f32_16x16x16_f16 v[40:43], v[88:89], v[36:37], v[40:43]
	v_mov_b32_e32 v88, v86
	v_mov_b32_e32 v89, v87
	v_pk_mul_f32 v[50:51], v[50:51], v[78:79]
	s_nop 0
	s_nop 0
	ds_read2_b64 v[76:79], v76 offset0:96 offset1:176
	v_mfma_f32_16x16x16_f16 v[48:51], v[88:89], v[0:1], v[48:51]
	s_waitcnt lgkmcnt(0)
	v_mov_b32_e32 v92, v76
	v_mfma_f32_16x16x16_f16 v[48:51], v[84:85], v[36:37], v[48:51]
	ds_read_b128 v[84:87], v180 offset:384
	ds_read_b64 v[88:89], v230 offset:5120
	v_mov_b32_e32 v93, v77
	v_pack_b32_f16 v76, v96, v97
	v_cndmask_b32_e64 v96, v56, 0, s[12:13]
	s_waitcnt lgkmcnt(1)
	v_pk_mul_f32 v[46:47], v[46:47], v[86:87]
	v_pk_mul_f32 v[44:45], v[44:45], v[84:85]
	v_cvt_f16_f32_e32 v56, v57
	v_cvt_f16_f32_e32 v57, v58
	v_mfma_f32_16x16x16_f16 v[44:47], v[92:93], v[0:1], v[44:47]
	v_cvt_f16_f32_e32 v58, v59
	v_mov_b32_e32 v92, v78
	v_mov_b32_e32 v93, v79
	s_waitcnt lgkmcnt(0)
	v_mfma_f32_16x16x16_f16 v[44:47], v[88:89], v[36:37], v[44:47]
	ds_read_b128 v[84:87], v180 offset:448
	ds_read_b64 v[88:89], v231 offset:5120
	v_cndmask_b32_e64 v78, v57, 0, s[18:19]
	v_cndmask_b32_e64 v79, v58, 0, s[22:23]
	v_pack_b32_f16 v77, v98, v99
	s_waitcnt lgkmcnt(1)
	v_pk_mul_f32 v[52:53], v[52:53], v[84:85]
	v_cndmask_b32_e64 v84, 0, v56, s[10:11]
	v_mfma_f32_16x16x32_f16 v[56:59], v[72:75], v[60:63], 0
	v_pack_b32_f16 v61, v78, v79
	v_mov_b32_e32 v78, v3
	v_mov_b32_e32 v79, v3
	v_mfma_f32_16x16x32_f16 v[56:59], v[68:71], v[64:67], v[56:59]
	v_mul_f32_e64 v54, v54, v86
	v_mul_f32_e64 v55, v55, v87
	v_pack_b32_f16 v60, v96, v84
	v_mov_b32_e32 v62, v3
	v_mov_b32_e32 v63, v3
	v_mfma_f32_16x16x16_f16 v[52:55], v[92:93], v[0:1], v[52:55]
	v_mfma_f32_16x16x16_f16 v[56:59], v[76:77], v[0:1], v[56:59]
	v_mad_i64_i32 v[0:1], s[28:29], v83, s91, v[126:127]
	global_store_short v[0:1], v82, off
	s_waitcnt lgkmcnt(0)
	v_mfma_f32_16x16x16_f16 v[52:55], v[88:89], v[36:37], v[52:55]
	v_subrev_u32_e32 v0, 48, v80
	v_add_u32_e32 v1, 0xef, v81
	v_cndmask_b32_e64 v0, v1, v0, s[2:3]
	v_mfma_f32_16x16x16_f16 v[36:39], v[60:61], v[36:37], v[56:59]
	v_add_u32_e32 v0, v0, v173
	v_mad_i64_i32 v[0:1], s[28:29], v0, s91, v[126:127]
	s_nop 5
	v_cvt_f16_f32_e32 v2, v36
	global_store_short v[0:1], v2, off
	v_subrev_u32_e32 v0, 47, v80
	v_add_u32_e32 v1, 0xee, v81
	v_cvt_f16_f32_e32 v2, v37
	v_cndmask_b32_e64 v0, v1, v0, s[2:3]
	v_add_u32_e32 v0, v0, v173
	v_mad_i64_i32 v[0:1], s[28:29], v0, s91, v[126:127]
	global_store_short v[0:1], v2, off
	v_subrev_u32_e32 v0, 46, v80
	v_add_u32_e32 v1, 0xed, v81
	v_cvt_f16_f32_e32 v2, v38
	v_cndmask_b32_e64 v0, v1, v0, s[2:3]
	v_add_u32_e32 v0, v0, v173
	v_mad_i64_i32 v[0:1], s[28:29], v0, s91, v[126:127]
	global_store_short v[0:1], v2, off
	v_subrev_u32_e32 v0, 45, v80
	v_add_u32_e32 v1, 0xec, v81
	v_cndmask_b32_e64 v0, v1, v0, s[2:3]
	v_cvt_f16_f32_e32 v2, v39
	v_add_u32_e32 v0, v0, v173
	v_mad_i64_i32 v[0:1], s[28:29], v0, s91, v[126:127]
	s_mov_b64 s[28:29], 0
	global_store_short v[0:1], v2, off

.LBB0_369:
	v_cmp_lt_i32_e32 vcc, 2, v176
	s_and_saveexec_b64 s[30:31], vcc
	s_xor_b64 s[70:71], exec, s[30:31]
	s_cbranch_execz .LBB0_371
	v_lshl_add_u32 v253, v206, 1, v2
	v_lshl_add_u32 v252, v208, 1, v2
	ds_read2st64_b32 v[36:37], v253 offset0:64 offset1:80
	ds_read2st64_b32 v[46:47], v253 offset0:96 offset1:112
	ds_read_b32 v60, v253 offset:32768
	ds_read2st64_b32 v[128:129], v252 offset0:64 offset1:80
	ds_read2st64_b32 v[130:131], v252 offset0:96 offset1:112
	ds_read_b32 v61, v252 offset:32768
	v_lshl_add_u32 v48, v206, 1, v2
	s_nop 0
	s_nop 0
	v_rcp_f32_e32 v44, v62
	v_rcp_f32_e32 v45, v63
	v_lshl_add_u32 v253, v210, 1, v2
	ds_read2st64_b32 v[132:133], v253 offset0:64 offset1:80
	s_waitcnt lgkmcnt(5)
	v_cvt_f32_f16_e32 v58, v47
	v_cvt_f32_f16_e32 v50, v37
	v_cvt_f32_f16_sdwa v51, v37 dst_sel:DWORD dst_unused:UNUSED_PAD src0_sel:WORD_1
	ds_read2st64_b32 v[134:135], v253 offset0:96 offset1:112
	v_cvt_f32_f16_sdwa v59, v47 dst_sel:DWORD dst_unused:UNUSED_PAD src0_sel:WORD_1
	v_cvt_f32_f16_e32 v48, v36
	v_cvt_f32_f16_e32 v54, v46
	v_cvt_f32_f16_sdwa v55, v46 dst_sel:DWORD dst_unused:UNUSED_PAD src0_sel:WORD_1
	v_cvt_f32_f16_sdwa v49, v36 dst_sel:DWORD dst_unused:UNUSED_PAD src0_sel:WORD_1
	v_pk_mul_f32 v[36:37], v[42:43], v[50:51]
	v_pk_mul_f32 v[42:43], v[62:63], v[58:59]
	v_pk_mul_f32 v[46:47], v[44:45], v[54:55]
	v_pk_mul_f32 v[44:45], v[44:45], v[48:49]
	v_pk_mul_f32 v[48:49], v[40:41], v[36:37]
	v_pk_mul_f32 v[50:51], v[40:41], v[42:43]
	v_cvt_pk_f16_f32 v36, v36, v37
	v_cvt_pk_f16_f32 v37, v42, v43
	v_pk_mul_f32 v[54:55], v[38:39], v[46:47]
	v_pk_mul_f32 v[58:59], v[38:39], v[44:45]
	ds_write2st64_b32 v207, v36, v37 offset1:18
	v_cvt_pk_f16_f32 v36, v48, v49
	v_cvt_pk_f16_f32 v37, v50, v51
	v_pk_mul_f32 v[46:47], v[0:1], v[46:47]
	ds_write2st64_b32 v207, v36, v37 offset0:36 offset1:54
	v_cvt_pk_f16_f32 v36, v54, v55
	v_cvt_pk_f16_f32 v37, v58, v59
	ds_write2st64_b32 v207, v36, v37 offset0:72 offset1:90
	v_cvt_f16_f32_e32 v36, v46
	v_pk_mul_f32 v[44:45], v[0:1], v[44:45]
	v_cvt_f16_f32_e32 v37, v47
	v_cvt_f16_f32_e32 v42, v44
	v_cvt_f16_f32_e32 v43, v45
	ds_write_b16 v178, v36 offset:24
	ds_write_b16 v178, v37 offset:64
	ds_write_b16 v178, v42 offset:5144
	ds_write_b16 v178, v43 offset:5184
	s_waitcnt lgkmcnt(12)
	ds_write_b16 v178, v60 offset:10264
	v_lshl_add_u32 v46, v208, 1, v2
	v_rcp_f32_e32 v42, v56
	v_rcp_f32_e32 v43, v57
	s_waitcnt lgkmcnt(12)
	v_cvt_f32_f16_e32 v48, v129
	v_cvt_f32_f16_sdwa v49, v129 dst_sel:DWORD dst_unused:UNUSED_PAD src0_sel:WORD_1
	s_waitcnt lgkmcnt(11)
	v_cvt_f32_f16_e32 v54, v131
	v_cvt_f32_f16_sdwa v55, v131 dst_sel:DWORD dst_unused:UNUSED_PAD src0_sel:WORD_1
	v_cvt_f32_f16_e32 v46, v128
	v_cvt_f32_f16_e32 v50, v130
	v_cvt_f32_f16_sdwa v51, v130 dst_sel:DWORD dst_unused:UNUSED_PAD src0_sel:WORD_1
	v_cvt_f32_f16_sdwa v47, v128 dst_sel:DWORD dst_unused:UNUSED_PAD src0_sel:WORD_1
	v_pk_mul_f32 v[36:37], v[62:63], v[48:49]
	v_pk_mul_f32 v[44:45], v[56:57], v[54:55]
	v_pk_mul_f32 v[48:49], v[42:43], v[50:51]
	v_pk_mul_f32 v[42:43], v[42:43], v[46:47]
	v_pk_mul_f32 v[46:47], v[40:41], v[36:37]
	v_pk_mul_f32 v[50:51], v[40:41], v[44:45]
	v_cvt_pk_f16_f32 v36, v36, v37
	v_cvt_pk_f16_f32 v37, v44, v45
	v_pk_mul_f32 v[54:55], v[38:39], v[48:49]
	v_pk_mul_f32 v[58:59], v[38:39], v[42:43]
	ds_write2st64_b32 v209, v36, v37 offset1:18
	v_cvt_pk_f16_f32 v36, v46, v47
	v_cvt_pk_f16_f32 v37, v50, v51
	v_pk_mul_f32 v[48:49], v[0:1], v[48:49]
	ds_write2st64_b32 v209, v36, v37 offset0:36 offset1:54
	v_cvt_pk_f16_f32 v36, v54, v55
	v_cvt_pk_f16_f32 v37, v58, v59
	v_lshl_add_u32 v252, v212, 1, v2
	ds_read_b32 v58, v253 offset:32768
	ds_read2st64_b32 v[136:137], v252 offset0:64 offset1:80
	s_waitcnt lgkmcnt(14)
	ds_read2st64_b32 v[138:139], v252 offset0:96 offset1:112
	s_waitcnt lgkmcnt(14)
	ds_write2st64_b32 v209, v36, v37 offset0:72 offset1:90
	v_cvt_f16_f32_e32 v36, v48
	v_pk_mul_f32 v[42:43], v[0:1], v[42:43]
	v_cvt_f16_f32_e32 v37, v49
	v_cvt_f16_f32_e32 v42, v42
	v_cvt_f16_f32_e32 v43, v43
	s_waitcnt lgkmcnt(14)
	ds_write_b16 v178, v36 offset:26
	s_waitcnt lgkmcnt(14)
	ds_write_b16 v178, v37 offset:66
	s_waitcnt lgkmcnt(14)
	ds_write_b16 v178, v42 offset:5146
	s_waitcnt lgkmcnt(14)
	ds_write_b16 v178, v43 offset:5186
	s_waitcnt lgkmcnt(14)
	ds_write_b16 v178, v61 offset:10266
	v_lshl_add_u32 v46, v210, 1, v2
	v_rcp_f32_e32 v42, v52
	v_rcp_f32_e32 v43, v53
	v_lshl_add_u32 v2, v212, 1, v2
	v_cvt_f32_f16_e32 v48, v133
	v_cvt_f32_f16_sdwa v49, v133 dst_sel:DWORD dst_unused:UNUSED_PAD src0_sel:WORD_1
	v_cvt_f32_f16_e32 v54, v135
	v_cvt_f32_f16_sdwa v55, v135 dst_sel:DWORD dst_unused:UNUSED_PAD src0_sel:WORD_1
	v_cvt_f32_f16_e32 v46, v132
	v_cvt_f32_f16_e32 v50, v134
	v_cvt_f32_f16_sdwa v51, v134 dst_sel:DWORD dst_unused:UNUSED_PAD src0_sel:WORD_1
	v_cvt_f32_f16_sdwa v47, v132 dst_sel:DWORD dst_unused:UNUSED_PAD src0_sel:WORD_1
	v_pk_mul_f32 v[36:37], v[56:57], v[48:49]
	v_pk_mul_f32 v[44:45], v[52:53], v[54:55]
	v_pk_mul_f32 v[48:49], v[42:43], v[50:51]
	v_pk_mul_f32 v[42:43], v[42:43], v[46:47]
	v_pk_mul_f32 v[46:47], v[40:41], v[36:37]
	v_pk_mul_f32 v[50:51], v[40:41], v[44:45]
	v_cvt_pk_f16_f32 v36, v36, v37
	v_cvt_pk_f16_f32 v37, v44, v45
	v_pk_mul_f32 v[54:55], v[38:39], v[48:49]
	v_pk_mul_f32 v[56:57], v[38:39], v[42:43]
	s_waitcnt lgkmcnt(14)
	ds_write2st64_b32 v211, v36, v37 offset1:18
	v_cvt_pk_f16_f32 v36, v46, v47
	v_cvt_pk_f16_f32 v37, v50, v51
	v_pk_mul_f32 v[48:49], v[0:1], v[48:49]
	s_waitcnt lgkmcnt(14)
	ds_write2st64_b32 v211, v36, v37 offset0:36 offset1:54
	v_cvt_pk_f16_f32 v36, v54, v55
	v_cvt_pk_f16_f32 v37, v56, v57
	s_waitcnt lgkmcnt(14)
	ds_write2st64_b32 v211, v36, v37 offset0:72 offset1:90
	v_cvt_f16_f32_e32 v36, v48
	v_pk_mul_f32 v[42:43], v[0:1], v[42:43]
	v_cvt_f16_f32_e32 v37, v49
	v_cvt_f16_f32_e32 v42, v42
	v_cvt_f16_f32_e32 v43, v43
	s_waitcnt lgkmcnt(14)
	ds_write_b16 v178, v36 offset:28
	s_waitcnt lgkmcnt(14)
	ds_write_b16 v178, v37 offset:68
	s_waitcnt lgkmcnt(14)
	ds_write_b16 v178, v42 offset:5148
	s_waitcnt lgkmcnt(14)
	ds_write_b16 v178, v43 offset:5188
	s_waitcnt lgkmcnt(14)
	ds_write_b16 v178, v58 offset:10268
	s_waitcnt lgkmcnt(14)
	ds_read_b32 v2, v252 offset:32768
	v_rcp_f32_e32 v42, v0
	v_rcp_f32_e32 v43, v1
	v_cvt_f32_f16_e32 v48, v137
	v_cvt_f32_f16_sdwa v49, v137 dst_sel:DWORD dst_unused:UNUSED_PAD src0_sel:WORD_1
	v_cvt_f32_f16_e32 v54, v139
	v_cvt_f32_f16_sdwa v55, v139 dst_sel:DWORD dst_unused:UNUSED_PAD src0_sel:WORD_1
	v_cvt_f32_f16_e32 v46, v136
	v_cvt_f32_f16_e32 v50, v138
	v_cvt_f32_f16_sdwa v51, v138 dst_sel:DWORD dst_unused:UNUSED_PAD src0_sel:WORD_1
	v_cvt_f32_f16_sdwa v47, v136 dst_sel:DWORD dst_unused:UNUSED_PAD src0_sel:WORD_1
	v_pk_mul_f32 v[36:37], v[52:53], v[48:49]
	v_pk_mul_f32 v[44:45], v[0:1], v[54:55]
	v_pk_mul_f32 v[48:49], v[42:43], v[50:51]
	v_pk_mul_f32 v[42:43], v[42:43], v[46:47]
	v_pk_mul_f32 v[46:47], v[40:41], v[36:37]
	v_pk_mul_f32 v[40:41], v[40:41], v[44:45]
	v_cvt_pk_f16_f32 v36, v36, v37
	v_cvt_pk_f16_f32 v37, v44, v45
	v_pk_mul_f32 v[50:51], v[38:39], v[48:49]
	v_pk_mul_f32 v[38:39], v[38:39], v[42:43]
	s_waitcnt lgkmcnt(14)
	ds_write2st64_b32 v213, v36, v37 offset1:18
	v_cvt_pk_f16_f32 v36, v46, v47
	v_cvt_pk_f16_f32 v37, v40, v41
	v_pk_mul_f32 v[48:49], v[0:1], v[48:49]
	s_waitcnt lgkmcnt(14)
	ds_write2st64_b32 v213, v36, v37 offset0:36 offset1:54
	v_cvt_pk_f16_f32 v36, v50, v51
	v_cvt_pk_f16_f32 v37, v38, v39
	s_waitcnt lgkmcnt(14)
	ds_write2st64_b32 v213, v36, v37 offset0:72 offset1:90
	v_cvt_f16_f32_e32 v36, v48
	v_pk_mul_f32 v[42:43], v[0:1], v[42:43]
	v_cvt_f16_f32_e32 v37, v49
	v_cvt_f16_f32_e32 v38, v42
	v_cvt_f16_f32_e32 v39, v43
	s_waitcnt lgkmcnt(14)
	ds_write_b16 v178, v36 offset:30
	s_waitcnt lgkmcnt(14)
	ds_write_b16 v178, v37 offset:70
	s_waitcnt lgkmcnt(14)
	ds_write_b16 v178, v38 offset:5150
	s_waitcnt lgkmcnt(14)
	ds_write_b16 v178, v39 offset:5190
	s_nop 0
	s_waitcnt lgkmcnt(7)
	ds_write_b16 v178, v2 offset:10270
	v_perm_b32 v36, v61, v60, s82
	v_perm_b32 v37, v2, v58, s82
	ds_write_b64 v178, v[36:37] offset:10304
.LBB0_371:
	s_andn2_saveexec_b64 s[70:71], s[70:71]
	s_cbranch_execz .LBB0_373
	v_lshl_add_u32 v253, v198, 1, v2
	v_lshl_add_u32 v252, v200, 1, v2
	ds_read2st64_b32 v[36:37], v253 offset0:64 offset1:80
	ds_read2st64_b32 v[48:49], v253 offset0:96 offset1:112
	ds_read_b32 v64, v253 offset:32768
	ds_read2st64_b32 v[128:129], v252 offset0:64 offset1:80
	ds_read2st64_b32 v[130:131], v252 offset0:96 offset1:112
	v_lshl_add_u32 v52, v198, 1, v2
	s_nop 0
	s_nop 0
	s_nop 0
	v_rcp_f32_e32 v44, v58
	v_rcp_f32_e32 v45, v59
	s_waitcnt lgkmcnt(3)
	v_cvt_f32_f16_e32 v60, v49
	v_cvt_f32_f16_e32 v54, v37
	v_cvt_f32_f16_sdwa v55, v37 dst_sel:DWORD dst_unused:UNUSED_PAD src0_sel:WORD_1
	v_cvt_f32_f16_sdwa v61, v49 dst_sel:DWORD dst_unused:UNUSED_PAD src0_sel:WORD_1
	v_cvt_f32_f16_e32 v52, v36
	v_cvt_f32_f16_e32 v56, v48
	v_cvt_f32_f16_sdwa v57, v48 dst_sel:DWORD dst_unused:UNUSED_PAD src0_sel:WORD_1
	v_cvt_f32_f16_sdwa v53, v36 dst_sel:DWORD dst_unused:UNUSED_PAD src0_sel:WORD_1
	v_pk_mul_f32 v[36:37], v[38:39], v[54:55]
	v_pk_mul_f32 v[48:49], v[58:59], v[60:61]
	v_pk_mul_f32 v[54:55], v[44:45], v[56:57]
	v_pk_mul_f32 v[44:45], v[44:45], v[52:53]
	v_pk_mul_f32 v[52:53], v[40:41], v[36:37]
	v_pk_mul_f32 v[56:57], v[40:41], v[48:49]
	v_cvt_pk_f16_f32 v36, v36, v37
	v_cvt_pk_f16_f32 v37, v48, v49
	v_pk_mul_f32 v[60:61], v[38:39], v[54:55]
	v_pk_mul_f32 v[62:63], v[38:39], v[44:45]
	ds_write2st64_b32 v199, v36, v37 offset1:18
	v_cvt_pk_f16_f32 v36, v52, v53
	v_cvt_pk_f16_f32 v37, v56, v57
	v_pk_mul_f32 v[54:55], v[0:1], v[54:55]
	ds_write2st64_b32 v199, v36, v37 offset0:36 offset1:54
	v_cvt_pk_f16_f32 v36, v60, v61
	v_cvt_pk_f16_f32 v37, v62, v63
	v_lshl_add_u32 v253, v202, 1, v2
	ds_read_b32 v62, v252 offset:32768
	ds_read2st64_b32 v[132:133], v253 offset0:64 offset1:80
	ds_read2st64_b32 v[134:135], v253 offset0:96 offset1:112
	ds_write2st64_b32 v199, v36, v37 offset0:72 offset1:90
	v_cvt_f16_f32_e32 v36, v54
	v_pk_mul_f32 v[44:45], v[0:1], v[44:45]
	v_cvt_f16_f32_e32 v37, v55
	v_cvt_f16_f32_e32 v44, v44
	v_cvt_f16_f32_e32 v45, v45
	ds_write_b16 v178, v36 offset:16
	ds_write_b16 v178, v37 offset:56
	ds_write_b16 v178, v44 offset:5136
	ds_write_b16 v178, v45 offset:5176
	s_waitcnt lgkmcnt(12)
	ds_write_b16 v178, v64 offset:10256
	v_lshl_add_u32 v52, v200, 1, v2
	v_rcp_f32_e32 v44, v50
	v_rcp_f32_e32 v45, v51
	s_waitcnt lgkmcnt(12)
	v_cvt_f32_f16_e32 v54, v129
	v_cvt_f32_f16_sdwa v55, v129 dst_sel:DWORD dst_unused:UNUSED_PAD src0_sel:WORD_1
	s_waitcnt lgkmcnt(11)
	v_cvt_f32_f16_e32 v60, v131
	v_cvt_f32_f16_sdwa v61, v131 dst_sel:DWORD dst_unused:UNUSED_PAD src0_sel:WORD_1
	v_cvt_f32_f16_e32 v52, v128
	v_cvt_f32_f16_e32 v56, v130
	v_cvt_f32_f16_sdwa v57, v130 dst_sel:DWORD dst_unused:UNUSED_PAD src0_sel:WORD_1
	v_cvt_f32_f16_sdwa v53, v128 dst_sel:DWORD dst_unused:UNUSED_PAD src0_sel:WORD_1
	v_pk_mul_f32 v[36:37], v[58:59], v[54:55]
	v_pk_mul_f32 v[48:49], v[50:51], v[60:61]
	v_pk_mul_f32 v[54:55], v[44:45], v[56:57]
	v_pk_mul_f32 v[44:45], v[44:45], v[52:53]
	v_pk_mul_f32 v[52:53], v[40:41], v[36:37]
	v_pk_mul_f32 v[56:57], v[40:41], v[48:49]
	v_cvt_pk_f16_f32 v36, v36, v37
	v_cvt_pk_f16_f32 v37, v48, v49
	v_pk_mul_f32 v[58:59], v[38:39], v[54:55]
	v_pk_mul_f32 v[60:61], v[38:39], v[44:45]
	ds_write2st64_b32 v201, v36, v37 offset1:18
	v_cvt_pk_f16_f32 v36, v52, v53
	v_cvt_pk_f16_f32 v37, v56, v57
	v_pk_mul_f32 v[54:55], v[0:1], v[54:55]
	ds_write2st64_b32 v201, v36, v37 offset0:36 offset1:54
	v_cvt_pk_f16_f32 v36, v58, v59
	v_cvt_pk_f16_f32 v37, v60, v61
	v_lshl_add_u32 v252, v204, 1, v2
	ds_read_b32 v60, v253 offset:32768
	ds_read2st64_b32 v[136:137], v252 offset0:64 offset1:80
	s_waitcnt lgkmcnt(14)
	ds_read2st64_b32 v[138:139], v252 offset0:96 offset1:112
	s_waitcnt lgkmcnt(14)
	ds_write2st64_b32 v201, v36, v37 offset0:72 offset1:90
	v_cvt_f16_f32_e32 v36, v54
	v_pk_mul_f32 v[44:45], v[0:1], v[44:45]
	v_cvt_f16_f32_e32 v37, v55
	v_cvt_f16_f32_e32 v44, v44
	v_cvt_f16_f32_e32 v45, v45
	s_waitcnt lgkmcnt(14)
	ds_write_b16 v178, v36 offset:18
	s_waitcnt lgkmcnt(14)
	ds_write_b16 v178, v37 offset:58
	s_waitcnt lgkmcnt(14)
	ds_write_b16 v178, v44 offset:5138
	s_waitcnt lgkmcnt(14)
	ds_write_b16 v178, v45 offset:5178
	s_waitcnt lgkmcnt(14)
	ds_write_b16 v178, v62 offset:10258
	v_lshl_add_u32 v52, v202, 1, v2
	v_rcp_f32_e32 v44, v46
	v_rcp_f32_e32 v45, v47
	v_lshl_add_u32 v2, v204, 1, v2
	v_cvt_f32_f16_e32 v54, v133
	v_cvt_f32_f16_sdwa v55, v133 dst_sel:DWORD dst_unused:UNUSED_PAD src0_sel:WORD_1
	v_cvt_f32_f16_e32 v58, v135
	v_cvt_f32_f16_sdwa v59, v135 dst_sel:DWORD dst_unused:UNUSED_PAD src0_sel:WORD_1
	v_cvt_f32_f16_e32 v52, v132
	v_cvt_f32_f16_e32 v56, v134
	v_cvt_f32_f16_sdwa v57, v134 dst_sel:DWORD dst_unused:UNUSED_PAD src0_sel:WORD_1
	v_cvt_f32_f16_sdwa v53, v132 dst_sel:DWORD dst_unused:UNUSED_PAD src0_sel:WORD_1
	v_pk_mul_f32 v[36:37], v[50:51], v[54:55]
	v_pk_mul_f32 v[48:49], v[46:47], v[58:59]
	v_pk_mul_f32 v[50:51], v[44:45], v[56:57]
	v_pk_mul_f32 v[44:45], v[44:45], v[52:53]
	v_pk_mul_f32 v[52:53], v[40:41], v[36:37]
	v_pk_mul_f32 v[54:55], v[40:41], v[48:49]
	v_cvt_pk_f16_f32 v36, v36, v37
	v_cvt_pk_f16_f32 v37, v48, v49
	v_pk_mul_f32 v[56:57], v[38:39], v[50:51]
	v_pk_mul_f32 v[58:59], v[38:39], v[44:45]
	s_waitcnt lgkmcnt(14)
	ds_write2st64_b32 v203, v36, v37 offset1:18
	v_cvt_pk_f16_f32 v36, v52, v53
	v_cvt_pk_f16_f32 v37, v54, v55
	v_pk_mul_f32 v[50:51], v[0:1], v[50:51]
	s_waitcnt lgkmcnt(14)
	ds_write2st64_b32 v203, v36, v37 offset0:36 offset1:54
	v_cvt_pk_f16_f32 v36, v56, v57
	v_cvt_pk_f16_f32 v37, v58, v59
	s_waitcnt lgkmcnt(14)
	ds_write2st64_b32 v203, v36, v37 offset0:72 offset1:90
	v_cvt_f16_f32_e32 v36, v50
	v_pk_mul_f32 v[44:45], v[0:1], v[44:45]
	v_cvt_f16_f32_e32 v37, v51
	v_cvt_f16_f32_e32 v44, v44
	v_cvt_f16_f32_e32 v45, v45
	s_waitcnt lgkmcnt(14)
	ds_write_b16 v178, v36 offset:20
	s_waitcnt lgkmcnt(14)
	ds_write_b16 v178, v37 offset:60
	s_waitcnt lgkmcnt(14)
	ds_write_b16 v178, v44 offset:5140
	s_waitcnt lgkmcnt(14)
	ds_write_b16 v178, v45 offset:5180
	s_waitcnt lgkmcnt(14)
	ds_write_b16 v178, v60 offset:10260
	s_waitcnt lgkmcnt(14)
	ds_read_b32 v2, v252 offset:32768
	v_rcp_f32_e32 v44, v42
	v_rcp_f32_e32 v45, v43
	v_cvt_f32_f16_e32 v52, v137
	v_cvt_f32_f16_sdwa v53, v137 dst_sel:DWORD dst_unused:UNUSED_PAD src0_sel:WORD_1
	v_cvt_f32_f16_e32 v56, v139
	v_cvt_f32_f16_sdwa v57, v139 dst_sel:DWORD dst_unused:UNUSED_PAD src0_sel:WORD_1
	v_cvt_f32_f16_e32 v50, v136
	v_cvt_f32_f16_e32 v54, v138
	v_cvt_f32_f16_sdwa v55, v138 dst_sel:DWORD dst_unused:UNUSED_PAD src0_sel:WORD_1
	v_cvt_f32_f16_sdwa v51, v136 dst_sel:DWORD dst_unused:UNUSED_PAD src0_sel:WORD_1
	v_pk_mul_f32 v[36:37], v[46:47], v[52:53]
	v_pk_mul_f32 v[42:43], v[42:43], v[56:57]
	v_pk_mul_f32 v[46:47], v[44:45], v[54:55]
	v_pk_mul_f32 v[44:45], v[44:45], v[50:51]
	v_pk_mul_f32 v[48:49], v[40:41], v[36:37]
	v_pk_mul_f32 v[40:41], v[40:41], v[42:43]
	v_cvt_pk_f16_f32 v36, v36, v37
	v_cvt_pk_f16_f32 v37, v42, v43
	v_pk_mul_f32 v[50:51], v[38:39], v[46:47]
	v_pk_mul_f32 v[38:39], v[38:39], v[44:45]
	s_waitcnt lgkmcnt(14)
	ds_write2st64_b32 v205, v36, v37 offset1:18
	v_cvt_pk_f16_f32 v36, v48, v49
	v_cvt_pk_f16_f32 v37, v40, v41
	v_pk_mul_f32 v[46:47], v[0:1], v[46:47]
	s_waitcnt lgkmcnt(14)
	ds_write2st64_b32 v205, v36, v37 offset0:36 offset1:54
	v_cvt_pk_f16_f32 v36, v50, v51
	v_cvt_pk_f16_f32 v37, v38, v39
	s_waitcnt lgkmcnt(14)
	ds_write2st64_b32 v205, v36, v37 offset0:72 offset1:90
	v_cvt_f16_f32_e32 v36, v46
	v_pk_mul_f32 v[44:45], v[0:1], v[44:45]
	v_cvt_f16_f32_e32 v37, v47
	v_cvt_f16_f32_e32 v38, v44
	v_cvt_f16_f32_e32 v39, v45
	s_waitcnt lgkmcnt(14)
	ds_write_b16 v178, v36 offset:22
	s_waitcnt lgkmcnt(14)
	ds_write_b16 v178, v37 offset:62
	s_waitcnt lgkmcnt(14)
	ds_write_b16 v178, v38 offset:5142
	s_waitcnt lgkmcnt(14)
	ds_write_b16 v178, v39 offset:5182
	s_nop 0
	s_waitcnt lgkmcnt(7)
	ds_write_b16 v178, v2 offset:10262
	v_perm_b32 v36, v62, v64, s82
	v_perm_b32 v37, v2, v60, s82
	ds_write_b64 v178, v[36:37] offset:10296

.LBB0_374:
	v_cmp_eq_u32_e32 vcc, 1, v176
	s_and_saveexec_b64 s[70:71], vcc
	s_cbranch_execz .LBB0_376
	v_lshl_add_u32 v253, v190, 1, v2
	v_lshl_add_u32 v252, v192, 1, v2
	ds_read2st64_b32 v[36:37], v253 offset0:64 offset1:80
	ds_read2st64_b32 v[46:47], v253 offset0:96 offset1:112
	ds_read_b32 v62, v253 offset:32768
	ds_read2st64_b32 v[128:129], v252 offset0:64 offset1:80
	ds_read2st64_b32 v[130:131], v252 offset0:96 offset1:112
	v_lshl_add_u32 v50, v190, 1, v2
	s_nop 0
	s_nop 0
	s_nop 0
	v_rcp_f32_e32 v42, v54
	v_rcp_f32_e32 v43, v55
	s_waitcnt lgkmcnt(3)
	v_cvt_f32_f16_e32 v58, v47
	v_cvt_f32_f16_e32 v52, v37
	v_cvt_f32_f16_sdwa v53, v37 dst_sel:DWORD dst_unused:UNUSED_PAD src0_sel:WORD_1
	v_cvt_f32_f16_sdwa v59, v47 dst_sel:DWORD dst_unused:UNUSED_PAD src0_sel:WORD_1
	v_cvt_f32_f16_e32 v50, v36
	v_cvt_f32_f16_e32 v56, v46
	v_cvt_f32_f16_sdwa v57, v46 dst_sel:DWORD dst_unused:UNUSED_PAD src0_sel:WORD_1
	v_cvt_f32_f16_sdwa v51, v36 dst_sel:DWORD dst_unused:UNUSED_PAD src0_sel:WORD_1
	v_pk_mul_f32 v[36:37], v[60:61], v[52:53]
	v_pk_mul_f32 v[46:47], v[54:55], v[58:59]
	v_pk_mul_f32 v[52:53], v[42:43], v[56:57]
	v_pk_mul_f32 v[42:43], v[42:43], v[50:51]
	v_pk_mul_f32 v[50:51], v[40:41], v[36:37]
	v_pk_mul_f32 v[56:57], v[40:41], v[46:47]
	v_cvt_pk_f16_f32 v36, v36, v37
	v_cvt_pk_f16_f32 v37, v46, v47
	v_pk_mul_f32 v[58:59], v[38:39], v[52:53]
	v_pk_mul_f32 v[60:61], v[38:39], v[42:43]
	ds_write2st64_b32 v191, v36, v37 offset1:18
	v_cvt_pk_f16_f32 v36, v50, v51
	v_cvt_pk_f16_f32 v37, v56, v57
	v_pk_mul_f32 v[52:53], v[0:1], v[52:53]
	ds_write2st64_b32 v191, v36, v37 offset0:36 offset1:54
	v_cvt_pk_f16_f32 v36, v58, v59
	v_cvt_pk_f16_f32 v37, v60, v61
	v_lshl_add_u32 v253, v194, 1, v2
	ds_read_b32 v60, v252 offset:32768
	ds_read2st64_b32 v[132:133], v253 offset0:64 offset1:80
	ds_read2st64_b32 v[134:135], v253 offset0:96 offset1:112
	ds_write2st64_b32 v191, v36, v37 offset0:72 offset1:90
	v_cvt_f16_f32_e32 v36, v52
	v_pk_mul_f32 v[42:43], v[0:1], v[42:43]
	v_cvt_f16_f32_e32 v37, v53
	v_cvt_f16_f32_e32 v42, v42
	v_cvt_f16_f32_e32 v43, v43
	ds_write_b16 v178, v36 offset:8
	ds_write_b16 v178, v37 offset:48
	ds_write_b16 v178, v42 offset:5128
	ds_write_b16 v178, v43 offset:5168
	s_waitcnt lgkmcnt(12)
	ds_write_b16 v178, v62 offset:10248
	v_lshl_add_u32 v50, v192, 1, v2
	v_rcp_f32_e32 v42, v48
	v_rcp_f32_e32 v43, v49
	s_waitcnt lgkmcnt(12)
	v_cvt_f32_f16_e32 v52, v129
	v_cvt_f32_f16_sdwa v53, v129 dst_sel:DWORD dst_unused:UNUSED_PAD src0_sel:WORD_1
	s_waitcnt lgkmcnt(11)
	v_cvt_f32_f16_e32 v58, v131
	v_cvt_f32_f16_sdwa v59, v131 dst_sel:DWORD dst_unused:UNUSED_PAD src0_sel:WORD_1
	v_cvt_f32_f16_e32 v50, v128
	v_cvt_f32_f16_e32 v56, v130
	v_cvt_f32_f16_sdwa v57, v130 dst_sel:DWORD dst_unused:UNUSED_PAD src0_sel:WORD_1
	v_cvt_f32_f16_sdwa v51, v128 dst_sel:DWORD dst_unused:UNUSED_PAD src0_sel:WORD_1
	v_pk_mul_f32 v[36:37], v[54:55], v[52:53]
	v_pk_mul_f32 v[46:47], v[48:49], v[58:59]
	v_pk_mul_f32 v[52:53], v[42:43], v[56:57]
	v_pk_mul_f32 v[42:43], v[42:43], v[50:51]
	v_pk_mul_f32 v[50:51], v[40:41], v[36:37]
	v_pk_mul_f32 v[54:55], v[40:41], v[46:47]
	v_cvt_pk_f16_f32 v36, v36, v37
	v_cvt_pk_f16_f32 v37, v46, v47
	v_pk_mul_f32 v[56:57], v[38:39], v[52:53]
	v_pk_mul_f32 v[58:59], v[38:39], v[42:43]
	ds_write2st64_b32 v193, v36, v37 offset1:18
	v_cvt_pk_f16_f32 v36, v50, v51
	v_cvt_pk_f16_f32 v37, v54, v55
	v_pk_mul_f32 v[52:53], v[0:1], v[52:53]
	ds_write2st64_b32 v193, v36, v37 offset0:36 offset1:54
	v_cvt_pk_f16_f32 v36, v56, v57
	v_cvt_pk_f16_f32 v37, v58, v59
	v_lshl_add_u32 v252, v196, 1, v2
	ds_read_b32 v58, v253 offset:32768
	ds_read2st64_b32 v[136:137], v252 offset0:64 offset1:80
	s_waitcnt lgkmcnt(14)
	ds_read2st64_b32 v[138:139], v252 offset0:96 offset1:112
	s_waitcnt lgkmcnt(14)
	ds_write2st64_b32 v193, v36, v37 offset0:72 offset1:90
	v_cvt_f16_f32_e32 v36, v52
	v_pk_mul_f32 v[42:43], v[0:1], v[42:43]
	v_cvt_f16_f32_e32 v37, v53
	v_cvt_f16_f32_e32 v42, v42
	v_cvt_f16_f32_e32 v43, v43
	s_waitcnt lgkmcnt(14)
	ds_write_b16 v178, v36 offset:10
	s_waitcnt lgkmcnt(14)
	ds_write_b16 v178, v37 offset:50
	s_waitcnt lgkmcnt(14)
	ds_write_b16 v178, v42 offset:5130
	s_waitcnt lgkmcnt(14)
	ds_write_b16 v178, v43 offset:5170
	s_waitcnt lgkmcnt(14)
	ds_write_b16 v178, v60 offset:10250
	v_lshl_add_u32 v50, v194, 1, v2
	v_rcp_f32_e32 v42, v44
	v_rcp_f32_e32 v43, v45
	v_lshl_add_u32 v2, v196, 1, v2
	v_cvt_f32_f16_e32 v52, v133
	v_cvt_f32_f16_sdwa v53, v133 dst_sel:DWORD dst_unused:UNUSED_PAD src0_sel:WORD_1
	v_cvt_f32_f16_e32 v56, v135
	v_cvt_f32_f16_sdwa v57, v135 dst_sel:DWORD dst_unused:UNUSED_PAD src0_sel:WORD_1
	v_cvt_f32_f16_e32 v50, v132
	v_cvt_f32_f16_e32 v54, v134
	v_cvt_f32_f16_sdwa v55, v134 dst_sel:DWORD dst_unused:UNUSED_PAD src0_sel:WORD_1
	v_cvt_f32_f16_sdwa v51, v132 dst_sel:DWORD dst_unused:UNUSED_PAD src0_sel:WORD_1
	v_pk_mul_f32 v[36:37], v[48:49], v[52:53]
	v_pk_mul_f32 v[46:47], v[44:45], v[56:57]
	v_pk_mul_f32 v[48:49], v[42:43], v[54:55]
	v_pk_mul_f32 v[42:43], v[42:43], v[50:51]
	v_pk_mul_f32 v[50:51], v[40:41], v[36:37]
	v_pk_mul_f32 v[52:53], v[40:41], v[46:47]
	v_cvt_pk_f16_f32 v36, v36, v37
	v_cvt_pk_f16_f32 v37, v46, v47
	v_pk_mul_f32 v[54:55], v[38:39], v[48:49]
	v_pk_mul_f32 v[56:57], v[38:39], v[42:43]
	s_waitcnt lgkmcnt(14)
	ds_write2st64_b32 v195, v36, v37 offset1:18
	v_cvt_pk_f16_f32 v36, v50, v51
	v_cvt_pk_f16_f32 v37, v52, v53
	v_pk_mul_f32 v[48:49], v[0:1], v[48:49]
	s_waitcnt lgkmcnt(14)
	ds_write2st64_b32 v195, v36, v37 offset0:36 offset1:54
	v_cvt_pk_f16_f32 v36, v54, v55
	v_cvt_pk_f16_f32 v37, v56, v57
	s_waitcnt lgkmcnt(14)
	ds_write2st64_b32 v195, v36, v37 offset0:72 offset1:90
	v_cvt_f16_f32_e32 v36, v48
	v_pk_mul_f32 v[42:43], v[0:1], v[42:43]
	v_cvt_f16_f32_e32 v37, v49
	v_cvt_f16_f32_e32 v42, v42
	v_cvt_f16_f32_e32 v43, v43
	s_waitcnt lgkmcnt(14)
	ds_write_b16 v178, v36 offset:12
	s_waitcnt lgkmcnt(14)
	ds_write_b16 v178, v37 offset:52
	s_waitcnt lgkmcnt(14)
	ds_write_b16 v178, v42 offset:5132
	s_waitcnt lgkmcnt(14)
	ds_write_b16 v178, v43 offset:5172
	s_waitcnt lgkmcnt(14)
	ds_write_b16 v178, v58 offset:10252
	s_waitcnt lgkmcnt(14)
	ds_read_b32 v2, v252 offset:32768
	v_cvt_f32_f16_e32 v48, v137
	v_cvt_f32_f16_sdwa v49, v137 dst_sel:DWORD dst_unused:UNUSED_PAD src0_sel:WORD_1
	v_cvt_f32_f16_e32 v52, v139
	v_cvt_f32_f16_sdwa v53, v139 dst_sel:DWORD dst_unused:UNUSED_PAD src0_sel:WORD_1
	v_cvt_f32_f16_e32 v46, v136
	v_cvt_f32_f16_e32 v50, v138
	v_cvt_f32_f16_sdwa v51, v138 dst_sel:DWORD dst_unused:UNUSED_PAD src0_sel:WORD_1
	v_cvt_f32_f16_sdwa v47, v136 dst_sel:DWORD dst_unused:UNUSED_PAD src0_sel:WORD_1
	v_pk_mul_f32 v[36:37], v[44:45], v[48:49]
	v_pk_mul_f32 v[42:43], v[38:39], v[52:53]
	v_pk_mul_f32 v[44:45], v[40:41], v[50:51]
	v_pk_mul_f32 v[46:47], v[40:41], v[46:47]
	v_pk_mul_f32 v[48:49], v[40:41], v[36:37]
	v_pk_mul_f32 v[40:41], v[40:41], v[42:43]
	v_cvt_pk_f16_f32 v36, v36, v37
	v_cvt_pk_f16_f32 v37, v42, v43
	v_pk_mul_f32 v[50:51], v[38:39], v[44:45]
	v_pk_mul_f32 v[38:39], v[38:39], v[46:47]
	s_waitcnt lgkmcnt(14)
	ds_write2st64_b32 v197, v36, v37 offset1:18
	v_cvt_pk_f16_f32 v36, v48, v49
	v_cvt_pk_f16_f32 v37, v40, v41
	v_pk_mul_f32 v[44:45], v[0:1], v[44:45]
	s_waitcnt lgkmcnt(14)
	ds_write2st64_b32 v197, v36, v37 offset0:36 offset1:54
	v_cvt_pk_f16_f32 v36, v50, v51
	v_cvt_pk_f16_f32 v37, v38, v39
	s_waitcnt lgkmcnt(14)
	ds_write2st64_b32 v197, v36, v37 offset0:72 offset1:90
	v_cvt_f16_f32_e32 v36, v44
	v_pk_mul_f32 v[46:47], v[0:1], v[46:47]
	v_cvt_f16_f32_e32 v37, v45
	v_cvt_f16_f32_e32 v38, v46
	v_cvt_f16_f32_e32 v39, v47
	s_waitcnt lgkmcnt(14)
	ds_write_b16 v178, v36 offset:14
	s_waitcnt lgkmcnt(14)
	ds_write_b16 v178, v37 offset:54
	s_waitcnt lgkmcnt(14)
	ds_write_b16 v178, v38 offset:5134
	s_waitcnt lgkmcnt(14)
	ds_write_b16 v178, v39 offset:5174
	s_nop 0
	s_waitcnt lgkmcnt(7)
	ds_write_b16 v178, v2 offset:10254
	v_perm_b32 v36, v60, v62, s82
	v_perm_b32 v37, v2, v58, s82
	ds_write_b64 v178, v[36:37] offset:10288

.LBB0_455:
	s_andn2_b64 vcc, exec, s[24:25]
	s_mov_b64 s[26:27], -1
	s_cbranch_vccnz .LBB0_463
	s_and_b32 s26, s76, 1
	v_lshl_add_u32 v0, s26, 13, v227
	ds_read2_b64 v[36:39], v0 offset1:32
	v_mad_u32_u24 v2, s26, v165, v228
	s_waitcnt lgkmcnt(0)
	v_pk_mul_f32 v[66:67], v[36:37], v[38:39]
	v_xor_b32_e32 v90, 16, v0
	ds_read2_b64 v[38:41], v90 offset0:64 offset1:96
	s_waitcnt lgkmcnt(0)
	v_pk_mul_f32 v[64:65], v[66:67], v[38:39]
	s_nop 0
	v_pk_mul_f32 v[60:61], v[64:65], v[40:41]
	v_xor_b32_e32 v91, 32, v0
	ds_read2_b64 v[38:41], v91 offset0:128 offset1:160
	s_waitcnt lgkmcnt(0)
	v_pk_mul_f32 v[54:55], v[60:61], v[38:39]
	s_nop 0
	v_pk_mul_f32 v[48:49], v[54:55], v[40:41]
	v_xor_b32_e32 v92, 48, v0
	ds_read2_b64 v[38:41], v92 offset0:192 offset1:224
	v_add_u32_e32 v0, 0x800, v0
	v_xor_b32_e32 v91, 32, v0
	ds_read2_b64 v[68:71], v91 offset0:128 offset1:160
	s_waitcnt lgkmcnt(1)
	v_pk_mul_f32 v[44:45], v[48:49], v[38:39]
	s_nop 0
	v_pk_mul_f32 v[38:39], v[44:45], v[40:41]
	ds_read2_b64 v[40:43], v0 offset1:32
	s_waitcnt lgkmcnt(0)
	v_pk_mul_f32 v[58:59], v[38:39], v[40:41]
	s_nop 0
	v_pk_mul_f32 v[50:51], v[58:59], v[42:43]
	v_xor_b32_e32 v90, 16, v0
	ds_read2_b64 v[40:43], v90 offset0:64 offset1:96
	s_waitcnt lgkmcnt(0)
	v_pk_mul_f32 v[46:47], v[50:51], v[40:41]
	s_nop 0
	v_pk_mul_f32 v[42:43], v[46:47], v[42:43]
	v_rcp_f32_e32 v40, v38
	v_pk_mul_f32 v[62:63], v[42:43], v[68:69]
	v_rcp_f32_e32 v41, v39
	v_pk_mul_f32 v[56:57], v[62:63], v[70:71]
	v_xor_b32_e32 v92, 48, v0
	ds_read2_b64 v[68:71], v92 offset0:192 offset1:224
	s_waitcnt lgkmcnt(0)
	v_pk_mul_f32 v[52:53], v[56:57], v[68:69]
	s_nop 0
	v_pk_mul_f32 v[0:1], v[52:53], v[70:71]
	s_and_saveexec_b64 s[26:27], s[4:5]
	s_cbranch_execz .LBB0_458
	v_lshl_add_u32 v253, v173, 1, v2
	v_lshl_add_u32 v252, v180, 1, v2
	ds_read2st64_b32 v[72:73], v253 offset0:96 offset1:112
	ds_read2st64_b32 v[68:69], v253 offset0:64 offset1:80
	ds_read_b32 v84, v253 offset:32768
	ds_read2st64_b32 v[126:127], v252 offset0:64 offset1:80
	ds_read2st64_b32 v[128:129], v252 offset0:96 offset1:112
	v_lshl_add_u32 v74, v173, 1, v2
	s_nop 0
	s_nop 0
	v_rcp_f32_e32 v70, v36
	v_rcp_f32_e32 v71, v37
	s_waitcnt lgkmcnt(4)
	v_cvt_f32_f16_e32 v78, v73
	v_cvt_f32_f16_sdwa v79, v73 dst_sel:DWORD dst_unused:UNUSED_PAD src0_sel:WORD_1
	s_waitcnt lgkmcnt(3)
	v_cvt_f32_f16_e32 v74, v68
	v_cvt_f32_f16_sdwa v75, v68 dst_sel:DWORD dst_unused:UNUSED_PAD src0_sel:WORD_1
	v_cvt_f32_f16_e32 v76, v72
	v_cvt_f32_f16_sdwa v77, v72 dst_sel:DWORD dst_unused:UNUSED_PAD src0_sel:WORD_1
	v_cvt_f32_f16_e32 v72, v69
	v_cvt_f32_f16_sdwa v73, v69 dst_sel:DWORD dst_unused:UNUSED_PAD src0_sel:WORD_1
	v_pk_mul_f32 v[78:79], v[36:37], v[78:79]
	v_pk_mul_f32 v[76:77], v[70:71], v[76:77]
	v_pk_mul_f32 v[70:71], v[70:71], v[74:75]
	v_pk_mul_f32 v[72:73], v[40:41], v[72:73]
	v_pk_mul_f32 v[74:75], v[40:41], v[78:79]
	v_cvt_pk_f16_f32 v68, v78, v79
	v_pk_mul_f32 v[80:81], v[38:39], v[76:77]
	v_pk_mul_f32 v[82:83], v[38:39], v[70:71]
	ds_write2st64_b32 v179, v69, v68 offset1:18
	v_cvt_pk_f16_f32 v68, v72, v73
	v_cvt_pk_f16_f32 v69, v74, v75
	v_pk_mul_f32 v[76:77], v[0:1], v[76:77]
	ds_write2st64_b32 v179, v68, v69 offset0:36 offset1:54
	v_cvt_pk_f16_f32 v68, v80, v81
	v_cvt_pk_f16_f32 v69, v82, v83
	v_lshl_add_u32 v253, v182, 1, v2
	ds_read_b32 v82, v252 offset:32768
	ds_read2st64_b32 v[130:131], v253 offset0:64 offset1:80
	ds_read2st64_b32 v[132:133], v253 offset0:96 offset1:112
	ds_write2st64_b32 v179, v68, v69 offset0:72 offset1:90
	v_cvt_f16_f32_e32 v68, v76
	v_pk_mul_f32 v[70:71], v[0:1], v[70:71]
	v_cvt_f16_f32_e32 v69, v77
	v_cvt_f16_f32_e32 v70, v70
	v_cvt_f16_f32_e32 v71, v71
	ds_write_b16 v174, v68
	ds_write_b16 v174, v69 offset:40
	ds_write_b16 v174, v70 offset:5120
	ds_write_b16 v174, v71 offset:5160
	s_waitcnt lgkmcnt(12)
	ds_write_b16 v174, v84 offset:10240
	v_lshl_add_u32 v74, v180, 1, v2
	v_rcp_f32_e32 v70, v66
	v_rcp_f32_e32 v71, v67
	s_waitcnt lgkmcnt(12)
	v_cvt_f32_f16_e32 v76, v127
	v_cvt_f32_f16_sdwa v77, v127 dst_sel:DWORD dst_unused:UNUSED_PAD src0_sel:WORD_1
	s_waitcnt lgkmcnt(11)
	v_cvt_f32_f16_e32 v80, v129
	v_cvt_f32_f16_sdwa v81, v129 dst_sel:DWORD dst_unused:UNUSED_PAD src0_sel:WORD_1
	v_cvt_f32_f16_e32 v74, v126
	v_cvt_f32_f16_e32 v78, v128
	v_cvt_f32_f16_sdwa v79, v128 dst_sel:DWORD dst_unused:UNUSED_PAD src0_sel:WORD_1
	v_cvt_f32_f16_sdwa v75, v126 dst_sel:DWORD dst_unused:UNUSED_PAD src0_sel:WORD_1
	v_pk_mul_f32 v[36:37], v[36:37], v[76:77]
	v_pk_mul_f32 v[68:69], v[66:67], v[80:81]
	v_pk_mul_f32 v[72:73], v[70:71], v[78:79]
	v_pk_mul_f32 v[70:71], v[70:71], v[74:75]
	v_pk_mul_f32 v[74:75], v[40:41], v[36:37]
	v_pk_mul_f32 v[76:77], v[40:41], v[68:69]
	v_cvt_pk_f16_f32 v36, v36, v37
	v_cvt_pk_f16_f32 v37, v68, v69
	v_pk_mul_f32 v[78:79], v[38:39], v[72:73]
	v_pk_mul_f32 v[80:81], v[38:39], v[70:71]
	ds_write2st64_b32 v181, v36, v37 offset1:18
	v_cvt_pk_f16_f32 v36, v74, v75
	v_cvt_pk_f16_f32 v37, v76, v77
	v_pk_mul_f32 v[72:73], v[0:1], v[72:73]
	ds_write2st64_b32 v181, v36, v37 offset0:36 offset1:54
	v_cvt_pk_f16_f32 v36, v78, v79
	v_cvt_pk_f16_f32 v37, v80, v81
	v_lshl_add_u32 v252, v184, 1, v2
	ds_read_b32 v80, v253 offset:32768
	ds_read2st64_b32 v[134:135], v252 offset0:64 offset1:80
	s_waitcnt lgkmcnt(14)
	ds_read2st64_b32 v[136:137], v252 offset0:96 offset1:112
	s_waitcnt lgkmcnt(14)
	ds_write2st64_b32 v181, v36, v37 offset0:72 offset1:90
	v_cvt_f16_f32_e32 v36, v72
	v_pk_mul_f32 v[70:71], v[0:1], v[70:71]
	v_cvt_f16_f32_e32 v37, v73
	v_cvt_f16_f32_e32 v68, v70
	v_cvt_f16_f32_e32 v69, v71
	s_waitcnt lgkmcnt(14)
	ds_write_b16 v174, v36 offset:2
	s_waitcnt lgkmcnt(14)
	ds_write_b16 v174, v37 offset:42
	s_waitcnt lgkmcnt(14)
	ds_write_b16 v174, v68 offset:5122
	s_waitcnt lgkmcnt(14)
	ds_write_b16 v174, v69 offset:5162
	s_waitcnt lgkmcnt(14)
	ds_write_b16 v174, v82 offset:10242
	v_lshl_add_u32 v72, v182, 1, v2
	v_rcp_f32_e32 v68, v64
	v_rcp_f32_e32 v69, v65
	v_cvt_f32_f16_e32 v74, v131
	v_cvt_f32_f16_sdwa v75, v131 dst_sel:DWORD dst_unused:UNUSED_PAD src0_sel:WORD_1
	v_cvt_f32_f16_e32 v78, v133
	v_cvt_f32_f16_sdwa v79, v133 dst_sel:DWORD dst_unused:UNUSED_PAD src0_sel:WORD_1
	v_cvt_f32_f16_e32 v72, v130
	v_cvt_f32_f16_e32 v76, v132
	v_cvt_f32_f16_sdwa v77, v132 dst_sel:DWORD dst_unused:UNUSED_PAD src0_sel:WORD_1
	v_cvt_f32_f16_sdwa v73, v130 dst_sel:DWORD dst_unused:UNUSED_PAD src0_sel:WORD_1
	v_pk_mul_f32 v[36:37], v[66:67], v[74:75]
	v_pk_mul_f32 v[66:67], v[64:65], v[78:79]
	v_pk_mul_f32 v[70:71], v[68:69], v[76:77]
	v_pk_mul_f32 v[68:69], v[68:69], v[72:73]
	v_pk_mul_f32 v[72:73], v[40:41], v[36:37]
	v_pk_mul_f32 v[74:75], v[40:41], v[66:67]
	v_cvt_pk_f16_f32 v36, v36, v37
	v_cvt_pk_f16_f32 v37, v66, v67
	v_pk_mul_f32 v[76:77], v[38:39], v[70:71]
	v_pk_mul_f32 v[78:79], v[38:39], v[68:69]
	s_waitcnt lgkmcnt(14)
	ds_write2st64_b32 v183, v36, v37 offset1:18
	v_cvt_pk_f16_f32 v36, v72, v73
	v_cvt_pk_f16_f32 v37, v74, v75
	v_pk_mul_f32 v[70:71], v[0:1], v[70:71]
	s_waitcnt lgkmcnt(14)
	ds_write2st64_b32 v183, v36, v37 offset0:36 offset1:54
	v_cvt_pk_f16_f32 v36, v76, v77
	v_cvt_pk_f16_f32 v37, v78, v79
	s_waitcnt lgkmcnt(14)
	ds_read_b32 v78, v252 offset:32768
	s_waitcnt lgkmcnt(14)
	ds_write2st64_b32 v183, v36, v37 offset0:72 offset1:90
	v_cvt_f16_f32_e32 v36, v70
	v_pk_mul_f32 v[68:69], v[0:1], v[68:69]
	v_cvt_f16_f32_e32 v37, v71
	v_cvt_f16_f32_e32 v66, v68
	v_cvt_f16_f32_e32 v67, v69
	s_waitcnt lgkmcnt(14)
	ds_write_b16 v174, v36 offset:4
	s_waitcnt lgkmcnt(14)
	ds_write_b16 v174, v37 offset:44
	s_waitcnt lgkmcnt(14)
	ds_write_b16 v174, v66 offset:5124
	s_waitcnt lgkmcnt(14)
	ds_write_b16 v174, v67 offset:5164
	s_waitcnt lgkmcnt(14)
	ds_write_b16 v174, v80 offset:10244
	v_lshl_add_u32 v70, v184, 1, v2
	v_rcp_f32_e32 v66, v60
	v_rcp_f32_e32 v67, v61
	v_cvt_f32_f16_e32 v72, v135
	v_cvt_f32_f16_sdwa v73, v135 dst_sel:DWORD dst_unused:UNUSED_PAD src0_sel:WORD_1
	v_cvt_f32_f16_e32 v76, v137
	v_cvt_f32_f16_sdwa v77, v137 dst_sel:DWORD dst_unused:UNUSED_PAD src0_sel:WORD_1
	v_cvt_f32_f16_e32 v70, v134
	v_cvt_f32_f16_e32 v74, v136
	v_cvt_f32_f16_sdwa v75, v136 dst_sel:DWORD dst_unused:UNUSED_PAD src0_sel:WORD_1
	v_cvt_f32_f16_sdwa v71, v134 dst_sel:DWORD dst_unused:UNUSED_PAD src0_sel:WORD_1
	v_pk_mul_f32 v[36:37], v[64:65], v[72:73]
	v_pk_mul_f32 v[64:65], v[60:61], v[76:77]
	v_pk_mul_f32 v[68:69], v[66:67], v[74:75]
	v_pk_mul_f32 v[66:67], v[66:67], v[70:71]
	v_pk_mul_f32 v[70:71], v[40:41], v[36:37]
	v_pk_mul_f32 v[72:73], v[40:41], v[64:65]
	v_cvt_pk_f16_f32 v36, v36, v37
	v_cvt_pk_f16_f32 v37, v64, v65
	v_pk_mul_f32 v[74:75], v[38:39], v[68:69]
	v_pk_mul_f32 v[76:77], v[38:39], v[66:67]
	s_waitcnt lgkmcnt(14)
	ds_write2st64_b32 v185, v36, v37 offset1:18
	v_cvt_pk_f16_f32 v36, v70, v71
	v_cvt_pk_f16_f32 v37, v72, v73
	v_pk_mul_f32 v[68:69], v[0:1], v[68:69]
	s_waitcnt lgkmcnt(14)
	ds_write2st64_b32 v185, v36, v37 offset0:36 offset1:54
	v_cvt_pk_f16_f32 v36, v74, v75
	v_cvt_pk_f16_f32 v37, v76, v77
	s_waitcnt lgkmcnt(14)
	ds_write2st64_b32 v185, v36, v37 offset0:72 offset1:90
	v_cvt_f16_f32_e32 v36, v68
	v_pk_mul_f32 v[66:67], v[0:1], v[66:67]
	v_cvt_f16_f32_e32 v37, v69
	v_cvt_f16_f32_e32 v64, v66
	v_cvt_f16_f32_e32 v65, v67
	s_waitcnt lgkmcnt(14)
	ds_write_b16 v174, v36 offset:6
	s_waitcnt lgkmcnt(14)
	ds_write_b16 v174, v37 offset:46
	s_waitcnt lgkmcnt(14)
	ds_write_b16 v174, v64 offset:5126
	s_waitcnt lgkmcnt(14)
	ds_write_b16 v174, v65 offset:5166
	s_nop 0
	s_waitcnt lgkmcnt(13)
	ds_write_b16 v174, v78 offset:10246
	v_perm_b32 v36, v82, v84, s82
	v_perm_b32 v37, v78, v80, s82
	ds_write_b64 v174, v[36:37] offset:10280

.LBB0_462:
	s_or_b64 exec, exec, s[26:27]
	s_waitcnt lgkmcnt(0)
	s_barrier
	ds_read_b128 v[36:39], v210 offset:18432
	ds_read_b128 v[40:43], v210 offset:9216
	ds_read_b128 v[48:51], v210 offset:18496
	s_waitcnt lgkmcnt(1)
	v_mfma_f32_16x16x32_f16 v[52:55], v[40:43], v[36:39], 0
	ds_read_b128 v[56:59], v210 offset:9280
	ds_read_b128 v[60:63], v210 offset:23040
	ds_read_b128 v[64:67], v210 offset:13824
	ds_read_b128 v[68:71], v210 offset:13888
	ds_read_b128 v[72:75], v210 offset:23104
	v_add_u32_e32 v80, 0x1000, v215
	s_waitcnt lgkmcnt(4)
	v_mfma_f32_16x16x32_f16 v[52:55], v[56:59], v[48:51], v[52:55]
	s_nop 0
	s_nop 0
	s_nop 0
	v_mfma_f32_16x16x32_f16 v[44:47], v[36:39], v[40:43], 0
	s_nop 3
	v_cvt_f16_f32_e32 v0, v52
	v_cvt_f16_f32_e32 v1, v54
	v_cvt_f16_f32_e32 v2, v55
	v_mfma_f32_16x16x32_f16 v[44:47], v[48:51], v[56:59], v[44:47]
	v_cndmask_b32_e64 v79, 0, v0, s[12:13]
	v_cvt_f16_f32_e32 v0, v53
	v_cndmask_b32_e64 v54, 0, v1, s[18:19]
	s_waitcnt lgkmcnt(3)
	v_mfma_f32_16x16x32_f16 v[40:43], v[60:63], v[40:43], 0
	v_cndmask_b32_e64 v55, 0, v2, s[22:23]
	s_nop 1
	v_cndmask_b32_e64 v76, 0, v44, s[10:11]
	v_cndmask_b32_e64 v77, 0, v45, s[14:15]
	s_waitcnt lgkmcnt(2)
	v_mfma_f32_16x16x32_f16 v[36:39], v[36:39], v[64:67], 0
	v_cndmask_b32_e64 v52, 0, v46, s[16:17]
	v_cndmask_b32_e64 v78, 0, v47, s[20:21]
	v_cndmask_b32_e64 v53, v0, 0, s[10:11]
	v_mfma_f32_16x16x32_f16 v[44:47], v[60:63], v[64:67], 0
	v_cvt_pk_f16_f32 v1, v52, v78
	v_cvt_pk_f16_f32 v0, v76, v77
	s_nop 0
	s_waitcnt lgkmcnt(0)
	v_mfma_f32_16x16x32_f16 v[60:63], v[72:75], v[56:59], v[40:43]
	v_add_f32_e32 v56, v211, v76
	v_add_f32_e32 v57, v212, v77
	v_add_f32_e32 v58, v213, v52
	v_mfma_f32_16x16x32_f16 v[40:43], v[48:51], v[68:71], v[36:39]
	v_add_f32_e32 v59, v214, v78
	v_cvt_pk_f16_f32 v67, v18, v19
	v_cvt_pk_f16_f32 v66, v16, v17
	v_pack_b32_f16 v37, v54, v55
	v_pack_b32_f16 v36, v79, v53
	s_nop 0
	s_nop 0
	v_mfma_f32_16x16x32_f16 v[52:55], v[72:75], v[68:71], v[44:47]
	ds_read2_b64 v[68:71], v215 offset0:8 offset1:12
	v_cvt_pk_f16_f32 v65, v14, v15
	v_cvt_pk_f16_f32 v64, v12, v13
	v_mfma_f32_16x16x16_f16 v[48:51], v[0:1], v[36:37], 0
	v_cvt_pk_f16_f32 v45, v58, v59
	v_cvt_pk_f16_f32 v44, v56, v57
	s_nop 0
	v_mfma_f32_16x16x16_f16 v[36:39], v[36:37], v[0:1], 0
	s_nop 0
	s_nop 2
	v_cvt_pk_f16_f32 v1, v50, v51
	v_cvt_pk_f16_f32 v0, v48, v49
	s_nop 0
	s_nop 0
	v_cvt_pk_f16_f32 v49, v38, v39
	v_cvt_pk_f16_f32 v48, v36, v37
	v_mfma_f32_16x16x16_f16 v[44:47], v[0:1], v[44:45], v[56:59]
	s_nop 0
	s_nop 0
	s_nop 0
	v_mfma_f32_16x16x16_f16 v[36:39], v[48:49], v[0:1], 0
	v_cvt_pk_f16_f32 v59, v10, v11
	v_cvt_pk_f16_f32 v58, v8, v9
	v_cvt_pk_f16_f32 v57, v6, v7
	v_mfma_f32_16x16x16_f16 v[48:51], v[0:1], v[48:49], 0
	v_cvt_pk_f16_f32 v56, v4, v5
	s_nop 2
	v_cvt_pk_f16_f32 v1, v38, v39
	v_cvt_pk_f16_f32 v0, v36, v37
	v_cvt_pk_f16_f32 v37, v46, v47
	v_cvt_pk_f16_f32 v36, v44, v45
	s_nop 0
	s_nop 0
	v_cvt_f16_f32_e32 v52, v52
	s_add_i32 s28, s76, 1
	v_mfma_f32_16x16x16_f16 v[44:47], v[0:1], v[36:37], v[44:47]
	v_cvt_pk_f16_f32 v37, v50, v51
	v_cvt_pk_f16_f32 v36, v48, v49
	s_nop 0
	s_nop 0
	v_mfma_f32_16x16x16_f16 v[36:39], v[36:37], v[0:1], 0
	s_nop 2
	v_cvt_pk_f16_f32 v1, v46, v47
	v_cvt_pk_f16_f32 v0, v44, v45
	s_nop 2
	v_cvt_pk_f16_f32 v49, v38, v39
	v_cvt_pk_f16_f32 v48, v36, v37
	ds_read2_b64 v[36:39], v215 offset1:4
	s_waitcnt lgkmcnt(0)
	v_mfma_f32_16x16x32_f16 v[36:39], v[36:39], v[56:59], 0
	v_mfma_f32_16x16x16_f16 v[44:47], v[48:49], v[0:1], v[44:47]
	v_cvt_f16_f32_e32 v0, v60
	v_cvt_f16_f32_e32 v1, v61
	v_cvt_f16_f32_e32 v2, v62
	v_cvt_f16_f32_e32 v48, v63
	v_mfma_f32_16x16x32_f16 v[76:79], v[68:71], v[64:67], v[36:39]
	ds_read2_b64 v[72:75], v80 offset0:64 offset1:68
	ds_read2_b64 v[68:71], v80 offset0:72 offset1:76
	s_nop 0
	ds_read2st64_b64 v[36:39], v216 offset0:20 offset1:25
	v_cndmask_b32_e64 v0, 0, v0, s[10:11]
	v_cndmask_b32_e64 v49, 0, v1, s[14:15]
	v_cndmask_b32_e64 v1, 0, v2, s[16:17]
	v_cndmask_b32_e64 v2, 0, v48, s[20:21]
	v_pack_b32_f16 v1, v1, v2
	v_pack_b32_f16 v0, v0, v49
	s_nop 0
	s_waitcnt lgkmcnt(0)
	v_mov_b32_e32 v60, v36
	v_mov_b32_e32 v61, v37
	s_nop 0
	s_nop 0
	v_cvt_f16_f32_e32 v36, v40
	v_cvt_f16_f32_e32 v40, v42
	v_mfma_f32_16x16x16_f16 v[48:51], v[0:1], v[60:61], v[76:79]
	v_cvt_pk_f16_f32 v1, v46, v47
	v_cvt_pk_f16_f32 v0, v44, v45
	v_cvt_f16_f32_e32 v37, v41
	s_nop 0
	s_nop 0
	s_nop 2
	v_cvt_pk_f16_f32 v77, v50, v51
	v_cvt_pk_f16_f32 v76, v48, v49
	v_cndmask_b32_e64 v88, v40, 0, s[18:19]
	v_mfma_f32_16x16x32_f16 v[56:59], v[72:75], v[56:59], 0
	v_cndmask_b32_e64 v36, v36, 0, s[12:13]
	v_cndmask_b32_e64 v37, 0, v37, s[10:11]
	s_nop 0
	v_mfma_f32_16x16x16_f16 v[44:47], v[0:1], v[76:77], 0
	s_nop 0
	v_mfma_f32_16x16x32_f16 v[56:59], v[68:71], v[64:67], v[56:59]
	s_nop 5
	v_cvt_pk_f16_f32 v1, v46, v47
	v_cvt_pk_f16_f32 v0, v44, v45
	ds_read2_b64 v[44:47], v231 offset1:80
	ds_read_b128 v[48:51], v176
	ds_read_b64 v[76:77], v217 offset:5120
	s_waitcnt lgkmcnt(2)
	v_mov_b32_e32 v80, v44
	v_mov_b32_e32 v81, v45
	s_waitcnt lgkmcnt(1)
	v_pk_mul_f32 v[50:51], v[6:7], v[50:51]
	v_pk_mul_f32 v[48:49], v[4:5], v[48:49]
	s_nop 1
	v_mfma_f32_16x16x16_f16 v[48:51], v[80:81], v[0:1], v[48:51]
	v_cvt_f16_f32_e32 v80, v43
	v_cndmask_b32_e64 v89, v80, 0, s[22:23]
	s_waitcnt lgkmcnt(0)
	v_mfma_f32_16x16x16_f16 v[40:43], v[76:77], v[60:61], v[48:51]
	s_nop 3
	ds_read_b128 v[48:51], v176 offset:64
	ds_read_b64 v[44:45], v218 offset:5120
	v_mov_b32_e32 v76, v46
	v_mov_b32_e32 v77, v47
	s_nop 0
	s_waitcnt lgkmcnt(1)
	v_pk_mul_f32 v[50:51], v[10:11], v[50:51]
	v_pk_mul_f32 v[48:49], v[8:9], v[48:49]
	s_nop 0
	s_nop 0
	v_mfma_f32_16x16x16_f16 v[48:51], v[76:77], v[0:1], v[48:51]
	ds_read2_b64 v[76:79], v231 offset0:160 offset1:240
	s_waitcnt lgkmcnt(0)
	v_mov_b32_e32 v84, v76
	v_mfma_f32_16x16x16_f16 v[48:51], v[44:45], v[60:61], v[48:51]
	ds_read_b128 v[44:47], v176 offset:128
	ds_read_b64 v[80:81], v219 offset:5120
	v_mov_b32_e32 v85, v77
	v_pack_b32_f16 v77, v88, v89
	v_mov_b32_e32 v88, v78
	s_waitcnt lgkmcnt(1)
	v_pk_mul_f32 v[46:47], v[14:15], v[46:47]
	v_pk_mul_f32 v[44:45], v[12:13], v[44:45]
	v_mov_b32_e32 v89, v79
	v_pack_b32_f16 v76, v36, v37
	v_mfma_f32_16x16x16_f16 v[44:47], v[84:85], v[0:1], v[44:47]
	v_cndmask_b32_e64 v36, v52, 0, s[12:13]
	v_cvt_f16_f32_e32 v37, v53
	v_cndmask_b32_e64 v37, 0, v37, s[10:11]
	s_waitcnt lgkmcnt(0)
	v_mfma_f32_16x16x16_f16 v[44:47], v[80:81], v[60:61], v[44:47]
	ds_read_b128 v[80:83], v176 offset:192
	ds_read_b64 v[84:85], v220 offset:5120
	v_pack_b32_f16 v72, v36, v37
	ds_read_b128 v[68:71], v221 offset:9216
	ds_read_b128 v[94:97], v221 offset:9280
	s_waitcnt lgkmcnt(3)
	v_pk_mul_f32 v[82:83], v[18:19], v[82:83]
	v_pk_mul_f32 v[80:81], v[16:17], v[80:81]
	ds_read_b128 v[64:67], v221 offset:18432
	ds_read_b128 v[98:101], v221 offset:23104
	v_mfma_f32_16x16x16_f16 v[78:81], v[88:89], v[0:1], v[80:83]
	ds_read_b128 v[90:93], v221 offset:18496
	s_nop 1
	v_cvt_f16_f32_e32 v82, v54
	v_cvt_f16_f32_e32 v83, v55
	s_waitcnt lgkmcnt(5)
	v_mfma_f32_16x16x16_f16 v[52:55], v[84:85], v[60:61], v[78:81]
	ds_read_b128 v[86:89], v221 offset:13824
	s_nop 1
	v_cndmask_b32_e64 v78, v82, 0, s[18:19]
	v_cndmask_b32_e64 v79, v83, 0, s[22:23]
	v_pack_b32_f16 v73, v78, v79
	s_nop 0
	s_nop 0
	v_add_u32_e32 v80, s71, v153
	v_add_u32_e32 v81, s70, v230
	v_mfma_f32_16x16x16_f16 v[56:59], v[76:77], v[0:1], v[56:59]
	ds_read_b128 v[76:79], v221 offset:23040
	v_subrev_u32_e32 v102, 64, v80
	v_add_u32_e32 v0, 0x7ff, v81
	v_mfma_f32_16x16x16_f16 v[58:61], v[72:73], v[60:61], v[56:59]
	v_cndmask_b32_e64 v0, v0, v102, s[2:3]
	v_add_u32_e32 v0, v0, v151
	v_mad_i64_i32 v[0:1], s[26:27], v0, s91, v[122:123]
	s_waitcnt lgkmcnt(4)
	v_mfma_f32_16x16x32_f16 v[82:85], v[68:71], v[64:67], 0
	s_nop 2
	v_cvt_f16_f32_e32 v2, v58
	v_cvt_f16_f32_e32 v60, v60
	global_store_short v[0:1], v2, off
	v_subrev_u32_e32 v0, 63, v80
	v_xad_u32 v1, v102, -2, v170
	v_cvt_f16_f32_e32 v2, v59
	ds_read_b128 v[56:59], v221 offset:13888
	v_mfma_f32_16x16x32_f16 v[72:75], v[64:67], v[68:71], 0
	v_cndmask_b32_e64 v0, v1, v0, s[2:3]
	v_add_u32_e32 v0, v0, v151
	v_mad_i64_i32 v[0:1], s[26:27], v0, s91, v[122:123]
	s_waitcnt lgkmcnt(2)
	v_mfma_f32_16x16x32_f16 v[62:65], v[64:67], v[86:89], 0
	global_store_short v[0:1], v2, off
	v_subrev_u32_e32 v0, 62, v80
	v_xad_u32 v1, v102, -3, v170
	v_mfma_f32_16x16x32_f16 v[82:85], v[94:97], v[90:93], v[82:85]
	v_cndmask_b32_e64 v36, v1, v0, s[2:3]
	v_add_u32_e32 v36, v36, v151
	s_waitcnt lgkmcnt(1)
	v_mfma_f32_16x16x32_f16 v[68:71], v[76:79], v[68:71], 0
	v_mfma_f32_16x16x32_f16 v[86:89], v[76:79], v[86:89], 0
	s_nop 2
	v_cvt_f16_f32_e32 v1, v82
	v_cvt_f16_f32_e32 v2, v83
	v_cvt_f16_f32_e32 v66, v85
	v_mfma_f32_16x16x32_f16 v[72:75], v[90:93], v[94:97], v[72:75]
	s_nop 0
	v_cndmask_b32_e64 v66, 0, v66, s[22:23]
	s_waitcnt lgkmcnt(0)
	v_mfma_f32_16x16x32_f16 v[76:79], v[90:93], v[56:59], v[62:65]
	s_nop 0
	s_nop 2
	v_cndmask_b32_e64 v0, 0, v72, s[10:11]
	v_cndmask_b32_e64 v37, 0, v73, s[14:15]
	v_cvt_f16_f32_e32 v63, v84
	v_mfma_f32_16x16x32_f16 v[94:97], v[98:101], v[94:97], v[68:71]
	v_cndmask_b32_e64 v64, 0, v74, s[16:17]
	v_cndmask_b32_e64 v65, 0, v75, s[20:21]
	v_cndmask_b32_e64 v63, 0, v63, s[18:19]
	v_cndmask_b32_e64 v68, 0, v1, s[12:13]
	v_cndmask_b32_e64 v69, v2, 0, s[10:11]
	v_add_f32_e32 v62, v211, v0
	v_cvt_pk_f16_f32 v1, v64, v65
	v_cvt_pk_f16_f32 v0, v0, v37
	s_nop 0
	v_pack_b32_f16 v67, v63, v66
	v_pack_b32_f16 v66, v68, v69
	s_nop 0
	s_nop 0
	v_add_f32_e32 v63, v212, v37
	v_add_f32_e32 v64, v213, v64
	v_mfma_f32_16x16x16_f16 v[70:73], v[0:1], v[66:67], 0
	v_add_f32_e32 v65, v214, v65
	v_cvt_pk_f16_f32 v83, v64, v65
	v_cvt_pk_f16_f32 v82, v62, v63
	v_mfma_f32_16x16x16_f16 v[66:69], v[66:67], v[0:1], 0
	s_nop 0
	s_nop 2
	v_cvt_pk_f16_f32 v0, v70, v71
	s_nop 0
	s_nop 0
	v_cvt_pk_f16_f32 v1, v72, v73
	v_cvt_pk_f16_f32 v69, v68, v69
	v_cvt_pk_f16_f32 v68, v66, v67
	v_mfma_f32_16x16x16_f16 v[62:65], v[0:1], v[82:83], v[62:65]
	v_mad_i64_i32 v[36:37], s[26:27], v36, s91, v[122:123]
	global_store_short v[36:37], v60, off
	v_mfma_f32_16x16x16_f16 v[72:75], v[68:69], v[0:1], 0
	v_cvt_f16_f32_e32 v82, v61
	v_subrev_u32_e32 v36, 61, v80
	v_xad_u32 v37, v102, -4, v170
	v_mfma_f32_16x16x16_f16 v[66:69], v[0:1], v[68:69], 0
	s_nop 0
	v_cvt_pk_f16_f32 v71, v64, v65
	s_nop 1
	v_cvt_pk_f16_f32 v1, v74, v75
	v_cvt_pk_f16_f32 v0, v72, v73
	v_mfma_f32_16x16x32_f16 v[56:59], v[98:101], v[56:59], v[86:89]
	v_cvt_pk_f16_f32 v70, v62, v63
	s_nop 0
	s_nop 0
	v_cvt_pk_f16_f32 v85, v68, v69
	v_cvt_pk_f16_f32 v84, v66, v67
	s_nop 0
	s_nop 0
	v_mfma_f32_16x16x16_f16 v[88:91], v[0:1], v[70:71], v[62:65]
	ds_read2_b64 v[68:71], v222 offset1:4
	ds_read2_b64 v[72:75], v222 offset0:8 offset1:12
	v_cndmask_b32_e64 v36, v37, v36, s[2:3]
	v_mfma_f32_16x16x16_f16 v[60:63], v[84:85], v[0:1], 0
	v_add_u32_e32 v83, v36, v151
	s_nop 2
	v_cvt_pk_f16_f32 v1, v90, v91
	v_cvt_pk_f16_f32 v0, v88, v89
	v_cvt_pk_f16_f32 v67, v54, v55
	v_cvt_pk_f16_f32 v66, v52, v53
	v_cvt_pk_f16_f32 v85, v62, v63
	v_cvt_pk_f16_f32 v84, v60, v61
	v_cvt_pk_f16_f32 v63, v50, v51
	v_cvt_pk_f16_f32 v62, v48, v49
	v_cvt_pk_f16_f32 v61, v42, v43
	v_cvt_pk_f16_f32 v60, v40, v41
	v_cvt_pk_f16_f32 v65, v46, v47
	v_cvt_pk_f16_f32 v64, v44, v45
	s_waitcnt lgkmcnt(1)
	v_mfma_f32_16x16x32_f16 v[68:71], v[68:71], v[60:63], 0
	v_add_u32_e32 v36, 0x1000, v222
	s_nop 0
	v_cvt_f16_f32_e32 v76, v76
	s_waitcnt lgkmcnt(0)
	v_mfma_f32_16x16x32_f16 v[98:101], v[72:75], v[64:67], v[68:71]
	ds_read2_b64 v[72:75], v36 offset0:64 offset1:68
	s_nop 1
	ds_read2_b64 v[68:71], v36 offset0:72 offset1:76
	v_cvt_f16_f32_e32 v36, v97
	v_cvt_f16_f32_e32 v97, v77
	v_mfma_f32_16x16x16_f16 v[84:87], v[84:85], v[0:1], v[88:91]
	v_cvt_f16_f32_e32 v0, v94
	v_cvt_f16_f32_e32 v1, v95
	v_cvt_f16_f32_e32 v2, v96
	v_cndmask_b32_e64 v96, v76, 0, s[12:13]
	v_cndmask_b32_e64 v0, 0, v0, s[10:11]
	v_cndmask_b32_e64 v37, 0, v1, s[14:15]
	v_cndmask_b32_e64 v1, 0, v2, s[16:17]
	v_cndmask_b32_e64 v2, 0, v36, s[20:21]
	v_pack_b32_f16 v1, v1, v2
	v_pack_b32_f16 v0, v0, v37
	s_nop 0
	v_mov_b32_e32 v36, v38
	v_mov_b32_e32 v37, v39
	s_nop 0
	s_nop 0
	v_mov_b32_e32 v94, v3
	v_mov_b32_e32 v95, v3
	v_mfma_f32_16x16x16_f16 v[88:91], v[0:1], v[36:37], v[98:101]
	v_cvt_pk_f16_f32 v1, v86, v87
	v_cvt_pk_f16_f32 v0, v84, v85
	v_cvt_f16_f32_e32 v56, v56
	v_cvt_f16_f32_e32 v98, v78
	v_cvt_f16_f32_e32 v99, v79
	s_nop 2
	v_cvt_pk_f16_f32 v91, v90, v91
	v_cvt_pk_f16_f32 v90, v88, v89
	v_cndmask_b32_e64 v97, 0, v97, s[10:11]
	v_cndmask_b32_e64 v98, v98, 0, s[18:19]
	v_mfma_f32_16x16x16_f16 v[84:87], v[0:1], v[90:91], 0
	v_add_u32_e32 v2, 0x800, v231
	v_mov_b32_e32 v90, v3
	v_mov_b32_e32 v91, v3
	v_cndmask_b32_e64 v99, v99, 0, s[22:23]
	s_nop 3
	v_cvt_pk_f16_f32 v1, v86, v87
	v_cvt_pk_f16_f32 v0, v84, v85
	ds_read2_b64 v[84:87], v2 offset0:64 offset1:144
	ds_read_b128 v[76:79], v176 offset:256
	ds_read_b64 v[88:89], v223 offset:5120
	s_nop 0
	s_waitcnt lgkmcnt(2)
	v_mov_b32_e32 v92, v84
	v_mov_b32_e32 v93, v85
	s_waitcnt lgkmcnt(1)
	v_pk_mul_f32 v[42:43], v[42:43], v[78:79]
	v_pk_mul_f32 v[40:41], v[40:41], v[76:77]
	ds_read_b128 v[76:79], v176 offset:320
	ds_read_b64 v[84:85], v224 offset:5120
	v_mfma_f32_16x16x16_f16 v[40:43], v[92:93], v[0:1], v[40:43]
	s_waitcnt lgkmcnt(1)
	v_pk_mul_f32 v[48:49], v[48:49], v[76:77]
	v_add_u32_e32 v76, 0xc00, v231
	v_mfma_f32_16x16x16_f16 v[40:43], v[88:89], v[36:37], v[40:43]
	v_mov_b32_e32 v88, v86
	v_mov_b32_e32 v89, v87
	v_pk_mul_f32 v[50:51], v[50:51], v[78:79]
	s_nop 0
	s_nop 0
	ds_read2_b64 v[76:79], v76 offset0:96 offset1:176
	v_mfma_f32_16x16x16_f16 v[48:51], v[88:89], v[0:1], v[48:51]
	s_waitcnt lgkmcnt(0)
	v_mov_b32_e32 v92, v76
	v_mfma_f32_16x16x16_f16 v[48:51], v[84:85], v[36:37], v[48:51]
	ds_read_b128 v[84:87], v176 offset:384
	ds_read_b64 v[88:89], v225 offset:5120
	v_mov_b32_e32 v93, v77
	v_pack_b32_f16 v76, v96, v97
	v_cndmask_b32_e64 v96, v56, 0, s[12:13]
	s_waitcnt lgkmcnt(1)
	v_pk_mul_f32 v[46:47], v[46:47], v[86:87]
	v_pk_mul_f32 v[44:45], v[44:45], v[84:85]
	v_cvt_f16_f32_e32 v56, v57
	v_cvt_f16_f32_e32 v57, v58
	v_mfma_f32_16x16x16_f16 v[44:47], v[92:93], v[0:1], v[44:47]
	v_cvt_f16_f32_e32 v58, v59
	v_mov_b32_e32 v92, v78
	v_mov_b32_e32 v93, v79
	s_waitcnt lgkmcnt(0)
	v_mfma_f32_16x16x16_f16 v[44:47], v[88:89], v[36:37], v[44:47]
	ds_read_b128 v[84:87], v176 offset:448
	ds_read_b64 v[88:89], v226 offset:5120
	v_cndmask_b32_e64 v78, v57, 0, s[18:19]
	v_cndmask_b32_e64 v79, v58, 0, s[22:23]
	v_pack_b32_f16 v77, v98, v99
	s_waitcnt lgkmcnt(1)
	v_pk_mul_f32 v[52:53], v[52:53], v[84:85]
	v_cndmask_b32_e64 v84, 0, v56, s[10:11]
	v_mfma_f32_16x16x32_f16 v[56:59], v[72:75], v[60:63], 0
	v_pack_b32_f16 v61, v78, v79
	v_mov_b32_e32 v78, v3
	v_mov_b32_e32 v79, v3
	v_mfma_f32_16x16x32_f16 v[56:59], v[68:71], v[64:67], v[56:59]
	v_mul_f32_e64 v54, v54, v86
	v_mul_f32_e64 v55, v55, v87
	v_pack_b32_f16 v60, v96, v84
	v_mov_b32_e32 v62, v3
	v_mov_b32_e32 v63, v3
	v_mfma_f32_16x16x16_f16 v[52:55], v[92:93], v[0:1], v[52:55]
	v_mfma_f32_16x16x16_f16 v[56:59], v[76:77], v[0:1], v[56:59]
	v_mad_i64_i32 v[0:1], s[26:27], v83, s91, v[122:123]
	global_store_short v[0:1], v82, off
	s_waitcnt lgkmcnt(0)
	v_mfma_f32_16x16x16_f16 v[52:55], v[88:89], v[36:37], v[52:55]
	v_subrev_u32_e32 v0, 48, v80
	v_add_u32_e32 v1, 0x7ef, v81
	v_cndmask_b32_e64 v0, v1, v0, s[2:3]
	v_mfma_f32_16x16x16_f16 v[36:39], v[60:61], v[36:37], v[56:59]
	v_add_u32_e32 v0, v0, v151
	v_mad_i64_i32 v[0:1], s[26:27], v0, s91, v[122:123]
	s_nop 5
	v_cvt_f16_f32_e32 v2, v36
	global_store_short v[0:1], v2, off
	v_subrev_u32_e32 v0, 47, v80
	v_add_u32_e32 v1, 0x7ee, v81
	v_cvt_f16_f32_e32 v2, v37
	v_cndmask_b32_e64 v0, v1, v0, s[2:3]
	v_add_u32_e32 v0, v0, v151
	v_mad_i64_i32 v[0:1], s[26:27], v0, s91, v[122:123]
	global_store_short v[0:1], v2, off
	v_subrev_u32_e32 v0, 46, v80
	v_add_u32_e32 v1, 0x7ed, v81
	v_cvt_f16_f32_e32 v2, v38
	v_cndmask_b32_e64 v0, v1, v0, s[2:3]
	v_add_u32_e32 v0, v0, v151
	v_mad_i64_i32 v[0:1], s[26:27], v0, s91, v[122:123]
	global_store_short v[0:1], v2, off
	v_subrev_u32_e32 v0, 45, v80
	v_add_u32_e32 v1, 0x7ec, v81
	v_cndmask_b32_e64 v0, v1, v0, s[2:3]
	v_cvt_f16_f32_e32 v2, v39
	v_add_u32_e32 v0, v0, v151
	v_mad_i64_i32 v[0:1], s[26:27], v0, s91, v[122:123]
	s_mov_b64 s[26:27], 0
	global_store_short v[0:1], v2, off

.LBB0_468:
	v_cmp_lt_i32_e32 vcc, 2, v172
	s_and_saveexec_b64 s[28:29], vcc
	s_xor_b64 s[28:29], exec, s[28:29]
	s_cbranch_execz .LBB0_470
	v_lshl_add_u32 v253, v202, 1, v2
	v_lshl_add_u32 v252, v204, 1, v2
	ds_read2st64_b32 v[36:37], v253 offset0:64 offset1:80
	ds_read2st64_b32 v[46:47], v253 offset0:96 offset1:112
	ds_read_b32 v60, v253 offset:32768
	ds_read2st64_b32 v[126:127], v252 offset0:64 offset1:80
	ds_read2st64_b32 v[128:129], v252 offset0:96 offset1:112
	ds_read_b32 v61, v252 offset:32768
	v_lshl_add_u32 v48, v202, 1, v2
	s_nop 0
	s_nop 0
	v_rcp_f32_e32 v44, v62
	v_rcp_f32_e32 v45, v63
	v_lshl_add_u32 v253, v206, 1, v2
	ds_read2st64_b32 v[130:131], v253 offset0:64 offset1:80
	s_waitcnt lgkmcnt(5)
	v_cvt_f32_f16_e32 v58, v47
	v_cvt_f32_f16_e32 v50, v37
	v_cvt_f32_f16_sdwa v51, v37 dst_sel:DWORD dst_unused:UNUSED_PAD src0_sel:WORD_1
	ds_read2st64_b32 v[132:133], v253 offset0:96 offset1:112
	v_cvt_f32_f16_sdwa v59, v47 dst_sel:DWORD dst_unused:UNUSED_PAD src0_sel:WORD_1
	v_cvt_f32_f16_e32 v48, v36
	v_cvt_f32_f16_e32 v54, v46
	v_cvt_f32_f16_sdwa v55, v46 dst_sel:DWORD dst_unused:UNUSED_PAD src0_sel:WORD_1
	v_cvt_f32_f16_sdwa v49, v36 dst_sel:DWORD dst_unused:UNUSED_PAD src0_sel:WORD_1
	v_pk_mul_f32 v[36:37], v[42:43], v[50:51]
	v_pk_mul_f32 v[42:43], v[62:63], v[58:59]
	v_pk_mul_f32 v[46:47], v[44:45], v[54:55]
	v_pk_mul_f32 v[44:45], v[44:45], v[48:49]
	v_pk_mul_f32 v[48:49], v[40:41], v[36:37]
	v_pk_mul_f32 v[50:51], v[40:41], v[42:43]
	v_cvt_pk_f16_f32 v36, v36, v37
	v_cvt_pk_f16_f32 v37, v42, v43
	v_pk_mul_f32 v[54:55], v[38:39], v[46:47]
	v_pk_mul_f32 v[58:59], v[38:39], v[44:45]
	ds_write2st64_b32 v203, v36, v37 offset1:18
	v_cvt_pk_f16_f32 v36, v48, v49
	v_cvt_pk_f16_f32 v37, v50, v51
	v_pk_mul_f32 v[46:47], v[0:1], v[46:47]
	ds_write2st64_b32 v203, v36, v37 offset0:36 offset1:54
	v_cvt_pk_f16_f32 v36, v54, v55
	v_cvt_pk_f16_f32 v37, v58, v59
	ds_write2st64_b32 v203, v36, v37 offset0:72 offset1:90
	v_cvt_f16_f32_e32 v36, v46
	v_pk_mul_f32 v[44:45], v[0:1], v[44:45]
	v_cvt_f16_f32_e32 v37, v47
	v_cvt_f16_f32_e32 v42, v44
	v_cvt_f16_f32_e32 v43, v45
	ds_write_b16 v174, v36 offset:24
	ds_write_b16 v174, v37 offset:64
	ds_write_b16 v174, v42 offset:5144
	ds_write_b16 v174, v43 offset:5184
	s_waitcnt lgkmcnt(12)
	ds_write_b16 v174, v60 offset:10264
	v_lshl_add_u32 v46, v204, 1, v2
	v_rcp_f32_e32 v42, v56
	v_rcp_f32_e32 v43, v57
	s_waitcnt lgkmcnt(12)
	v_cvt_f32_f16_e32 v48, v127
	v_cvt_f32_f16_sdwa v49, v127 dst_sel:DWORD dst_unused:UNUSED_PAD src0_sel:WORD_1
	s_waitcnt lgkmcnt(11)
	v_cvt_f32_f16_e32 v54, v129
	v_cvt_f32_f16_sdwa v55, v129 dst_sel:DWORD dst_unused:UNUSED_PAD src0_sel:WORD_1
	v_cvt_f32_f16_e32 v46, v126
	v_cvt_f32_f16_e32 v50, v128
	v_cvt_f32_f16_sdwa v51, v128 dst_sel:DWORD dst_unused:UNUSED_PAD src0_sel:WORD_1
	v_cvt_f32_f16_sdwa v47, v126 dst_sel:DWORD dst_unused:UNUSED_PAD src0_sel:WORD_1
	v_pk_mul_f32 v[36:37], v[62:63], v[48:49]
	v_pk_mul_f32 v[44:45], v[56:57], v[54:55]
	v_pk_mul_f32 v[48:49], v[42:43], v[50:51]
	v_pk_mul_f32 v[42:43], v[42:43], v[46:47]
	v_pk_mul_f32 v[46:47], v[40:41], v[36:37]
	v_pk_mul_f32 v[50:51], v[40:41], v[44:45]
	v_cvt_pk_f16_f32 v36, v36, v37
	v_cvt_pk_f16_f32 v37, v44, v45
	v_pk_mul_f32 v[54:55], v[38:39], v[48:49]
	v_pk_mul_f32 v[58:59], v[38:39], v[42:43]
	ds_write2st64_b32 v205, v36, v37 offset1:18
	v_cvt_pk_f16_f32 v36, v46, v47
	v_cvt_pk_f16_f32 v37, v50, v51
	v_pk_mul_f32 v[48:49], v[0:1], v[48:49]
	ds_write2st64_b32 v205, v36, v37 offset0:36 offset1:54
	v_cvt_pk_f16_f32 v36, v54, v55
	v_cvt_pk_f16_f32 v37, v58, v59
	v_lshl_add_u32 v252, v208, 1, v2
	ds_read_b32 v58, v253 offset:32768
	ds_read2st64_b32 v[134:135], v252 offset0:64 offset1:80
	s_waitcnt lgkmcnt(14)
	ds_read2st64_b32 v[136:137], v252 offset0:96 offset1:112
	s_waitcnt lgkmcnt(14)
	ds_write2st64_b32 v205, v36, v37 offset0:72 offset1:90
	v_cvt_f16_f32_e32 v36, v48
	v_pk_mul_f32 v[42:43], v[0:1], v[42:43]
	v_cvt_f16_f32_e32 v37, v49
	v_cvt_f16_f32_e32 v42, v42
	v_cvt_f16_f32_e32 v43, v43
	s_waitcnt lgkmcnt(14)
	ds_write_b16 v174, v36 offset:26
	s_waitcnt lgkmcnt(14)
	ds_write_b16 v174, v37 offset:66
	s_waitcnt lgkmcnt(14)
	ds_write_b16 v174, v42 offset:5146
	s_waitcnt lgkmcnt(14)
	ds_write_b16 v174, v43 offset:5186
	s_waitcnt lgkmcnt(14)
	ds_write_b16 v174, v61 offset:10266
	v_lshl_add_u32 v46, v206, 1, v2
	v_rcp_f32_e32 v42, v52
	v_rcp_f32_e32 v43, v53
	v_lshl_add_u32 v2, v208, 1, v2
	v_cvt_f32_f16_e32 v48, v131
	v_cvt_f32_f16_sdwa v49, v131 dst_sel:DWORD dst_unused:UNUSED_PAD src0_sel:WORD_1
	v_cvt_f32_f16_e32 v54, v133
	v_cvt_f32_f16_sdwa v55, v133 dst_sel:DWORD dst_unused:UNUSED_PAD src0_sel:WORD_1
	v_cvt_f32_f16_e32 v46, v130
	v_cvt_f32_f16_e32 v50, v132
	v_cvt_f32_f16_sdwa v51, v132 dst_sel:DWORD dst_unused:UNUSED_PAD src0_sel:WORD_1
	v_cvt_f32_f16_sdwa v47, v130 dst_sel:DWORD dst_unused:UNUSED_PAD src0_sel:WORD_1
	v_pk_mul_f32 v[36:37], v[56:57], v[48:49]
	v_pk_mul_f32 v[44:45], v[52:53], v[54:55]
	v_pk_mul_f32 v[48:49], v[42:43], v[50:51]
	v_pk_mul_f32 v[42:43], v[42:43], v[46:47]
	v_pk_mul_f32 v[46:47], v[40:41], v[36:37]
	v_pk_mul_f32 v[50:51], v[40:41], v[44:45]
	v_cvt_pk_f16_f32 v36, v36, v37
	v_cvt_pk_f16_f32 v37, v44, v45
	v_pk_mul_f32 v[54:55], v[38:39], v[48:49]
	v_pk_mul_f32 v[56:57], v[38:39], v[42:43]
	s_waitcnt lgkmcnt(14)
	ds_write2st64_b32 v207, v36, v37 offset1:18
	v_cvt_pk_f16_f32 v36, v46, v47
	v_cvt_pk_f16_f32 v37, v50, v51
	v_pk_mul_f32 v[48:49], v[0:1], v[48:49]
	s_waitcnt lgkmcnt(14)
	ds_write2st64_b32 v207, v36, v37 offset0:36 offset1:54
	v_cvt_pk_f16_f32 v36, v54, v55
	v_cvt_pk_f16_f32 v37, v56, v57
	s_waitcnt lgkmcnt(14)
	ds_write2st64_b32 v207, v36, v37 offset0:72 offset1:90
	v_cvt_f16_f32_e32 v36, v48
	v_pk_mul_f32 v[42:43], v[0:1], v[42:43]
	v_cvt_f16_f32_e32 v37, v49
	v_cvt_f16_f32_e32 v42, v42
	v_cvt_f16_f32_e32 v43, v43
	s_waitcnt lgkmcnt(14)
	ds_write_b16 v174, v36 offset:28
	s_waitcnt lgkmcnt(14)
	ds_write_b16 v174, v37 offset:68
	s_waitcnt lgkmcnt(14)
	ds_write_b16 v174, v42 offset:5148
	s_waitcnt lgkmcnt(14)
	ds_write_b16 v174, v43 offset:5188
	s_waitcnt lgkmcnt(14)
	ds_write_b16 v174, v58 offset:10268
	s_waitcnt lgkmcnt(14)
	ds_read_b32 v2, v252 offset:32768
	v_rcp_f32_e32 v42, v0
	v_rcp_f32_e32 v43, v1
	v_cvt_f32_f16_e32 v48, v135
	v_cvt_f32_f16_sdwa v49, v135 dst_sel:DWORD dst_unused:UNUSED_PAD src0_sel:WORD_1
	v_cvt_f32_f16_e32 v54, v137
	v_cvt_f32_f16_sdwa v55, v137 dst_sel:DWORD dst_unused:UNUSED_PAD src0_sel:WORD_1
	v_cvt_f32_f16_e32 v46, v134
	v_cvt_f32_f16_e32 v50, v136
	v_cvt_f32_f16_sdwa v51, v136 dst_sel:DWORD dst_unused:UNUSED_PAD src0_sel:WORD_1
	v_cvt_f32_f16_sdwa v47, v134 dst_sel:DWORD dst_unused:UNUSED_PAD src0_sel:WORD_1
	v_pk_mul_f32 v[36:37], v[52:53], v[48:49]
	v_pk_mul_f32 v[44:45], v[0:1], v[54:55]
	v_pk_mul_f32 v[48:49], v[42:43], v[50:51]
	v_pk_mul_f32 v[42:43], v[42:43], v[46:47]
	v_pk_mul_f32 v[46:47], v[40:41], v[36:37]
	v_pk_mul_f32 v[40:41], v[40:41], v[44:45]
	v_cvt_pk_f16_f32 v36, v36, v37
	v_cvt_pk_f16_f32 v37, v44, v45
	v_pk_mul_f32 v[50:51], v[38:39], v[48:49]
	v_pk_mul_f32 v[38:39], v[38:39], v[42:43]
	s_waitcnt lgkmcnt(14)
	ds_write2st64_b32 v209, v36, v37 offset1:18
	v_cvt_pk_f16_f32 v36, v46, v47
	v_cvt_pk_f16_f32 v37, v40, v41
	v_pk_mul_f32 v[48:49], v[0:1], v[48:49]
	s_waitcnt lgkmcnt(14)
	ds_write2st64_b32 v209, v36, v37 offset0:36 offset1:54
	v_cvt_pk_f16_f32 v36, v50, v51
	v_cvt_pk_f16_f32 v37, v38, v39
	s_waitcnt lgkmcnt(14)
	ds_write2st64_b32 v209, v36, v37 offset0:72 offset1:90
	v_cvt_f16_f32_e32 v36, v48
	v_pk_mul_f32 v[42:43], v[0:1], v[42:43]
	v_cvt_f16_f32_e32 v37, v49
	v_cvt_f16_f32_e32 v38, v42
	v_cvt_f16_f32_e32 v39, v43
	s_waitcnt lgkmcnt(14)
	ds_write_b16 v174, v36 offset:30
	s_waitcnt lgkmcnt(14)
	ds_write_b16 v174, v37 offset:70
	s_waitcnt lgkmcnt(14)
	ds_write_b16 v174, v38 offset:5150
	s_waitcnt lgkmcnt(14)
	ds_write_b16 v174, v39 offset:5190
	s_nop 0
	s_waitcnt lgkmcnt(7)
	ds_write_b16 v174, v2 offset:10270
	v_perm_b32 v36, v61, v60, s82
	v_perm_b32 v37, v2, v58, s82
	ds_write_b64 v174, v[36:37] offset:10304
.LBB0_470:
	s_andn2_saveexec_b64 s[28:29], s[28:29]
	s_cbranch_execz .LBB0_472
	v_lshl_add_u32 v253, v194, 1, v2
	v_lshl_add_u32 v252, v196, 1, v2
	ds_read2st64_b32 v[36:37], v253 offset0:64 offset1:80
	ds_read2st64_b32 v[48:49], v253 offset0:96 offset1:112
	ds_read_b32 v64, v253 offset:32768
	ds_read2st64_b32 v[126:127], v252 offset0:64 offset1:80
	ds_read2st64_b32 v[128:129], v252 offset0:96 offset1:112
	v_lshl_add_u32 v52, v194, 1, v2
	s_nop 0
	s_nop 0
	s_nop 0
	v_rcp_f32_e32 v44, v58
	v_rcp_f32_e32 v45, v59
	s_waitcnt lgkmcnt(3)
	v_cvt_f32_f16_e32 v60, v49
	v_cvt_f32_f16_e32 v54, v37
	v_cvt_f32_f16_sdwa v55, v37 dst_sel:DWORD dst_unused:UNUSED_PAD src0_sel:WORD_1
	v_cvt_f32_f16_sdwa v61, v49 dst_sel:DWORD dst_unused:UNUSED_PAD src0_sel:WORD_1
	v_cvt_f32_f16_e32 v52, v36
	v_cvt_f32_f16_e32 v56, v48
	v_cvt_f32_f16_sdwa v57, v48 dst_sel:DWORD dst_unused:UNUSED_PAD src0_sel:WORD_1
	v_cvt_f32_f16_sdwa v53, v36 dst_sel:DWORD dst_unused:UNUSED_PAD src0_sel:WORD_1
	v_pk_mul_f32 v[36:37], v[38:39], v[54:55]
	v_pk_mul_f32 v[48:49], v[58:59], v[60:61]
	v_pk_mul_f32 v[54:55], v[44:45], v[56:57]
	v_pk_mul_f32 v[44:45], v[44:45], v[52:53]
	v_pk_mul_f32 v[52:53], v[40:41], v[36:37]
	v_pk_mul_f32 v[56:57], v[40:41], v[48:49]
	v_cvt_pk_f16_f32 v36, v36, v37
	v_cvt_pk_f16_f32 v37, v48, v49
	v_pk_mul_f32 v[60:61], v[38:39], v[54:55]
	v_pk_mul_f32 v[62:63], v[38:39], v[44:45]
	ds_write2st64_b32 v195, v36, v37 offset1:18
	v_cvt_pk_f16_f32 v36, v52, v53
	v_cvt_pk_f16_f32 v37, v56, v57
	v_pk_mul_f32 v[54:55], v[0:1], v[54:55]
	ds_write2st64_b32 v195, v36, v37 offset0:36 offset1:54
	v_cvt_pk_f16_f32 v36, v60, v61
	v_cvt_pk_f16_f32 v37, v62, v63
	v_lshl_add_u32 v253, v198, 1, v2
	ds_read_b32 v62, v252 offset:32768
	ds_read2st64_b32 v[130:131], v253 offset0:64 offset1:80
	ds_read2st64_b32 v[132:133], v253 offset0:96 offset1:112
	ds_write2st64_b32 v195, v36, v37 offset0:72 offset1:90
	v_cvt_f16_f32_e32 v36, v54
	v_pk_mul_f32 v[44:45], v[0:1], v[44:45]
	v_cvt_f16_f32_e32 v37, v55
	v_cvt_f16_f32_e32 v44, v44
	v_cvt_f16_f32_e32 v45, v45
	ds_write_b16 v174, v36 offset:16
	ds_write_b16 v174, v37 offset:56
	ds_write_b16 v174, v44 offset:5136
	ds_write_b16 v174, v45 offset:5176
	s_waitcnt lgkmcnt(12)
	ds_write_b16 v174, v64 offset:10256
	v_lshl_add_u32 v52, v196, 1, v2
	v_rcp_f32_e32 v44, v50
	v_rcp_f32_e32 v45, v51
	s_waitcnt lgkmcnt(12)
	v_cvt_f32_f16_e32 v54, v127
	v_cvt_f32_f16_sdwa v55, v127 dst_sel:DWORD dst_unused:UNUSED_PAD src0_sel:WORD_1
	s_waitcnt lgkmcnt(11)
	v_cvt_f32_f16_e32 v60, v129
	v_cvt_f32_f16_sdwa v61, v129 dst_sel:DWORD dst_unused:UNUSED_PAD src0_sel:WORD_1
	v_cvt_f32_f16_e32 v52, v126
	v_cvt_f32_f16_e32 v56, v128
	v_cvt_f32_f16_sdwa v57, v128 dst_sel:DWORD dst_unused:UNUSED_PAD src0_sel:WORD_1
	v_cvt_f32_f16_sdwa v53, v126 dst_sel:DWORD dst_unused:UNUSED_PAD src0_sel:WORD_1
	v_pk_mul_f32 v[36:37], v[58:59], v[54:55]
	v_pk_mul_f32 v[48:49], v[50:51], v[60:61]
	v_pk_mul_f32 v[54:55], v[44:45], v[56:57]
	v_pk_mul_f32 v[44:45], v[44:45], v[52:53]
	v_pk_mul_f32 v[52:53], v[40:41], v[36:37]
	v_pk_mul_f32 v[56:57], v[40:41], v[48:49]
	v_cvt_pk_f16_f32 v36, v36, v37
	v_cvt_pk_f16_f32 v37, v48, v49
	v_pk_mul_f32 v[58:59], v[38:39], v[54:55]
	v_pk_mul_f32 v[60:61], v[38:39], v[44:45]
	ds_write2st64_b32 v197, v36, v37 offset1:18
	v_cvt_pk_f16_f32 v36, v52, v53
	v_cvt_pk_f16_f32 v37, v56, v57
	v_pk_mul_f32 v[54:55], v[0:1], v[54:55]
	ds_write2st64_b32 v197, v36, v37 offset0:36 offset1:54
	v_cvt_pk_f16_f32 v36, v58, v59
	v_cvt_pk_f16_f32 v37, v60, v61
	v_lshl_add_u32 v252, v200, 1, v2
	ds_read_b32 v60, v253 offset:32768
	ds_read2st64_b32 v[134:135], v252 offset0:64 offset1:80
	s_waitcnt lgkmcnt(14)
	ds_read2st64_b32 v[136:137], v252 offset0:96 offset1:112
	s_waitcnt lgkmcnt(14)
	ds_write2st64_b32 v197, v36, v37 offset0:72 offset1:90
	v_cvt_f16_f32_e32 v36, v54
	v_pk_mul_f32 v[44:45], v[0:1], v[44:45]
	v_cvt_f16_f32_e32 v37, v55
	v_cvt_f16_f32_e32 v44, v44
	v_cvt_f16_f32_e32 v45, v45
	s_waitcnt lgkmcnt(14)
	ds_write_b16 v174, v36 offset:18
	s_waitcnt lgkmcnt(14)
	ds_write_b16 v174, v37 offset:58
	s_waitcnt lgkmcnt(14)
	ds_write_b16 v174, v44 offset:5138
	s_waitcnt lgkmcnt(14)
	ds_write_b16 v174, v45 offset:5178
	s_waitcnt lgkmcnt(14)
	ds_write_b16 v174, v62 offset:10258
	v_lshl_add_u32 v52, v198, 1, v2
	v_rcp_f32_e32 v44, v46
	v_rcp_f32_e32 v45, v47
	v_lshl_add_u32 v2, v200, 1, v2
	v_cvt_f32_f16_e32 v54, v131
	v_cvt_f32_f16_sdwa v55, v131 dst_sel:DWORD dst_unused:UNUSED_PAD src0_sel:WORD_1
	v_cvt_f32_f16_e32 v58, v133
	v_cvt_f32_f16_sdwa v59, v133 dst_sel:DWORD dst_unused:UNUSED_PAD src0_sel:WORD_1
	v_cvt_f32_f16_e32 v52, v130
	v_cvt_f32_f16_e32 v56, v132
	v_cvt_f32_f16_sdwa v57, v132 dst_sel:DWORD dst_unused:UNUSED_PAD src0_sel:WORD_1
	v_cvt_f32_f16_sdwa v53, v130 dst_sel:DWORD dst_unused:UNUSED_PAD src0_sel:WORD_1
	v_pk_mul_f32 v[36:37], v[50:51], v[54:55]
	v_pk_mul_f32 v[48:49], v[46:47], v[58:59]
	v_pk_mul_f32 v[50:51], v[44:45], v[56:57]
	v_pk_mul_f32 v[44:45], v[44:45], v[52:53]
	v_pk_mul_f32 v[52:53], v[40:41], v[36:37]
	v_pk_mul_f32 v[54:55], v[40:41], v[48:49]
	v_cvt_pk_f16_f32 v36, v36, v37
	v_cvt_pk_f16_f32 v37, v48, v49
	v_pk_mul_f32 v[56:57], v[38:39], v[50:51]
	v_pk_mul_f32 v[58:59], v[38:39], v[44:45]
	s_waitcnt lgkmcnt(14)
	ds_write2st64_b32 v199, v36, v37 offset1:18
	v_cvt_pk_f16_f32 v36, v52, v53
	v_cvt_pk_f16_f32 v37, v54, v55
	v_pk_mul_f32 v[50:51], v[0:1], v[50:51]
	s_waitcnt lgkmcnt(14)
	ds_write2st64_b32 v199, v36, v37 offset0:36 offset1:54
	v_cvt_pk_f16_f32 v36, v56, v57
	v_cvt_pk_f16_f32 v37, v58, v59
	s_waitcnt lgkmcnt(14)
	ds_write2st64_b32 v199, v36, v37 offset0:72 offset1:90
	v_cvt_f16_f32_e32 v36, v50
	v_pk_mul_f32 v[44:45], v[0:1], v[44:45]
	v_cvt_f16_f32_e32 v37, v51
	v_cvt_f16_f32_e32 v44, v44
	v_cvt_f16_f32_e32 v45, v45
	s_waitcnt lgkmcnt(14)
	ds_write_b16 v174, v36 offset:20
	s_waitcnt lgkmcnt(14)
	ds_write_b16 v174, v37 offset:60
	s_waitcnt lgkmcnt(14)
	ds_write_b16 v174, v44 offset:5140
	s_waitcnt lgkmcnt(14)
	ds_write_b16 v174, v45 offset:5180
	s_waitcnt lgkmcnt(14)
	ds_write_b16 v174, v60 offset:10260
	s_waitcnt lgkmcnt(14)
	ds_read_b32 v2, v252 offset:32768
	v_rcp_f32_e32 v44, v42
	v_rcp_f32_e32 v45, v43
	v_cvt_f32_f16_e32 v52, v135
	v_cvt_f32_f16_sdwa v53, v135 dst_sel:DWORD dst_unused:UNUSED_PAD src0_sel:WORD_1
	v_cvt_f32_f16_e32 v56, v137
	v_cvt_f32_f16_sdwa v57, v137 dst_sel:DWORD dst_unused:UNUSED_PAD src0_sel:WORD_1
	v_cvt_f32_f16_e32 v50, v134
	v_cvt_f32_f16_e32 v54, v136
	v_cvt_f32_f16_sdwa v55, v136 dst_sel:DWORD dst_unused:UNUSED_PAD src0_sel:WORD_1
	v_cvt_f32_f16_sdwa v51, v134 dst_sel:DWORD dst_unused:UNUSED_PAD src0_sel:WORD_1
	v_pk_mul_f32 v[36:37], v[46:47], v[52:53]
	v_pk_mul_f32 v[42:43], v[42:43], v[56:57]
	v_pk_mul_f32 v[46:47], v[44:45], v[54:55]
	v_pk_mul_f32 v[44:45], v[44:45], v[50:51]
	v_pk_mul_f32 v[48:49], v[40:41], v[36:37]
	v_pk_mul_f32 v[40:41], v[40:41], v[42:43]
	v_cvt_pk_f16_f32 v36, v36, v37
	v_cvt_pk_f16_f32 v37, v42, v43
	v_pk_mul_f32 v[50:51], v[38:39], v[46:47]
	v_pk_mul_f32 v[38:39], v[38:39], v[44:45]
	s_waitcnt lgkmcnt(14)
	ds_write2st64_b32 v201, v36, v37 offset1:18
	v_cvt_pk_f16_f32 v36, v48, v49
	v_cvt_pk_f16_f32 v37, v40, v41
	v_pk_mul_f32 v[46:47], v[0:1], v[46:47]
	s_waitcnt lgkmcnt(14)
	ds_write2st64_b32 v201, v36, v37 offset0:36 offset1:54
	v_cvt_pk_f16_f32 v36, v50, v51
	v_cvt_pk_f16_f32 v37, v38, v39
	s_waitcnt lgkmcnt(14)
	ds_write2st64_b32 v201, v36, v37 offset0:72 offset1:90
	v_cvt_f16_f32_e32 v36, v46
	v_pk_mul_f32 v[44:45], v[0:1], v[44:45]
	v_cvt_f16_f32_e32 v37, v47
	v_cvt_f16_f32_e32 v38, v44
	v_cvt_f16_f32_e32 v39, v45
	s_waitcnt lgkmcnt(14)
	ds_write_b16 v174, v36 offset:22
	s_waitcnt lgkmcnt(14)
	ds_write_b16 v174, v37 offset:62
	s_waitcnt lgkmcnt(14)
	ds_write_b16 v174, v38 offset:5142
	s_waitcnt lgkmcnt(14)
	ds_write_b16 v174, v39 offset:5182
	s_nop 0
	s_waitcnt lgkmcnt(7)
	ds_write_b16 v174, v2 offset:10262
	v_perm_b32 v36, v62, v64, s82
	v_perm_b32 v37, v2, v60, s82
	ds_write_b64 v174, v[36:37] offset:10296

.LBB0_473:
	v_cmp_eq_u32_e32 vcc, 1, v172
	s_and_saveexec_b64 s[28:29], vcc
	s_cbranch_execz .LBB0_475
	v_lshl_add_u32 v253, v186, 1, v2
	v_lshl_add_u32 v252, v188, 1, v2
	ds_read2st64_b32 v[36:37], v253 offset0:64 offset1:80
	ds_read2st64_b32 v[46:47], v253 offset0:96 offset1:112
	ds_read_b32 v62, v253 offset:32768
	ds_read2st64_b32 v[126:127], v252 offset0:64 offset1:80
	ds_read2st64_b32 v[128:129], v252 offset0:96 offset1:112
	v_lshl_add_u32 v50, v186, 1, v2
	s_nop 0
	s_nop 0
	s_nop 0
	v_rcp_f32_e32 v42, v54
	v_rcp_f32_e32 v43, v55
	s_waitcnt lgkmcnt(3)
	v_cvt_f32_f16_e32 v58, v47
	v_cvt_f32_f16_e32 v52, v37
	v_cvt_f32_f16_sdwa v53, v37 dst_sel:DWORD dst_unused:UNUSED_PAD src0_sel:WORD_1
	v_cvt_f32_f16_sdwa v59, v47 dst_sel:DWORD dst_unused:UNUSED_PAD src0_sel:WORD_1
	v_cvt_f32_f16_e32 v50, v36
	v_cvt_f32_f16_e32 v56, v46
	v_cvt_f32_f16_sdwa v57, v46 dst_sel:DWORD dst_unused:UNUSED_PAD src0_sel:WORD_1
	v_cvt_f32_f16_sdwa v51, v36 dst_sel:DWORD dst_unused:UNUSED_PAD src0_sel:WORD_1
	v_pk_mul_f32 v[36:37], v[60:61], v[52:53]
	v_pk_mul_f32 v[46:47], v[54:55], v[58:59]
	v_pk_mul_f32 v[52:53], v[42:43], v[56:57]
	v_pk_mul_f32 v[42:43], v[42:43], v[50:51]
	v_pk_mul_f32 v[50:51], v[40:41], v[36:37]
	v_pk_mul_f32 v[56:57], v[40:41], v[46:47]
	v_cvt_pk_f16_f32 v36, v36, v37
	v_cvt_pk_f16_f32 v37, v46, v47
	v_pk_mul_f32 v[58:59], v[38:39], v[52:53]
	v_pk_mul_f32 v[60:61], v[38:39], v[42:43]
	ds_write2st64_b32 v187, v36, v37 offset1:18
	v_cvt_pk_f16_f32 v36, v50, v51
	v_cvt_pk_f16_f32 v37, v56, v57
	v_pk_mul_f32 v[52:53], v[0:1], v[52:53]
	ds_write2st64_b32 v187, v36, v37 offset0:36 offset1:54
	v_cvt_pk_f16_f32 v36, v58, v59
	v_cvt_pk_f16_f32 v37, v60, v61
	v_lshl_add_u32 v253, v190, 1, v2
	ds_read_b32 v60, v252 offset:32768
	ds_read2st64_b32 v[130:131], v253 offset0:64 offset1:80
	ds_read2st64_b32 v[132:133], v253 offset0:96 offset1:112
	ds_write2st64_b32 v187, v36, v37 offset0:72 offset1:90
	v_cvt_f16_f32_e32 v36, v52
	v_pk_mul_f32 v[42:43], v[0:1], v[42:43]
	v_cvt_f16_f32_e32 v37, v53
	v_cvt_f16_f32_e32 v42, v42
	v_cvt_f16_f32_e32 v43, v43
	ds_write_b16 v174, v36 offset:8
	ds_write_b16 v174, v37 offset:48
	ds_write_b16 v174, v42 offset:5128
	ds_write_b16 v174, v43 offset:5168
	s_waitcnt lgkmcnt(12)
	ds_write_b16 v174, v62 offset:10248
	v_lshl_add_u32 v50, v188, 1, v2
	v_rcp_f32_e32 v42, v48
	v_rcp_f32_e32 v43, v49
	s_waitcnt lgkmcnt(12)
	v_cvt_f32_f16_e32 v52, v127
	v_cvt_f32_f16_sdwa v53, v127 dst_sel:DWORD dst_unused:UNUSED_PAD src0_sel:WORD_1
	s_waitcnt lgkmcnt(11)
	v_cvt_f32_f16_e32 v58, v129
	v_cvt_f32_f16_sdwa v59, v129 dst_sel:DWORD dst_unused:UNUSED_PAD src0_sel:WORD_1
	v_cvt_f32_f16_e32 v50, v126
	v_cvt_f32_f16_e32 v56, v128
	v_cvt_f32_f16_sdwa v57, v128 dst_sel:DWORD dst_unused:UNUSED_PAD src0_sel:WORD_1
	v_cvt_f32_f16_sdwa v51, v126 dst_sel:DWORD dst_unused:UNUSED_PAD src0_sel:WORD_1
	v_pk_mul_f32 v[36:37], v[54:55], v[52:53]
	v_pk_mul_f32 v[46:47], v[48:49], v[58:59]
	v_pk_mul_f32 v[52:53], v[42:43], v[56:57]
	v_pk_mul_f32 v[42:43], v[42:43], v[50:51]
	v_pk_mul_f32 v[50:51], v[40:41], v[36:37]
	v_pk_mul_f32 v[54:55], v[40:41], v[46:47]
	v_cvt_pk_f16_f32 v36, v36, v37
	v_cvt_pk_f16_f32 v37, v46, v47
	v_pk_mul_f32 v[56:57], v[38:39], v[52:53]
	v_pk_mul_f32 v[58:59], v[38:39], v[42:43]
	ds_write2st64_b32 v189, v36, v37 offset1:18
	v_cvt_pk_f16_f32 v36, v50, v51
	v_cvt_pk_f16_f32 v37, v54, v55
	v_pk_mul_f32 v[52:53], v[0:1], v[52:53]
	ds_write2st64_b32 v189, v36, v37 offset0:36 offset1:54
	v_cvt_pk_f16_f32 v36, v56, v57
	v_cvt_pk_f16_f32 v37, v58, v59
	v_lshl_add_u32 v252, v192, 1, v2
	ds_read_b32 v58, v253 offset:32768
	ds_read2st64_b32 v[134:135], v252 offset0:64 offset1:80
	s_waitcnt lgkmcnt(14)
	ds_read2st64_b32 v[136:137], v252 offset0:96 offset1:112
	s_waitcnt lgkmcnt(14)
	ds_write2st64_b32 v189, v36, v37 offset0:72 offset1:90
	v_cvt_f16_f32_e32 v36, v52
	v_pk_mul_f32 v[42:43], v[0:1], v[42:43]
	v_cvt_f16_f32_e32 v37, v53
	v_cvt_f16_f32_e32 v42, v42
	v_cvt_f16_f32_e32 v43, v43
	s_waitcnt lgkmcnt(14)
	ds_write_b16 v174, v36 offset:10
	s_waitcnt lgkmcnt(14)
	ds_write_b16 v174, v37 offset:50
	s_waitcnt lgkmcnt(14)
	ds_write_b16 v174, v42 offset:5130
	s_waitcnt lgkmcnt(14)
	ds_write_b16 v174, v43 offset:5170
	s_waitcnt lgkmcnt(14)
	ds_write_b16 v174, v60 offset:10250
	v_lshl_add_u32 v50, v190, 1, v2
	v_rcp_f32_e32 v42, v44
	v_rcp_f32_e32 v43, v45
	v_lshl_add_u32 v2, v192, 1, v2
	v_cvt_f32_f16_e32 v52, v131
	v_cvt_f32_f16_sdwa v53, v131 dst_sel:DWORD dst_unused:UNUSED_PAD src0_sel:WORD_1
	v_cvt_f32_f16_e32 v56, v133
	v_cvt_f32_f16_sdwa v57, v133 dst_sel:DWORD dst_unused:UNUSED_PAD src0_sel:WORD_1
	v_cvt_f32_f16_e32 v50, v130
	v_cvt_f32_f16_e32 v54, v132
	v_cvt_f32_f16_sdwa v55, v132 dst_sel:DWORD dst_unused:UNUSED_PAD src0_sel:WORD_1
	v_cvt_f32_f16_sdwa v51, v130 dst_sel:DWORD dst_unused:UNUSED_PAD src0_sel:WORD_1
	v_pk_mul_f32 v[36:37], v[48:49], v[52:53]
	v_pk_mul_f32 v[46:47], v[44:45], v[56:57]
	v_pk_mul_f32 v[48:49], v[42:43], v[54:55]
	v_pk_mul_f32 v[42:43], v[42:43], v[50:51]
	v_pk_mul_f32 v[50:51], v[40:41], v[36:37]
	v_pk_mul_f32 v[52:53], v[40:41], v[46:47]
	v_cvt_pk_f16_f32 v36, v36, v37
	v_cvt_pk_f16_f32 v37, v46, v47
	v_pk_mul_f32 v[54:55], v[38:39], v[48:49]
	v_pk_mul_f32 v[56:57], v[38:39], v[42:43]
	s_waitcnt lgkmcnt(14)
	ds_write2st64_b32 v191, v36, v37 offset1:18
	v_cvt_pk_f16_f32 v36, v50, v51
	v_cvt_pk_f16_f32 v37, v52, v53
	v_pk_mul_f32 v[48:49], v[0:1], v[48:49]
	s_waitcnt lgkmcnt(14)
	ds_write2st64_b32 v191, v36, v37 offset0:36 offset1:54
	v_cvt_pk_f16_f32 v36, v54, v55
	v_cvt_pk_f16_f32 v37, v56, v57
	s_waitcnt lgkmcnt(14)
	ds_write2st64_b32 v191, v36, v37 offset0:72 offset1:90
	v_cvt_f16_f32_e32 v36, v48
	v_pk_mul_f32 v[42:43], v[0:1], v[42:43]
	v_cvt_f16_f32_e32 v37, v49
	v_cvt_f16_f32_e32 v42, v42
	v_cvt_f16_f32_e32 v43, v43
	s_waitcnt lgkmcnt(14)
	ds_write_b16 v174, v36 offset:12
	s_waitcnt lgkmcnt(14)
	ds_write_b16 v174, v37 offset:52
	s_waitcnt lgkmcnt(14)
	ds_write_b16 v174, v42 offset:5132
	s_waitcnt lgkmcnt(14)
	ds_write_b16 v174, v43 offset:5172
	s_waitcnt lgkmcnt(14)
	ds_write_b16 v174, v58 offset:10252
	s_waitcnt lgkmcnt(14)
	ds_read_b32 v2, v252 offset:32768
	v_cvt_f32_f16_e32 v48, v135
	v_cvt_f32_f16_sdwa v49, v135 dst_sel:DWORD dst_unused:UNUSED_PAD src0_sel:WORD_1
	v_cvt_f32_f16_e32 v52, v137
	v_cvt_f32_f16_sdwa v53, v137 dst_sel:DWORD dst_unused:UNUSED_PAD src0_sel:WORD_1
	v_cvt_f32_f16_e32 v46, v134
	v_cvt_f32_f16_e32 v50, v136
	v_cvt_f32_f16_sdwa v51, v136 dst_sel:DWORD dst_unused:UNUSED_PAD src0_sel:WORD_1
	v_cvt_f32_f16_sdwa v47, v134 dst_sel:DWORD dst_unused:UNUSED_PAD src0_sel:WORD_1
	v_pk_mul_f32 v[36:37], v[44:45], v[48:49]
	v_pk_mul_f32 v[42:43], v[38:39], v[52:53]
	v_pk_mul_f32 v[44:45], v[40:41], v[50:51]
	v_pk_mul_f32 v[46:47], v[40:41], v[46:47]
	v_pk_mul_f32 v[48:49], v[40:41], v[36:37]
	v_pk_mul_f32 v[40:41], v[40:41], v[42:43]
	v_cvt_pk_f16_f32 v36, v36, v37
	v_cvt_pk_f16_f32 v37, v42, v43
	v_pk_mul_f32 v[50:51], v[38:39], v[44:45]
	v_pk_mul_f32 v[38:39], v[38:39], v[46:47]
	s_waitcnt lgkmcnt(14)
	ds_write2st64_b32 v193, v36, v37 offset1:18
	v_cvt_pk_f16_f32 v36, v48, v49
	v_cvt_pk_f16_f32 v37, v40, v41
	v_pk_mul_f32 v[44:45], v[0:1], v[44:45]
	s_waitcnt lgkmcnt(14)
	ds_write2st64_b32 v193, v36, v37 offset0:36 offset1:54
	v_cvt_pk_f16_f32 v36, v50, v51
	v_cvt_pk_f16_f32 v37, v38, v39
	s_waitcnt lgkmcnt(14)
	ds_write2st64_b32 v193, v36, v37 offset0:72 offset1:90
	v_cvt_f16_f32_e32 v36, v44
	v_pk_mul_f32 v[46:47], v[0:1], v[46:47]
	v_cvt_f16_f32_e32 v37, v45
	v_cvt_f16_f32_e32 v38, v46
	v_cvt_f16_f32_e32 v39, v47
	s_waitcnt lgkmcnt(14)
	ds_write_b16 v174, v36 offset:14
	s_waitcnt lgkmcnt(14)
	ds_write_b16 v174, v37 offset:54
	s_waitcnt lgkmcnt(14)
	ds_write_b16 v174, v38 offset:5134
	s_waitcnt lgkmcnt(14)
	ds_write_b16 v174, v39 offset:5174
	s_nop 0
	s_waitcnt lgkmcnt(7)
	ds_write_b16 v174, v2 offset:10254
	v_perm_b32 v36, v60, v62, s82
	v_perm_b32 v37, v2, v58, s82
	ds_write_b64 v174, v[36:37] offset:10288

.LBB0_929:
	s_and_b32 s27, s26, 1
	v_lshl_add_u32 v0, s27, 13, v234
	ds_read2_b64 v[36:39], v0 offset1:32
	v_mad_u32_u24 v2, s27, v167, v235
	s_waitcnt lgkmcnt(0)
	v_pk_mul_f32 v[66:67], v[36:37], v[38:39]
	v_xor_b32_e32 v90, 16, v0
	ds_read2_b64 v[38:41], v90 offset0:64 offset1:96
	s_waitcnt lgkmcnt(0)
	v_pk_mul_f32 v[64:65], v[66:67], v[38:39]
	s_nop 0
	v_pk_mul_f32 v[60:61], v[64:65], v[40:41]
	v_xor_b32_e32 v91, 32, v0
	ds_read2_b64 v[38:41], v91 offset0:128 offset1:160
	s_waitcnt lgkmcnt(0)
	v_pk_mul_f32 v[54:55], v[60:61], v[38:39]
	s_nop 0
	v_pk_mul_f32 v[48:49], v[54:55], v[40:41]
	v_xor_b32_e32 v92, 48, v0
	ds_read2_b64 v[38:41], v92 offset0:192 offset1:224
	v_add_u32_e32 v0, 0x800, v0
	v_xor_b32_e32 v91, 32, v0
	ds_read2_b64 v[68:71], v91 offset0:128 offset1:160
	s_waitcnt lgkmcnt(1)
	v_pk_mul_f32 v[44:45], v[48:49], v[38:39]
	s_nop 0
	v_pk_mul_f32 v[38:39], v[44:45], v[40:41]
	ds_read2_b64 v[40:43], v0 offset1:32
	s_waitcnt lgkmcnt(0)
	v_pk_mul_f32 v[58:59], v[38:39], v[40:41]
	s_nop 0
	v_pk_mul_f32 v[50:51], v[58:59], v[42:43]
	v_xor_b32_e32 v90, 16, v0
	ds_read2_b64 v[40:43], v90 offset0:64 offset1:96
	s_waitcnt lgkmcnt(0)
	v_pk_mul_f32 v[46:47], v[50:51], v[40:41]
	s_nop 0
	v_pk_mul_f32 v[42:43], v[46:47], v[42:43]
	v_rcp_f32_e32 v40, v38
	v_pk_mul_f32 v[62:63], v[42:43], v[68:69]
	v_rcp_f32_e32 v41, v39
	v_pk_mul_f32 v[56:57], v[62:63], v[70:71]
	v_xor_b32_e32 v92, 48, v0
	ds_read2_b64 v[68:71], v92 offset0:192 offset1:224
	s_waitcnt lgkmcnt(0)
	v_pk_mul_f32 v[52:53], v[56:57], v[68:69]
	s_nop 0
	v_pk_mul_f32 v[0:1], v[52:53], v[70:71]
	s_and_saveexec_b64 s[28:29], s[4:5]
	s_cbranch_execz .LBB0_931
	v_lshl_add_u32 v251, v179, 1, v2
	v_lshl_add_u32 v250, v186, 1, v2
	ds_read2st64_b32 v[72:73], v251 offset0:96 offset1:112
	ds_read2st64_b32 v[68:69], v251 offset0:64 offset1:80
	ds_read_b32 v84, v251 offset:32768
	ds_read2st64_b32 v[128:129], v250 offset0:64 offset1:80
	ds_read2st64_b32 v[130:131], v250 offset0:96 offset1:112
	v_lshl_add_u32 v74, v179, 1, v2
	s_nop 0
	s_nop 0
	v_rcp_f32_e32 v70, v36
	v_rcp_f32_e32 v71, v37
	s_waitcnt lgkmcnt(4)
	v_cvt_f32_f16_e32 v78, v73
	v_cvt_f32_f16_sdwa v79, v73 dst_sel:DWORD dst_unused:UNUSED_PAD src0_sel:WORD_1
	s_waitcnt lgkmcnt(3)
	v_cvt_f32_f16_e32 v74, v68
	v_cvt_f32_f16_sdwa v75, v68 dst_sel:DWORD dst_unused:UNUSED_PAD src0_sel:WORD_1
	v_cvt_f32_f16_e32 v76, v72
	v_cvt_f32_f16_sdwa v77, v72 dst_sel:DWORD dst_unused:UNUSED_PAD src0_sel:WORD_1
	v_cvt_f32_f16_e32 v72, v69
	v_cvt_f32_f16_sdwa v73, v69 dst_sel:DWORD dst_unused:UNUSED_PAD src0_sel:WORD_1
	v_pk_mul_f32 v[78:79], v[36:37], v[78:79]
	v_pk_mul_f32 v[76:77], v[70:71], v[76:77]
	v_pk_mul_f32 v[70:71], v[70:71], v[74:75]
	v_pk_mul_f32 v[72:73], v[40:41], v[72:73]
	v_pk_mul_f32 v[74:75], v[40:41], v[78:79]
	v_cvt_pk_f16_f32 v68, v78, v79
	v_pk_mul_f32 v[80:81], v[38:39], v[76:77]
	v_pk_mul_f32 v[82:83], v[38:39], v[70:71]
	ds_write2st64_b32 v185, v69, v68 offset1:18
	v_cvt_pk_f16_f32 v68, v72, v73
	v_cvt_pk_f16_f32 v69, v74, v75
	v_pk_mul_f32 v[76:77], v[0:1], v[76:77]
	ds_write2st64_b32 v185, v68, v69 offset0:36 offset1:54
	v_cvt_pk_f16_f32 v68, v80, v81
	v_cvt_pk_f16_f32 v69, v82, v83
	v_lshl_add_u32 v251, v188, 1, v2
	ds_read_b32 v82, v250 offset:32768
	ds_read2st64_b32 v[132:133], v251 offset0:64 offset1:80
	ds_read2st64_b32 v[134:135], v251 offset0:96 offset1:112
	ds_write2st64_b32 v185, v68, v69 offset0:72 offset1:90
	v_cvt_f16_f32_e32 v68, v76
	v_pk_mul_f32 v[70:71], v[0:1], v[70:71]
	v_cvt_f16_f32_e32 v69, v77
	v_cvt_f16_f32_e32 v70, v70
	v_cvt_f16_f32_e32 v71, v71
	ds_write_b16 v180, v68
	ds_write_b16 v180, v69 offset:40
	ds_write_b16 v180, v70 offset:5120
	ds_write_b16 v180, v71 offset:5160
	s_waitcnt lgkmcnt(12)
	ds_write_b16 v180, v84 offset:10240
	v_lshl_add_u32 v74, v186, 1, v2
	v_rcp_f32_e32 v70, v66
	v_rcp_f32_e32 v71, v67
	s_waitcnt lgkmcnt(12)
	v_cvt_f32_f16_e32 v76, v129
	v_cvt_f32_f16_sdwa v77, v129 dst_sel:DWORD dst_unused:UNUSED_PAD src0_sel:WORD_1
	s_waitcnt lgkmcnt(11)
	v_cvt_f32_f16_e32 v80, v131
	v_cvt_f32_f16_sdwa v81, v131 dst_sel:DWORD dst_unused:UNUSED_PAD src0_sel:WORD_1
	v_cvt_f32_f16_e32 v74, v128
	v_cvt_f32_f16_e32 v78, v130
	v_cvt_f32_f16_sdwa v79, v130 dst_sel:DWORD dst_unused:UNUSED_PAD src0_sel:WORD_1
	v_cvt_f32_f16_sdwa v75, v128 dst_sel:DWORD dst_unused:UNUSED_PAD src0_sel:WORD_1
	v_pk_mul_f32 v[36:37], v[36:37], v[76:77]
	v_pk_mul_f32 v[68:69], v[66:67], v[80:81]
	v_pk_mul_f32 v[72:73], v[70:71], v[78:79]
	v_pk_mul_f32 v[70:71], v[70:71], v[74:75]
	v_pk_mul_f32 v[74:75], v[40:41], v[36:37]
	v_pk_mul_f32 v[76:77], v[40:41], v[68:69]
	v_cvt_pk_f16_f32 v36, v36, v37
	v_cvt_pk_f16_f32 v37, v68, v69
	v_pk_mul_f32 v[78:79], v[38:39], v[72:73]
	v_pk_mul_f32 v[80:81], v[38:39], v[70:71]
	ds_write2st64_b32 v187, v36, v37 offset1:18
	v_cvt_pk_f16_f32 v36, v74, v75
	v_cvt_pk_f16_f32 v37, v76, v77
	v_pk_mul_f32 v[72:73], v[0:1], v[72:73]
	ds_write2st64_b32 v187, v36, v37 offset0:36 offset1:54
	v_cvt_pk_f16_f32 v36, v78, v79
	v_cvt_pk_f16_f32 v37, v80, v81
	v_lshl_add_u32 v250, v190, 1, v2
	ds_read_b32 v80, v251 offset:32768
	ds_read2st64_b32 v[136:137], v250 offset0:64 offset1:80
	s_waitcnt lgkmcnt(14)
	ds_read2st64_b32 v[138:139], v250 offset0:96 offset1:112
	s_waitcnt lgkmcnt(14)
	ds_write2st64_b32 v187, v36, v37 offset0:72 offset1:90
	v_cvt_f16_f32_e32 v36, v72
	v_pk_mul_f32 v[70:71], v[0:1], v[70:71]
	v_cvt_f16_f32_e32 v37, v73
	v_cvt_f16_f32_e32 v68, v70
	v_cvt_f16_f32_e32 v69, v71
	s_waitcnt lgkmcnt(14)
	ds_write_b16 v180, v36 offset:2
	s_waitcnt lgkmcnt(14)
	ds_write_b16 v180, v37 offset:42
	s_waitcnt lgkmcnt(14)
	ds_write_b16 v180, v68 offset:5122
	s_waitcnt lgkmcnt(14)
	ds_write_b16 v180, v69 offset:5162
	s_waitcnt lgkmcnt(14)
	ds_write_b16 v180, v82 offset:10242
	v_lshl_add_u32 v72, v188, 1, v2
	v_rcp_f32_e32 v68, v64
	v_rcp_f32_e32 v69, v65
	v_cvt_f32_f16_e32 v74, v133
	v_cvt_f32_f16_sdwa v75, v133 dst_sel:DWORD dst_unused:UNUSED_PAD src0_sel:WORD_1
	v_cvt_f32_f16_e32 v78, v135
	v_cvt_f32_f16_sdwa v79, v135 dst_sel:DWORD dst_unused:UNUSED_PAD src0_sel:WORD_1
	v_cvt_f32_f16_e32 v72, v132
	v_cvt_f32_f16_e32 v76, v134
	v_cvt_f32_f16_sdwa v77, v134 dst_sel:DWORD dst_unused:UNUSED_PAD src0_sel:WORD_1
	v_cvt_f32_f16_sdwa v73, v132 dst_sel:DWORD dst_unused:UNUSED_PAD src0_sel:WORD_1
	v_pk_mul_f32 v[36:37], v[66:67], v[74:75]
	v_pk_mul_f32 v[66:67], v[64:65], v[78:79]
	v_pk_mul_f32 v[70:71], v[68:69], v[76:77]
	v_pk_mul_f32 v[68:69], v[68:69], v[72:73]
	v_pk_mul_f32 v[72:73], v[40:41], v[36:37]
	v_pk_mul_f32 v[74:75], v[40:41], v[66:67]
	v_cvt_pk_f16_f32 v36, v36, v37
	v_cvt_pk_f16_f32 v37, v66, v67
	v_pk_mul_f32 v[76:77], v[38:39], v[70:71]
	v_pk_mul_f32 v[78:79], v[38:39], v[68:69]
	s_waitcnt lgkmcnt(14)
	ds_write2st64_b32 v189, v36, v37 offset1:18
	v_cvt_pk_f16_f32 v36, v72, v73
	v_cvt_pk_f16_f32 v37, v74, v75
	v_pk_mul_f32 v[70:71], v[0:1], v[70:71]
	s_waitcnt lgkmcnt(14)
	ds_write2st64_b32 v189, v36, v37 offset0:36 offset1:54
	v_cvt_pk_f16_f32 v36, v76, v77
	v_cvt_pk_f16_f32 v37, v78, v79
	s_waitcnt lgkmcnt(14)
	ds_read_b32 v78, v250 offset:32768
	s_waitcnt lgkmcnt(14)
	ds_write2st64_b32 v189, v36, v37 offset0:72 offset1:90
	v_cvt_f16_f32_e32 v36, v70
	v_pk_mul_f32 v[68:69], v[0:1], v[68:69]
	v_cvt_f16_f32_e32 v37, v71
	v_cvt_f16_f32_e32 v66, v68
	v_cvt_f16_f32_e32 v67, v69
	s_waitcnt lgkmcnt(14)
	ds_write_b16 v180, v36 offset:4
	s_waitcnt lgkmcnt(14)
	ds_write_b16 v180, v37 offset:44
	s_waitcnt lgkmcnt(14)
	ds_write_b16 v180, v66 offset:5124
	s_waitcnt lgkmcnt(14)
	ds_write_b16 v180, v67 offset:5164
	s_waitcnt lgkmcnt(14)
	ds_write_b16 v180, v80 offset:10244
	v_lshl_add_u32 v70, v190, 1, v2
	v_rcp_f32_e32 v66, v60
	v_rcp_f32_e32 v67, v61
	v_cvt_f32_f16_e32 v72, v137
	v_cvt_f32_f16_sdwa v73, v137 dst_sel:DWORD dst_unused:UNUSED_PAD src0_sel:WORD_1
	v_cvt_f32_f16_e32 v76, v139
	v_cvt_f32_f16_sdwa v77, v139 dst_sel:DWORD dst_unused:UNUSED_PAD src0_sel:WORD_1
	v_cvt_f32_f16_e32 v70, v136
	v_cvt_f32_f16_e32 v74, v138
	v_cvt_f32_f16_sdwa v75, v138 dst_sel:DWORD dst_unused:UNUSED_PAD src0_sel:WORD_1
	v_cvt_f32_f16_sdwa v71, v136 dst_sel:DWORD dst_unused:UNUSED_PAD src0_sel:WORD_1
	v_pk_mul_f32 v[36:37], v[64:65], v[72:73]
	v_pk_mul_f32 v[64:65], v[60:61], v[76:77]
	v_pk_mul_f32 v[68:69], v[66:67], v[74:75]
	v_pk_mul_f32 v[66:67], v[66:67], v[70:71]
	v_pk_mul_f32 v[70:71], v[40:41], v[36:37]
	v_pk_mul_f32 v[72:73], v[40:41], v[64:65]
	v_cvt_pk_f16_f32 v36, v36, v37
	v_cvt_pk_f16_f32 v37, v64, v65
	v_pk_mul_f32 v[74:75], v[38:39], v[68:69]
	v_pk_mul_f32 v[76:77], v[38:39], v[66:67]
	s_waitcnt lgkmcnt(14)
	ds_write2st64_b32 v191, v36, v37 offset1:18
	v_cvt_pk_f16_f32 v36, v70, v71
	v_cvt_pk_f16_f32 v37, v72, v73
	v_pk_mul_f32 v[68:69], v[0:1], v[68:69]
	s_waitcnt lgkmcnt(14)
	ds_write2st64_b32 v191, v36, v37 offset0:36 offset1:54
	v_cvt_pk_f16_f32 v36, v74, v75
	v_cvt_pk_f16_f32 v37, v76, v77
	s_waitcnt lgkmcnt(14)
	ds_write2st64_b32 v191, v36, v37 offset0:72 offset1:90
	v_cvt_f16_f32_e32 v36, v68
	v_pk_mul_f32 v[66:67], v[0:1], v[66:67]
	v_cvt_f16_f32_e32 v37, v69
	v_cvt_f16_f32_e32 v64, v66
	v_cvt_f16_f32_e32 v65, v67
	s_waitcnt lgkmcnt(14)
	ds_write_b16 v180, v36 offset:6
	s_waitcnt lgkmcnt(14)
	ds_write_b16 v180, v37 offset:46
	s_waitcnt lgkmcnt(14)
	ds_write_b16 v180, v64 offset:5126
	s_waitcnt lgkmcnt(14)
	ds_write_b16 v180, v65 offset:5166
	s_nop 0
	s_waitcnt lgkmcnt(13)
	ds_write_b16 v180, v78 offset:10246
	v_perm_b32 v36, v82, v84, s35
	v_perm_b32 v37, v78, v80, s35
	ds_write_b64 v180, v[36:37] offset:10280

.LBB0_935:
	s_or_b64 exec, exec, s[28:29]
	s_waitcnt lgkmcnt(0)
	s_barrier
	ds_read_b128 v[36:39], v216 offset:18432
	ds_read_b128 v[40:43], v216 offset:9216
	ds_read_b128 v[48:51], v216 offset:18496
	s_waitcnt lgkmcnt(1)
	v_mfma_f32_16x16x32_f16 v[52:55], v[40:43], v[36:39], 0
	ds_read_b128 v[56:59], v216 offset:9280
	ds_read_b128 v[60:63], v216 offset:23040
	ds_read_b128 v[64:67], v216 offset:13824
	ds_read_b128 v[68:71], v216 offset:13888
	ds_read_b128 v[72:75], v216 offset:23104
	v_add_u32_e32 v80, 0x1000, v222
	s_waitcnt lgkmcnt(4)
	v_mfma_f32_16x16x32_f16 v[52:55], v[56:59], v[48:51], v[52:55]
	s_nop 0
	s_nop 0
	s_nop 0
	v_mfma_f32_16x16x32_f16 v[44:47], v[36:39], v[40:43], 0
	s_nop 3
	v_cvt_f16_f32_e32 v0, v52
	v_cvt_f16_f32_e32 v1, v54
	v_cvt_f16_f32_e32 v2, v55
	v_mfma_f32_16x16x32_f16 v[44:47], v[48:51], v[56:59], v[44:47]
	v_cndmask_b32_e64 v79, 0, v0, s[12:13]
	v_cvt_f16_f32_e32 v0, v53
	v_cndmask_b32_e64 v54, 0, v1, s[18:19]
	s_waitcnt lgkmcnt(3)
	v_mfma_f32_16x16x32_f16 v[40:43], v[60:63], v[40:43], 0
	v_cndmask_b32_e64 v55, 0, v2, s[22:23]
	s_nop 1
	v_cndmask_b32_e64 v76, 0, v44, s[10:11]
	v_cndmask_b32_e64 v77, 0, v45, s[14:15]
	s_waitcnt lgkmcnt(2)
	v_mfma_f32_16x16x32_f16 v[36:39], v[36:39], v[64:67], 0
	v_cndmask_b32_e64 v52, 0, v46, s[16:17]
	v_cndmask_b32_e64 v78, 0, v47, s[20:21]
	v_cndmask_b32_e64 v53, v0, 0, s[10:11]
	v_mfma_f32_16x16x32_f16 v[44:47], v[60:63], v[64:67], 0
	v_cvt_pk_f16_f32 v1, v52, v78
	v_cvt_pk_f16_f32 v0, v76, v77
	s_nop 0
	s_waitcnt lgkmcnt(0)
	v_mfma_f32_16x16x32_f16 v[60:63], v[72:75], v[56:59], v[40:43]
	v_add_f32_e32 v56, v217, v76
	v_add_f32_e32 v57, v219, v77
	v_add_f32_e32 v58, v220, v52
	v_mfma_f32_16x16x32_f16 v[40:43], v[48:51], v[68:71], v[36:39]
	v_add_f32_e32 v59, v221, v78
	v_cvt_pk_f16_f32 v67, v26, v27
	v_cvt_pk_f16_f32 v66, v24, v25
	v_pack_b32_f16 v37, v54, v55
	v_pack_b32_f16 v36, v79, v53
	s_nop 0
	s_nop 0
	v_mfma_f32_16x16x32_f16 v[52:55], v[72:75], v[68:71], v[44:47]
	ds_read2_b64 v[68:71], v222 offset0:8 offset1:12
	v_cvt_pk_f16_f32 v65, v30, v31
	v_cvt_pk_f16_f32 v64, v28, v29
	v_mfma_f32_16x16x16_f16 v[48:51], v[0:1], v[36:37], 0
	v_cvt_pk_f16_f32 v45, v58, v59
	v_cvt_pk_f16_f32 v44, v56, v57
	s_nop 0
	v_mfma_f32_16x16x16_f16 v[36:39], v[36:37], v[0:1], 0
	s_nop 0
	s_nop 2
	v_cvt_pk_f16_f32 v1, v50, v51
	v_cvt_pk_f16_f32 v0, v48, v49
	s_nop 0
	s_nop 0
	v_cvt_pk_f16_f32 v49, v38, v39
	v_cvt_pk_f16_f32 v48, v36, v37
	v_mfma_f32_16x16x16_f16 v[44:47], v[0:1], v[44:45], v[56:59]
	s_nop 0
	s_nop 0
	s_nop 0
	v_mfma_f32_16x16x16_f16 v[36:39], v[48:49], v[0:1], 0
	v_cvt_pk_f16_f32 v59, v34, v35
	v_cvt_pk_f16_f32 v58, v32, v33
	v_cvt_pk_f16_f32 v57, v22, v23
	v_mfma_f32_16x16x16_f16 v[48:51], v[0:1], v[48:49], 0
	v_cvt_pk_f16_f32 v56, v20, v21
	s_nop 2
	v_cvt_pk_f16_f32 v1, v38, v39
	v_cvt_pk_f16_f32 v0, v36, v37
	v_cvt_pk_f16_f32 v37, v46, v47
	v_cvt_pk_f16_f32 v36, v44, v45
	s_nop 0
	s_nop 0
	v_cvt_f16_f32_e32 v52, v52
	s_add_i32 s27, s26, 1
	v_mfma_f32_16x16x16_f16 v[44:47], v[0:1], v[36:37], v[44:47]
	v_cvt_pk_f16_f32 v37, v50, v51
	v_cvt_pk_f16_f32 v36, v48, v49
	s_nop 0
	s_nop 0
	v_mfma_f32_16x16x16_f16 v[36:39], v[36:37], v[0:1], 0
	s_nop 2
	v_cvt_pk_f16_f32 v1, v46, v47
	v_cvt_pk_f16_f32 v0, v44, v45
	s_nop 2
	v_cvt_pk_f16_f32 v49, v38, v39
	v_cvt_pk_f16_f32 v48, v36, v37
	ds_read2_b64 v[36:39], v222 offset1:4
	s_waitcnt lgkmcnt(0)
	v_mfma_f32_16x16x32_f16 v[36:39], v[36:39], v[56:59], 0
	v_mfma_f32_16x16x16_f16 v[44:47], v[48:49], v[0:1], v[44:47]
	v_cvt_f16_f32_e32 v0, v60
	v_cvt_f16_f32_e32 v1, v61
	v_cvt_f16_f32_e32 v2, v62
	v_cvt_f16_f32_e32 v48, v63
	v_mfma_f32_16x16x32_f16 v[76:79], v[68:71], v[64:67], v[36:39]
	ds_read2_b64 v[72:75], v80 offset0:64 offset1:68
	ds_read2_b64 v[68:71], v80 offset0:72 offset1:76
	s_nop 0
	ds_read2st64_b64 v[36:39], v223 offset0:20 offset1:25
	v_cndmask_b32_e64 v0, 0, v0, s[10:11]
	v_cndmask_b32_e64 v49, 0, v1, s[14:15]
	v_cndmask_b32_e64 v1, 0, v2, s[16:17]
	v_cndmask_b32_e64 v2, 0, v48, s[20:21]
	v_pack_b32_f16 v1, v1, v2
	v_pack_b32_f16 v0, v0, v49
	s_nop 0
	s_waitcnt lgkmcnt(0)
	v_mov_b32_e32 v60, v36
	v_mov_b32_e32 v61, v37
	s_nop 0
	s_nop 0
	v_cvt_f16_f32_e32 v36, v40
	v_cvt_f16_f32_e32 v40, v42
	v_mfma_f32_16x16x16_f16 v[48:51], v[0:1], v[60:61], v[76:79]
	v_cvt_pk_f16_f32 v1, v46, v47
	v_cvt_pk_f16_f32 v0, v44, v45
	v_cvt_f16_f32_e32 v37, v41
	s_nop 0
	s_nop 0
	s_nop 2
	v_cvt_pk_f16_f32 v77, v50, v51
	v_cvt_pk_f16_f32 v76, v48, v49
	v_cndmask_b32_e64 v88, v40, 0, s[18:19]
	v_mfma_f32_16x16x32_f16 v[56:59], v[72:75], v[56:59], 0
	v_cndmask_b32_e64 v36, v36, 0, s[12:13]
	v_cndmask_b32_e64 v37, 0, v37, s[10:11]
	s_nop 0
	v_mfma_f32_16x16x16_f16 v[44:47], v[0:1], v[76:77], 0
	s_nop 0
	v_mfma_f32_16x16x32_f16 v[56:59], v[68:71], v[64:67], v[56:59]
	s_nop 5
	v_cvt_pk_f16_f32 v1, v46, v47
	v_cvt_pk_f16_f32 v0, v44, v45
	ds_read2_b64 v[44:47], v240 offset1:80
	ds_read_b128 v[48:51], v182
	ds_read_b64 v[76:77], v224 offset:5120
	s_waitcnt lgkmcnt(2)
	v_mov_b32_e32 v80, v44
	v_mov_b32_e32 v81, v45
	s_waitcnt lgkmcnt(1)
	v_pk_mul_f32 v[50:51], v[22:23], v[50:51]
	v_pk_mul_f32 v[48:49], v[20:21], v[48:49]
	s_nop 1
	v_mfma_f32_16x16x16_f16 v[48:51], v[80:81], v[0:1], v[48:51]
	v_cvt_f16_f32_e32 v80, v43
	v_cndmask_b32_e64 v89, v80, 0, s[22:23]
	s_waitcnt lgkmcnt(0)
	v_mfma_f32_16x16x16_f16 v[40:43], v[76:77], v[60:61], v[48:51]
	s_nop 3
	ds_read_b128 v[48:51], v182 offset:64
	ds_read_b64 v[44:45], v225 offset:5120
	v_mov_b32_e32 v76, v46
	v_mov_b32_e32 v77, v47
	s_nop 0
	s_waitcnt lgkmcnt(1)
	v_pk_mul_f32 v[50:51], v[34:35], v[50:51]
	v_pk_mul_f32 v[48:49], v[32:33], v[48:49]
	s_nop 0
	s_nop 0
	v_mfma_f32_16x16x16_f16 v[48:51], v[76:77], v[0:1], v[48:51]
	ds_read2_b64 v[76:79], v240 offset0:160 offset1:240
	s_waitcnt lgkmcnt(0)
	v_mov_b32_e32 v84, v76
	v_mfma_f32_16x16x16_f16 v[48:51], v[44:45], v[60:61], v[48:51]
	ds_read_b128 v[44:47], v182 offset:128
	ds_read_b64 v[80:81], v226 offset:5120
	v_mov_b32_e32 v85, v77
	v_pack_b32_f16 v77, v88, v89
	v_mov_b32_e32 v88, v78
	s_waitcnt lgkmcnt(1)
	v_pk_mul_f32 v[46:47], v[30:31], v[46:47]
	v_pk_mul_f32 v[44:45], v[28:29], v[44:45]
	v_mov_b32_e32 v89, v79
	v_pack_b32_f16 v76, v36, v37
	v_mfma_f32_16x16x16_f16 v[44:47], v[84:85], v[0:1], v[44:47]
	v_cndmask_b32_e64 v36, v52, 0, s[12:13]
	v_cvt_f16_f32_e32 v37, v53
	v_cndmask_b32_e64 v37, 0, v37, s[10:11]
	s_waitcnt lgkmcnt(0)
	v_mfma_f32_16x16x16_f16 v[44:47], v[80:81], v[60:61], v[44:47]
	ds_read_b128 v[80:83], v182 offset:192
	ds_read_b64 v[84:85], v227 offset:5120
	v_pack_b32_f16 v72, v36, v37
	ds_read_b128 v[68:71], v228 offset:9216
	ds_read_b128 v[94:97], v228 offset:9280
	s_waitcnt lgkmcnt(3)
	v_pk_mul_f32 v[82:83], v[26:27], v[82:83]
	v_pk_mul_f32 v[80:81], v[24:25], v[80:81]
	ds_read_b128 v[64:67], v228 offset:18432
	ds_read_b128 v[98:101], v228 offset:23104
	v_mfma_f32_16x16x16_f16 v[78:81], v[88:89], v[0:1], v[80:83]
	ds_read_b128 v[90:93], v228 offset:18496
	s_nop 1
	v_cvt_f16_f32_e32 v82, v54
	v_cvt_f16_f32_e32 v83, v55
	s_waitcnt lgkmcnt(5)
	v_mfma_f32_16x16x16_f16 v[52:55], v[84:85], v[60:61], v[78:81]
	ds_read_b128 v[86:89], v228 offset:13824
	s_nop 1
	v_cndmask_b32_e64 v78, v82, 0, s[18:19]
	v_cndmask_b32_e64 v79, v83, 0, s[22:23]
	v_pack_b32_f16 v73, v78, v79
	s_nop 0
	s_nop 0
	v_add_u32_e32 v80, s77, v122
	v_add_u32_e32 v81, s76, v237
	v_mfma_f32_16x16x16_f16 v[56:59], v[76:77], v[0:1], v[56:59]
	ds_read_b128 v[76:79], v228 offset:23040
	v_subrev_u32_e32 v102, 64, v80
	v_add_u32_e32 v0, 0xff, v81
	v_mfma_f32_16x16x16_f16 v[58:61], v[72:73], v[60:61], v[56:59]
	v_cndmask_b32_e64 v0, v0, v102, s[2:3]
	v_add_u32_e32 v0, v0, v175
	v_mad_i64_i32 v[0:1], s[28:29], v0, s88, v[126:127]
	s_waitcnt lgkmcnt(4)
	v_mfma_f32_16x16x32_f16 v[82:85], v[68:71], v[64:67], 0
	s_nop 2
	v_cvt_f16_f32_e32 v2, v58
	v_cvt_f16_f32_e32 v60, v60
	global_store_short v[0:1], v2, off
	v_subrev_u32_e32 v0, 63, v80
	v_xad_u32 v1, v102, -2, v168
	v_cvt_f16_f32_e32 v2, v59
	ds_read_b128 v[56:59], v228 offset:13888
	v_mfma_f32_16x16x32_f16 v[72:75], v[64:67], v[68:71], 0
	v_cndmask_b32_e64 v0, v1, v0, s[2:3]
	v_add_u32_e32 v0, v0, v175
	v_mad_i64_i32 v[0:1], s[28:29], v0, s88, v[126:127]
	s_waitcnt lgkmcnt(2)
	v_mfma_f32_16x16x32_f16 v[62:65], v[64:67], v[86:89], 0
	global_store_short v[0:1], v2, off
	v_subrev_u32_e32 v0, 62, v80
	v_xad_u32 v1, v102, -3, v168
	v_mfma_f32_16x16x32_f16 v[82:85], v[94:97], v[90:93], v[82:85]
	v_cndmask_b32_e64 v36, v1, v0, s[2:3]
	v_add_u32_e32 v36, v36, v175
	s_waitcnt lgkmcnt(1)
	v_mfma_f32_16x16x32_f16 v[68:71], v[76:79], v[68:71], 0
	v_mfma_f32_16x16x32_f16 v[86:89], v[76:79], v[86:89], 0
	s_nop 2
	v_cvt_f16_f32_e32 v1, v82
	v_cvt_f16_f32_e32 v2, v83
	v_cvt_f16_f32_e32 v66, v85
	v_mfma_f32_16x16x32_f16 v[72:75], v[90:93], v[94:97], v[72:75]
	s_nop 0
	v_cndmask_b32_e64 v66, 0, v66, s[22:23]
	s_waitcnt lgkmcnt(0)
	v_mfma_f32_16x16x32_f16 v[76:79], v[90:93], v[56:59], v[62:65]
	s_nop 0
	s_nop 2
	v_cndmask_b32_e64 v0, 0, v72, s[10:11]
	v_cndmask_b32_e64 v37, 0, v73, s[14:15]
	v_cvt_f16_f32_e32 v63, v84
	v_mfma_f32_16x16x32_f16 v[94:97], v[98:101], v[94:97], v[68:71]
	v_cndmask_b32_e64 v64, 0, v74, s[16:17]
	v_cndmask_b32_e64 v65, 0, v75, s[20:21]
	v_cndmask_b32_e64 v63, 0, v63, s[18:19]
	v_cndmask_b32_e64 v68, 0, v1, s[12:13]
	v_cndmask_b32_e64 v69, v2, 0, s[10:11]
	v_add_f32_e32 v62, v217, v0
	v_cvt_pk_f16_f32 v1, v64, v65
	v_cvt_pk_f16_f32 v0, v0, v37
	s_nop 0
	v_pack_b32_f16 v67, v63, v66
	v_pack_b32_f16 v66, v68, v69
	s_nop 0
	s_nop 0
	v_add_f32_e32 v63, v219, v37
	v_add_f32_e32 v64, v220, v64
	v_mfma_f32_16x16x16_f16 v[70:73], v[0:1], v[66:67], 0
	v_add_f32_e32 v65, v221, v65
	v_cvt_pk_f16_f32 v83, v64, v65
	v_cvt_pk_f16_f32 v82, v62, v63
	v_mfma_f32_16x16x16_f16 v[66:69], v[66:67], v[0:1], 0
	s_nop 0
	s_nop 2
	v_cvt_pk_f16_f32 v0, v70, v71
	s_nop 0
	s_nop 0
	v_cvt_pk_f16_f32 v1, v72, v73
	v_cvt_pk_f16_f32 v69, v68, v69
	v_cvt_pk_f16_f32 v68, v66, v67
	v_mfma_f32_16x16x16_f16 v[62:65], v[0:1], v[82:83], v[62:65]
	v_mad_i64_i32 v[36:37], s[28:29], v36, s88, v[126:127]
	global_store_short v[36:37], v60, off
	v_mfma_f32_16x16x16_f16 v[72:75], v[68:69], v[0:1], 0
	v_cvt_f16_f32_e32 v82, v61
	v_subrev_u32_e32 v36, 61, v80
	v_xad_u32 v37, v102, -4, v168
	v_mfma_f32_16x16x16_f16 v[66:69], v[0:1], v[68:69], 0
	s_nop 0
	v_cvt_pk_f16_f32 v71, v64, v65
	s_nop 1
	v_cvt_pk_f16_f32 v1, v74, v75
	v_cvt_pk_f16_f32 v0, v72, v73
	v_mfma_f32_16x16x32_f16 v[56:59], v[98:101], v[56:59], v[86:89]
	v_cvt_pk_f16_f32 v70, v62, v63
	s_nop 0
	s_nop 0
	v_cvt_pk_f16_f32 v85, v68, v69
	v_cvt_pk_f16_f32 v84, v66, v67
	s_nop 0
	s_nop 0
	v_mfma_f32_16x16x16_f16 v[88:91], v[0:1], v[70:71], v[62:65]
	ds_read2_b64 v[68:71], v229 offset1:4
	ds_read2_b64 v[72:75], v229 offset0:8 offset1:12
	v_cndmask_b32_e64 v36, v37, v36, s[2:3]
	v_mfma_f32_16x16x16_f16 v[60:63], v[84:85], v[0:1], 0
	v_add_u32_e32 v83, v36, v175
	s_nop 2
	v_cvt_pk_f16_f32 v1, v90, v91
	v_cvt_pk_f16_f32 v0, v88, v89
	v_cvt_pk_f16_f32 v67, v54, v55
	v_cvt_pk_f16_f32 v66, v52, v53
	v_cvt_pk_f16_f32 v85, v62, v63
	v_cvt_pk_f16_f32 v84, v60, v61
	v_cvt_pk_f16_f32 v63, v50, v51
	v_cvt_pk_f16_f32 v62, v48, v49
	v_cvt_pk_f16_f32 v61, v42, v43
	v_cvt_pk_f16_f32 v60, v40, v41
	v_cvt_pk_f16_f32 v65, v46, v47
	v_cvt_pk_f16_f32 v64, v44, v45
	s_waitcnt lgkmcnt(1)
	v_mfma_f32_16x16x32_f16 v[68:71], v[68:71], v[60:63], 0
	v_add_u32_e32 v36, 0x1000, v229
	s_nop 0
	v_cvt_f16_f32_e32 v76, v76
	s_waitcnt lgkmcnt(0)
	v_mfma_f32_16x16x32_f16 v[98:101], v[72:75], v[64:67], v[68:71]
	ds_read2_b64 v[72:75], v36 offset0:64 offset1:68
	s_nop 1
	ds_read2_b64 v[68:71], v36 offset0:72 offset1:76
	v_cvt_f16_f32_e32 v36, v97
	v_cvt_f16_f32_e32 v97, v77
	v_mfma_f32_16x16x16_f16 v[84:87], v[84:85], v[0:1], v[88:91]
	v_cvt_f16_f32_e32 v0, v94
	v_cvt_f16_f32_e32 v1, v95
	v_cvt_f16_f32_e32 v2, v96
	v_cndmask_b32_e64 v96, v76, 0, s[12:13]
	v_cndmask_b32_e64 v0, 0, v0, s[10:11]
	v_cndmask_b32_e64 v37, 0, v1, s[14:15]
	v_cndmask_b32_e64 v1, 0, v2, s[16:17]
	v_cndmask_b32_e64 v2, 0, v36, s[20:21]
	v_pack_b32_f16 v1, v1, v2
	v_pack_b32_f16 v0, v0, v37
	s_nop 0
	v_mov_b32_e32 v36, v38
	v_mov_b32_e32 v37, v39
	s_nop 0
	s_nop 0
	v_mov_b32_e32 v94, v3
	v_mov_b32_e32 v95, v3
	v_mfma_f32_16x16x16_f16 v[88:91], v[0:1], v[36:37], v[98:101]
	v_cvt_pk_f16_f32 v1, v86, v87
	v_cvt_pk_f16_f32 v0, v84, v85
	v_cvt_f16_f32_e32 v56, v56
	v_cvt_f16_f32_e32 v98, v78
	v_cvt_f16_f32_e32 v99, v79
	s_nop 2
	v_cvt_pk_f16_f32 v91, v90, v91
	v_cvt_pk_f16_f32 v90, v88, v89
	v_cndmask_b32_e64 v97, 0, v97, s[10:11]
	v_cndmask_b32_e64 v98, v98, 0, s[18:19]
	v_mfma_f32_16x16x16_f16 v[84:87], v[0:1], v[90:91], 0
	v_add_u32_e32 v2, 0x800, v240
	v_mov_b32_e32 v90, v3
	v_mov_b32_e32 v91, v3
	v_cndmask_b32_e64 v99, v99, 0, s[22:23]
	s_nop 3
	v_cvt_pk_f16_f32 v1, v86, v87
	v_cvt_pk_f16_f32 v0, v84, v85
	ds_read2_b64 v[84:87], v2 offset0:64 offset1:144
	ds_read_b128 v[76:79], v182 offset:256
	ds_read_b64 v[88:89], v230 offset:5120
	s_nop 0
	s_waitcnt lgkmcnt(2)
	v_mov_b32_e32 v92, v84
	v_mov_b32_e32 v93, v85
	s_waitcnt lgkmcnt(1)
	v_pk_mul_f32 v[42:43], v[42:43], v[78:79]
	v_pk_mul_f32 v[40:41], v[40:41], v[76:77]
	ds_read_b128 v[76:79], v182 offset:320
	ds_read_b64 v[84:85], v231 offset:5120
	v_mfma_f32_16x16x16_f16 v[40:43], v[92:93], v[0:1], v[40:43]
	s_waitcnt lgkmcnt(1)
	v_pk_mul_f32 v[48:49], v[48:49], v[76:77]
	v_add_u32_e32 v76, 0xc00, v240
	v_mfma_f32_16x16x16_f16 v[40:43], v[88:89], v[36:37], v[40:43]
	v_mov_b32_e32 v88, v86
	v_mov_b32_e32 v89, v87
	v_pk_mul_f32 v[50:51], v[50:51], v[78:79]
	s_nop 0
	s_nop 0
	ds_read2_b64 v[76:79], v76 offset0:96 offset1:176
	v_mfma_f32_16x16x16_f16 v[48:51], v[88:89], v[0:1], v[48:51]
	s_waitcnt lgkmcnt(0)
	v_mov_b32_e32 v92, v76
	v_mfma_f32_16x16x16_f16 v[48:51], v[84:85], v[36:37], v[48:51]
	ds_read_b128 v[84:87], v182 offset:384
	ds_read_b64 v[88:89], v232 offset:5120
	v_mov_b32_e32 v93, v77
	v_pack_b32_f16 v76, v96, v97
	v_cndmask_b32_e64 v96, v56, 0, s[12:13]
	s_waitcnt lgkmcnt(1)
	v_pk_mul_f32 v[46:47], v[46:47], v[86:87]
	v_pk_mul_f32 v[44:45], v[44:45], v[84:85]
	v_cvt_f16_f32_e32 v56, v57
	v_cvt_f16_f32_e32 v57, v58
	v_mfma_f32_16x16x16_f16 v[44:47], v[92:93], v[0:1], v[44:47]
	v_cvt_f16_f32_e32 v58, v59
	v_mov_b32_e32 v92, v78
	v_mov_b32_e32 v93, v79
	s_waitcnt lgkmcnt(0)
	v_mfma_f32_16x16x16_f16 v[44:47], v[88:89], v[36:37], v[44:47]
	ds_read_b128 v[84:87], v182 offset:448
	ds_read_b64 v[88:89], v233 offset:5120
	v_cndmask_b32_e64 v78, v57, 0, s[18:19]
	v_cndmask_b32_e64 v79, v58, 0, s[22:23]
	v_pack_b32_f16 v77, v98, v99
	s_waitcnt lgkmcnt(1)
	v_pk_mul_f32 v[52:53], v[52:53], v[84:85]
	v_cndmask_b32_e64 v84, 0, v56, s[10:11]
	v_mfma_f32_16x16x32_f16 v[56:59], v[72:75], v[60:63], 0
	v_pack_b32_f16 v61, v78, v79
	v_mov_b32_e32 v78, v3
	v_mov_b32_e32 v79, v3
	v_mfma_f32_16x16x32_f16 v[56:59], v[68:71], v[64:67], v[56:59]
	v_mul_f32_e64 v54, v54, v86
	v_mul_f32_e64 v55, v55, v87
	v_pack_b32_f16 v60, v96, v84
	v_mov_b32_e32 v62, v3
	v_mov_b32_e32 v63, v3
	v_mfma_f32_16x16x16_f16 v[52:55], v[92:93], v[0:1], v[52:55]
	v_mfma_f32_16x16x16_f16 v[56:59], v[76:77], v[0:1], v[56:59]
	v_mad_i64_i32 v[0:1], s[28:29], v83, s88, v[126:127]
	global_store_short v[0:1], v82, off
	s_waitcnt lgkmcnt(0)
	v_mfma_f32_16x16x16_f16 v[52:55], v[88:89], v[36:37], v[52:55]
	v_subrev_u32_e32 v0, 48, v80
	v_add_u32_e32 v1, 0xef, v81
	v_cndmask_b32_e64 v0, v1, v0, s[2:3]
	v_mfma_f32_16x16x16_f16 v[36:39], v[60:61], v[36:37], v[56:59]
	v_add_u32_e32 v0, v0, v175
	v_mad_i64_i32 v[0:1], s[28:29], v0, s88, v[126:127]
	s_nop 5
	v_cvt_f16_f32_e32 v2, v36
	global_store_short v[0:1], v2, off
	v_subrev_u32_e32 v0, 47, v80
	v_add_u32_e32 v1, 0xee, v81
	v_cvt_f16_f32_e32 v2, v37
	v_cndmask_b32_e64 v0, v1, v0, s[2:3]
	v_add_u32_e32 v0, v0, v175
	v_mad_i64_i32 v[0:1], s[28:29], v0, s88, v[126:127]
	global_store_short v[0:1], v2, off
	v_subrev_u32_e32 v0, 46, v80
	v_add_u32_e32 v1, 0xed, v81
	v_cvt_f16_f32_e32 v2, v38
	v_cndmask_b32_e64 v0, v1, v0, s[2:3]
	v_add_u32_e32 v0, v0, v175
	v_mad_i64_i32 v[0:1], s[28:29], v0, s88, v[126:127]
	global_store_short v[0:1], v2, off
	v_subrev_u32_e32 v0, 45, v80
	v_add_u32_e32 v1, 0xec, v81
	v_cndmask_b32_e64 v0, v1, v0, s[2:3]
	v_cvt_f16_f32_e32 v2, v39
	v_add_u32_e32 v0, v0, v175
	v_mad_i64_i32 v[0:1], s[28:29], v0, s88, v[126:127]
	s_mov_b64 s[28:29], 0
	global_store_short v[0:1], v2, off

.LBB0_942:
	v_cmp_lt_i32_e32 vcc, 2, v178
	s_and_saveexec_b64 s[30:31], vcc
	s_xor_b64 s[68:69], exec, s[30:31]
	s_cbranch_execz .LBB0_944
	v_lshl_add_u32 v251, v208, 1, v2
	v_lshl_add_u32 v250, v210, 1, v2
	ds_read2st64_b32 v[36:37], v251 offset0:64 offset1:80
	ds_read2st64_b32 v[46:47], v251 offset0:96 offset1:112
	ds_read_b32 v60, v251 offset:32768
	ds_read2st64_b32 v[128:129], v250 offset0:64 offset1:80
	ds_read2st64_b32 v[130:131], v250 offset0:96 offset1:112
	ds_read_b32 v61, v250 offset:32768
	v_lshl_add_u32 v48, v208, 1, v2
	s_nop 0
	s_nop 0
	v_rcp_f32_e32 v44, v62
	v_rcp_f32_e32 v45, v63
	v_lshl_add_u32 v251, v212, 1, v2
	ds_read2st64_b32 v[132:133], v251 offset0:64 offset1:80
	s_waitcnt lgkmcnt(5)
	v_cvt_f32_f16_e32 v58, v47
	v_cvt_f32_f16_e32 v50, v37
	v_cvt_f32_f16_sdwa v51, v37 dst_sel:DWORD dst_unused:UNUSED_PAD src0_sel:WORD_1
	ds_read2st64_b32 v[134:135], v251 offset0:96 offset1:112
	v_cvt_f32_f16_sdwa v59, v47 dst_sel:DWORD dst_unused:UNUSED_PAD src0_sel:WORD_1
	v_cvt_f32_f16_e32 v48, v36
	v_cvt_f32_f16_e32 v54, v46
	v_cvt_f32_f16_sdwa v55, v46 dst_sel:DWORD dst_unused:UNUSED_PAD src0_sel:WORD_1
	v_cvt_f32_f16_sdwa v49, v36 dst_sel:DWORD dst_unused:UNUSED_PAD src0_sel:WORD_1
	v_pk_mul_f32 v[36:37], v[42:43], v[50:51]
	v_pk_mul_f32 v[42:43], v[62:63], v[58:59]
	v_pk_mul_f32 v[46:47], v[44:45], v[54:55]
	v_pk_mul_f32 v[44:45], v[44:45], v[48:49]
	v_pk_mul_f32 v[48:49], v[40:41], v[36:37]
	v_pk_mul_f32 v[50:51], v[40:41], v[42:43]
	v_cvt_pk_f16_f32 v36, v36, v37
	v_cvt_pk_f16_f32 v37, v42, v43
	v_pk_mul_f32 v[54:55], v[38:39], v[46:47]
	v_pk_mul_f32 v[58:59], v[38:39], v[44:45]
	ds_write2st64_b32 v209, v36, v37 offset1:18
	v_cvt_pk_f16_f32 v36, v48, v49
	v_cvt_pk_f16_f32 v37, v50, v51
	v_pk_mul_f32 v[46:47], v[0:1], v[46:47]
	ds_write2st64_b32 v209, v36, v37 offset0:36 offset1:54
	v_cvt_pk_f16_f32 v36, v54, v55
	v_cvt_pk_f16_f32 v37, v58, v59
	ds_write2st64_b32 v209, v36, v37 offset0:72 offset1:90
	v_cvt_f16_f32_e32 v36, v46
	v_pk_mul_f32 v[44:45], v[0:1], v[44:45]
	v_cvt_f16_f32_e32 v37, v47
	v_cvt_f16_f32_e32 v42, v44
	v_cvt_f16_f32_e32 v43, v45
	ds_write_b16 v180, v36 offset:24
	ds_write_b16 v180, v37 offset:64
	ds_write_b16 v180, v42 offset:5144
	ds_write_b16 v180, v43 offset:5184
	s_waitcnt lgkmcnt(12)
	ds_write_b16 v180, v60 offset:10264
	v_lshl_add_u32 v46, v210, 1, v2
	v_rcp_f32_e32 v42, v56
	v_rcp_f32_e32 v43, v57
	s_waitcnt lgkmcnt(12)
	v_cvt_f32_f16_e32 v48, v129
	v_cvt_f32_f16_sdwa v49, v129 dst_sel:DWORD dst_unused:UNUSED_PAD src0_sel:WORD_1
	s_waitcnt lgkmcnt(11)
	v_cvt_f32_f16_e32 v54, v131
	v_cvt_f32_f16_sdwa v55, v131 dst_sel:DWORD dst_unused:UNUSED_PAD src0_sel:WORD_1
	v_cvt_f32_f16_e32 v46, v128
	v_cvt_f32_f16_e32 v50, v130
	v_cvt_f32_f16_sdwa v51, v130 dst_sel:DWORD dst_unused:UNUSED_PAD src0_sel:WORD_1
	v_cvt_f32_f16_sdwa v47, v128 dst_sel:DWORD dst_unused:UNUSED_PAD src0_sel:WORD_1
	v_pk_mul_f32 v[36:37], v[62:63], v[48:49]
	v_pk_mul_f32 v[44:45], v[56:57], v[54:55]
	v_pk_mul_f32 v[48:49], v[42:43], v[50:51]
	v_pk_mul_f32 v[42:43], v[42:43], v[46:47]
	v_pk_mul_f32 v[46:47], v[40:41], v[36:37]
	v_pk_mul_f32 v[50:51], v[40:41], v[44:45]
	v_cvt_pk_f16_f32 v36, v36, v37
	v_cvt_pk_f16_f32 v37, v44, v45
	v_pk_mul_f32 v[54:55], v[38:39], v[48:49]
	v_pk_mul_f32 v[58:59], v[38:39], v[42:43]
	ds_write2st64_b32 v211, v36, v37 offset1:18
	v_cvt_pk_f16_f32 v36, v46, v47
	v_cvt_pk_f16_f32 v37, v50, v51
	v_pk_mul_f32 v[48:49], v[0:1], v[48:49]
	ds_write2st64_b32 v211, v36, v37 offset0:36 offset1:54
	v_cvt_pk_f16_f32 v36, v54, v55
	v_cvt_pk_f16_f32 v37, v58, v59
	v_lshl_add_u32 v250, v214, 1, v2
	ds_read_b32 v58, v251 offset:32768
	ds_read2st64_b32 v[136:137], v250 offset0:64 offset1:80
	s_waitcnt lgkmcnt(14)
	ds_read2st64_b32 v[138:139], v250 offset0:96 offset1:112
	s_waitcnt lgkmcnt(14)
	ds_write2st64_b32 v211, v36, v37 offset0:72 offset1:90
	v_cvt_f16_f32_e32 v36, v48
	v_pk_mul_f32 v[42:43], v[0:1], v[42:43]
	v_cvt_f16_f32_e32 v37, v49
	v_cvt_f16_f32_e32 v42, v42
	v_cvt_f16_f32_e32 v43, v43
	s_waitcnt lgkmcnt(14)
	ds_write_b16 v180, v36 offset:26
	s_waitcnt lgkmcnt(14)
	ds_write_b16 v180, v37 offset:66
	s_waitcnt lgkmcnt(14)
	ds_write_b16 v180, v42 offset:5146
	s_waitcnt lgkmcnt(14)
	ds_write_b16 v180, v43 offset:5186
	s_waitcnt lgkmcnt(14)
	ds_write_b16 v180, v61 offset:10266
	v_lshl_add_u32 v46, v212, 1, v2
	v_rcp_f32_e32 v42, v52
	v_rcp_f32_e32 v43, v53
	v_lshl_add_u32 v2, v214, 1, v2
	v_cvt_f32_f16_e32 v48, v133
	v_cvt_f32_f16_sdwa v49, v133 dst_sel:DWORD dst_unused:UNUSED_PAD src0_sel:WORD_1
	v_cvt_f32_f16_e32 v54, v135
	v_cvt_f32_f16_sdwa v55, v135 dst_sel:DWORD dst_unused:UNUSED_PAD src0_sel:WORD_1
	v_cvt_f32_f16_e32 v46, v132
	v_cvt_f32_f16_e32 v50, v134
	v_cvt_f32_f16_sdwa v51, v134 dst_sel:DWORD dst_unused:UNUSED_PAD src0_sel:WORD_1
	v_cvt_f32_f16_sdwa v47, v132 dst_sel:DWORD dst_unused:UNUSED_PAD src0_sel:WORD_1
	v_pk_mul_f32 v[36:37], v[56:57], v[48:49]
	v_pk_mul_f32 v[44:45], v[52:53], v[54:55]
	v_pk_mul_f32 v[48:49], v[42:43], v[50:51]
	v_pk_mul_f32 v[42:43], v[42:43], v[46:47]
	v_pk_mul_f32 v[46:47], v[40:41], v[36:37]
	v_pk_mul_f32 v[50:51], v[40:41], v[44:45]
	v_cvt_pk_f16_f32 v36, v36, v37
	v_cvt_pk_f16_f32 v37, v44, v45
	v_pk_mul_f32 v[54:55], v[38:39], v[48:49]
	v_pk_mul_f32 v[56:57], v[38:39], v[42:43]
	s_waitcnt lgkmcnt(14)
	ds_write2st64_b32 v213, v36, v37 offset1:18
	v_cvt_pk_f16_f32 v36, v46, v47
	v_cvt_pk_f16_f32 v37, v50, v51
	v_pk_mul_f32 v[48:49], v[0:1], v[48:49]
	s_waitcnt lgkmcnt(14)
	ds_write2st64_b32 v213, v36, v37 offset0:36 offset1:54
	v_cvt_pk_f16_f32 v36, v54, v55
	v_cvt_pk_f16_f32 v37, v56, v57
	s_waitcnt lgkmcnt(14)
	ds_write2st64_b32 v213, v36, v37 offset0:72 offset1:90
	v_cvt_f16_f32_e32 v36, v48
	v_pk_mul_f32 v[42:43], v[0:1], v[42:43]
	v_cvt_f16_f32_e32 v37, v49
	v_cvt_f16_f32_e32 v42, v42
	v_cvt_f16_f32_e32 v43, v43
	s_waitcnt lgkmcnt(14)
	ds_write_b16 v180, v36 offset:28
	s_waitcnt lgkmcnt(14)
	ds_write_b16 v180, v37 offset:68
	s_waitcnt lgkmcnt(14)
	ds_write_b16 v180, v42 offset:5148
	s_waitcnt lgkmcnt(14)
	ds_write_b16 v180, v43 offset:5188
	s_waitcnt lgkmcnt(14)
	ds_write_b16 v180, v58 offset:10268
	s_waitcnt lgkmcnt(14)
	ds_read_b32 v2, v250 offset:32768
	v_rcp_f32_e32 v42, v0
	v_rcp_f32_e32 v43, v1
	v_cvt_f32_f16_e32 v48, v137
	v_cvt_f32_f16_sdwa v49, v137 dst_sel:DWORD dst_unused:UNUSED_PAD src0_sel:WORD_1
	v_cvt_f32_f16_e32 v54, v139
	v_cvt_f32_f16_sdwa v55, v139 dst_sel:DWORD dst_unused:UNUSED_PAD src0_sel:WORD_1
	v_cvt_f32_f16_e32 v46, v136
	v_cvt_f32_f16_e32 v50, v138
	v_cvt_f32_f16_sdwa v51, v138 dst_sel:DWORD dst_unused:UNUSED_PAD src0_sel:WORD_1
	v_cvt_f32_f16_sdwa v47, v136 dst_sel:DWORD dst_unused:UNUSED_PAD src0_sel:WORD_1
	v_pk_mul_f32 v[36:37], v[52:53], v[48:49]
	v_pk_mul_f32 v[44:45], v[0:1], v[54:55]
	v_pk_mul_f32 v[48:49], v[42:43], v[50:51]
	v_pk_mul_f32 v[42:43], v[42:43], v[46:47]
	v_pk_mul_f32 v[46:47], v[40:41], v[36:37]
	v_pk_mul_f32 v[40:41], v[40:41], v[44:45]
	v_cvt_pk_f16_f32 v36, v36, v37
	v_cvt_pk_f16_f32 v37, v44, v45
	v_pk_mul_f32 v[50:51], v[38:39], v[48:49]
	v_pk_mul_f32 v[38:39], v[38:39], v[42:43]
	s_waitcnt lgkmcnt(14)
	ds_write2st64_b32 v215, v36, v37 offset1:18
	v_cvt_pk_f16_f32 v36, v46, v47
	v_cvt_pk_f16_f32 v37, v40, v41
	v_pk_mul_f32 v[48:49], v[0:1], v[48:49]
	s_waitcnt lgkmcnt(14)
	ds_write2st64_b32 v215, v36, v37 offset0:36 offset1:54
	v_cvt_pk_f16_f32 v36, v50, v51
	v_cvt_pk_f16_f32 v37, v38, v39
	s_waitcnt lgkmcnt(14)
	ds_write2st64_b32 v215, v36, v37 offset0:72 offset1:90
	v_cvt_f16_f32_e32 v36, v48
	v_pk_mul_f32 v[42:43], v[0:1], v[42:43]
	v_cvt_f16_f32_e32 v37, v49
	v_cvt_f16_f32_e32 v38, v42
	v_cvt_f16_f32_e32 v39, v43
	s_waitcnt lgkmcnt(14)
	ds_write_b16 v180, v36 offset:30
	s_waitcnt lgkmcnt(14)
	ds_write_b16 v180, v37 offset:70
	s_waitcnt lgkmcnt(14)
	ds_write_b16 v180, v38 offset:5150
	s_waitcnt lgkmcnt(14)
	ds_write_b16 v180, v39 offset:5190
	s_nop 0
	s_waitcnt lgkmcnt(7)
	ds_write_b16 v180, v2 offset:10270
	v_perm_b32 v36, v61, v60, s35
	v_perm_b32 v37, v2, v58, s35
	ds_write_b64 v180, v[36:37] offset:10304
.LBB0_944:
	s_andn2_saveexec_b64 s[68:69], s[68:69]
	s_cbranch_execz .LBB0_946
	v_lshl_add_u32 v251, v200, 1, v2
	v_lshl_add_u32 v250, v202, 1, v2
	ds_read2st64_b32 v[36:37], v251 offset0:64 offset1:80
	ds_read2st64_b32 v[48:49], v251 offset0:96 offset1:112
	ds_read_b32 v64, v251 offset:32768
	ds_read2st64_b32 v[128:129], v250 offset0:64 offset1:80
	ds_read2st64_b32 v[130:131], v250 offset0:96 offset1:112
	v_lshl_add_u32 v52, v200, 1, v2
	s_nop 0
	s_nop 0
	s_nop 0
	v_rcp_f32_e32 v44, v58
	v_rcp_f32_e32 v45, v59
	s_waitcnt lgkmcnt(3)
	v_cvt_f32_f16_e32 v60, v49
	v_cvt_f32_f16_e32 v54, v37
	v_cvt_f32_f16_sdwa v55, v37 dst_sel:DWORD dst_unused:UNUSED_PAD src0_sel:WORD_1
	v_cvt_f32_f16_sdwa v61, v49 dst_sel:DWORD dst_unused:UNUSED_PAD src0_sel:WORD_1
	v_cvt_f32_f16_e32 v52, v36
	v_cvt_f32_f16_e32 v56, v48
	v_cvt_f32_f16_sdwa v57, v48 dst_sel:DWORD dst_unused:UNUSED_PAD src0_sel:WORD_1
	v_cvt_f32_f16_sdwa v53, v36 dst_sel:DWORD dst_unused:UNUSED_PAD src0_sel:WORD_1
	v_pk_mul_f32 v[36:37], v[38:39], v[54:55]
	v_pk_mul_f32 v[48:49], v[58:59], v[60:61]
	v_pk_mul_f32 v[54:55], v[44:45], v[56:57]
	v_pk_mul_f32 v[44:45], v[44:45], v[52:53]
	v_pk_mul_f32 v[52:53], v[40:41], v[36:37]
	v_pk_mul_f32 v[56:57], v[40:41], v[48:49]
	v_cvt_pk_f16_f32 v36, v36, v37
	v_cvt_pk_f16_f32 v37, v48, v49
	v_pk_mul_f32 v[60:61], v[38:39], v[54:55]
	v_pk_mul_f32 v[62:63], v[38:39], v[44:45]
	ds_write2st64_b32 v201, v36, v37 offset1:18
	v_cvt_pk_f16_f32 v36, v52, v53
	v_cvt_pk_f16_f32 v37, v56, v57
	v_pk_mul_f32 v[54:55], v[0:1], v[54:55]
	ds_write2st64_b32 v201, v36, v37 offset0:36 offset1:54
	v_cvt_pk_f16_f32 v36, v60, v61
	v_cvt_pk_f16_f32 v37, v62, v63
	v_lshl_add_u32 v251, v204, 1, v2
	ds_read_b32 v62, v250 offset:32768
	ds_read2st64_b32 v[132:133], v251 offset0:64 offset1:80
	ds_read2st64_b32 v[134:135], v251 offset0:96 offset1:112
	ds_write2st64_b32 v201, v36, v37 offset0:72 offset1:90
	v_cvt_f16_f32_e32 v36, v54
	v_pk_mul_f32 v[44:45], v[0:1], v[44:45]
	v_cvt_f16_f32_e32 v37, v55
	v_cvt_f16_f32_e32 v44, v44
	v_cvt_f16_f32_e32 v45, v45
	ds_write_b16 v180, v36 offset:16
	ds_write_b16 v180, v37 offset:56
	ds_write_b16 v180, v44 offset:5136
	ds_write_b16 v180, v45 offset:5176
	s_waitcnt lgkmcnt(12)
	ds_write_b16 v180, v64 offset:10256
	v_lshl_add_u32 v52, v202, 1, v2
	v_rcp_f32_e32 v44, v50
	v_rcp_f32_e32 v45, v51
	s_waitcnt lgkmcnt(12)
	v_cvt_f32_f16_e32 v54, v129
	v_cvt_f32_f16_sdwa v55, v129 dst_sel:DWORD dst_unused:UNUSED_PAD src0_sel:WORD_1
	s_waitcnt lgkmcnt(11)
	v_cvt_f32_f16_e32 v60, v131
	v_cvt_f32_f16_sdwa v61, v131 dst_sel:DWORD dst_unused:UNUSED_PAD src0_sel:WORD_1
	v_cvt_f32_f16_e32 v52, v128
	v_cvt_f32_f16_e32 v56, v130
	v_cvt_f32_f16_sdwa v57, v130 dst_sel:DWORD dst_unused:UNUSED_PAD src0_sel:WORD_1
	v_cvt_f32_f16_sdwa v53, v128 dst_sel:DWORD dst_unused:UNUSED_PAD src0_sel:WORD_1
	v_pk_mul_f32 v[36:37], v[58:59], v[54:55]
	v_pk_mul_f32 v[48:49], v[50:51], v[60:61]
	v_pk_mul_f32 v[54:55], v[44:45], v[56:57]
	v_pk_mul_f32 v[44:45], v[44:45], v[52:53]
	v_pk_mul_f32 v[52:53], v[40:41], v[36:37]
	v_pk_mul_f32 v[56:57], v[40:41], v[48:49]
	v_cvt_pk_f16_f32 v36, v36, v37
	v_cvt_pk_f16_f32 v37, v48, v49
	v_pk_mul_f32 v[58:59], v[38:39], v[54:55]
	v_pk_mul_f32 v[60:61], v[38:39], v[44:45]
	ds_write2st64_b32 v203, v36, v37 offset1:18
	v_cvt_pk_f16_f32 v36, v52, v53
	v_cvt_pk_f16_f32 v37, v56, v57
	v_pk_mul_f32 v[54:55], v[0:1], v[54:55]
	ds_write2st64_b32 v203, v36, v37 offset0:36 offset1:54
	v_cvt_pk_f16_f32 v36, v58, v59
	v_cvt_pk_f16_f32 v37, v60, v61
	v_lshl_add_u32 v250, v206, 1, v2
	ds_read_b32 v60, v251 offset:32768
	ds_read2st64_b32 v[136:137], v250 offset0:64 offset1:80
	s_waitcnt lgkmcnt(14)
	ds_read2st64_b32 v[138:139], v250 offset0:96 offset1:112
	s_waitcnt lgkmcnt(14)
	ds_write2st64_b32 v203, v36, v37 offset0:72 offset1:90
	v_cvt_f16_f32_e32 v36, v54
	v_pk_mul_f32 v[44:45], v[0:1], v[44:45]
	v_cvt_f16_f32_e32 v37, v55
	v_cvt_f16_f32_e32 v44, v44
	v_cvt_f16_f32_e32 v45, v45
	s_waitcnt lgkmcnt(14)
	ds_write_b16 v180, v36 offset:18
	s_waitcnt lgkmcnt(14)
	ds_write_b16 v180, v37 offset:58
	s_waitcnt lgkmcnt(14)
	ds_write_b16 v180, v44 offset:5138
	s_waitcnt lgkmcnt(14)
	ds_write_b16 v180, v45 offset:5178
	s_waitcnt lgkmcnt(14)
	ds_write_b16 v180, v62 offset:10258
	v_lshl_add_u32 v52, v204, 1, v2
	v_rcp_f32_e32 v44, v46
	v_rcp_f32_e32 v45, v47
	v_lshl_add_u32 v2, v206, 1, v2
	v_cvt_f32_f16_e32 v54, v133
	v_cvt_f32_f16_sdwa v55, v133 dst_sel:DWORD dst_unused:UNUSED_PAD src0_sel:WORD_1
	v_cvt_f32_f16_e32 v58, v135
	v_cvt_f32_f16_sdwa v59, v135 dst_sel:DWORD dst_unused:UNUSED_PAD src0_sel:WORD_1
	v_cvt_f32_f16_e32 v52, v132
	v_cvt_f32_f16_e32 v56, v134
	v_cvt_f32_f16_sdwa v57, v134 dst_sel:DWORD dst_unused:UNUSED_PAD src0_sel:WORD_1
	v_cvt_f32_f16_sdwa v53, v132 dst_sel:DWORD dst_unused:UNUSED_PAD src0_sel:WORD_1
	v_pk_mul_f32 v[36:37], v[50:51], v[54:55]
	v_pk_mul_f32 v[48:49], v[46:47], v[58:59]
	v_pk_mul_f32 v[50:51], v[44:45], v[56:57]
	v_pk_mul_f32 v[44:45], v[44:45], v[52:53]
	v_pk_mul_f32 v[52:53], v[40:41], v[36:37]
	v_pk_mul_f32 v[54:55], v[40:41], v[48:49]
	v_cvt_pk_f16_f32 v36, v36, v37
	v_cvt_pk_f16_f32 v37, v48, v49
	v_pk_mul_f32 v[56:57], v[38:39], v[50:51]
	v_pk_mul_f32 v[58:59], v[38:39], v[44:45]
	s_waitcnt lgkmcnt(14)
	ds_write2st64_b32 v205, v36, v37 offset1:18
	v_cvt_pk_f16_f32 v36, v52, v53
	v_cvt_pk_f16_f32 v37, v54, v55
	v_pk_mul_f32 v[50:51], v[0:1], v[50:51]
	s_waitcnt lgkmcnt(14)
	ds_write2st64_b32 v205, v36, v37 offset0:36 offset1:54
	v_cvt_pk_f16_f32 v36, v56, v57
	v_cvt_pk_f16_f32 v37, v58, v59
	s_waitcnt lgkmcnt(14)
	ds_write2st64_b32 v205, v36, v37 offset0:72 offset1:90
	v_cvt_f16_f32_e32 v36, v50
	v_pk_mul_f32 v[44:45], v[0:1], v[44:45]
	v_cvt_f16_f32_e32 v37, v51
	v_cvt_f16_f32_e32 v44, v44
	v_cvt_f16_f32_e32 v45, v45
	s_waitcnt lgkmcnt(14)
	ds_write_b16 v180, v36 offset:20
	s_waitcnt lgkmcnt(14)
	ds_write_b16 v180, v37 offset:60
	s_waitcnt lgkmcnt(14)
	ds_write_b16 v180, v44 offset:5140
	s_waitcnt lgkmcnt(14)
	ds_write_b16 v180, v45 offset:5180
	s_waitcnt lgkmcnt(14)
	ds_write_b16 v180, v60 offset:10260
	s_waitcnt lgkmcnt(14)
	ds_read_b32 v2, v250 offset:32768
	v_rcp_f32_e32 v44, v42
	v_rcp_f32_e32 v45, v43
	v_cvt_f32_f16_e32 v52, v137
	v_cvt_f32_f16_sdwa v53, v137 dst_sel:DWORD dst_unused:UNUSED_PAD src0_sel:WORD_1
	v_cvt_f32_f16_e32 v56, v139
	v_cvt_f32_f16_sdwa v57, v139 dst_sel:DWORD dst_unused:UNUSED_PAD src0_sel:WORD_1
	v_cvt_f32_f16_e32 v50, v136
	v_cvt_f32_f16_e32 v54, v138
	v_cvt_f32_f16_sdwa v55, v138 dst_sel:DWORD dst_unused:UNUSED_PAD src0_sel:WORD_1
	v_cvt_f32_f16_sdwa v51, v136 dst_sel:DWORD dst_unused:UNUSED_PAD src0_sel:WORD_1
	v_pk_mul_f32 v[36:37], v[46:47], v[52:53]
	v_pk_mul_f32 v[42:43], v[42:43], v[56:57]
	v_pk_mul_f32 v[46:47], v[44:45], v[54:55]
	v_pk_mul_f32 v[44:45], v[44:45], v[50:51]
	v_pk_mul_f32 v[48:49], v[40:41], v[36:37]
	v_pk_mul_f32 v[40:41], v[40:41], v[42:43]
	v_cvt_pk_f16_f32 v36, v36, v37
	v_cvt_pk_f16_f32 v37, v42, v43
	v_pk_mul_f32 v[50:51], v[38:39], v[46:47]
	v_pk_mul_f32 v[38:39], v[38:39], v[44:45]
	s_waitcnt lgkmcnt(14)
	ds_write2st64_b32 v207, v36, v37 offset1:18
	v_cvt_pk_f16_f32 v36, v48, v49
	v_cvt_pk_f16_f32 v37, v40, v41
	v_pk_mul_f32 v[46:47], v[0:1], v[46:47]
	s_waitcnt lgkmcnt(14)
	ds_write2st64_b32 v207, v36, v37 offset0:36 offset1:54
	v_cvt_pk_f16_f32 v36, v50, v51
	v_cvt_pk_f16_f32 v37, v38, v39
	s_waitcnt lgkmcnt(14)
	ds_write2st64_b32 v207, v36, v37 offset0:72 offset1:90
	v_cvt_f16_f32_e32 v36, v46
	v_pk_mul_f32 v[44:45], v[0:1], v[44:45]
	v_cvt_f16_f32_e32 v37, v47
	v_cvt_f16_f32_e32 v38, v44
	v_cvt_f16_f32_e32 v39, v45
	s_waitcnt lgkmcnt(14)
	ds_write_b16 v180, v36 offset:22
	s_waitcnt lgkmcnt(14)
	ds_write_b16 v180, v37 offset:62
	s_waitcnt lgkmcnt(14)
	ds_write_b16 v180, v38 offset:5142
	s_waitcnt lgkmcnt(14)
	ds_write_b16 v180, v39 offset:5182
	s_nop 0
	s_waitcnt lgkmcnt(7)
	ds_write_b16 v180, v2 offset:10262
	v_perm_b32 v36, v62, v64, s35
	v_perm_b32 v37, v2, v60, s35
	ds_write_b64 v180, v[36:37] offset:10296

.LBB0_947:
	v_cmp_eq_u32_e32 vcc, 1, v178
	s_and_saveexec_b64 s[68:69], vcc
	s_cbranch_execz .LBB0_949
	v_lshl_add_u32 v251, v192, 1, v2
	v_lshl_add_u32 v250, v194, 1, v2
	ds_read2st64_b32 v[36:37], v251 offset0:64 offset1:80
	ds_read2st64_b32 v[46:47], v251 offset0:96 offset1:112
	ds_read_b32 v62, v251 offset:32768
	ds_read2st64_b32 v[128:129], v250 offset0:64 offset1:80
	ds_read2st64_b32 v[130:131], v250 offset0:96 offset1:112
	v_lshl_add_u32 v50, v192, 1, v2
	s_nop 0
	s_nop 0
	s_nop 0
	v_rcp_f32_e32 v42, v54
	v_rcp_f32_e32 v43, v55
	s_waitcnt lgkmcnt(3)
	v_cvt_f32_f16_e32 v58, v47
	v_cvt_f32_f16_e32 v52, v37
	v_cvt_f32_f16_sdwa v53, v37 dst_sel:DWORD dst_unused:UNUSED_PAD src0_sel:WORD_1
	v_cvt_f32_f16_sdwa v59, v47 dst_sel:DWORD dst_unused:UNUSED_PAD src0_sel:WORD_1
	v_cvt_f32_f16_e32 v50, v36
	v_cvt_f32_f16_e32 v56, v46
	v_cvt_f32_f16_sdwa v57, v46 dst_sel:DWORD dst_unused:UNUSED_PAD src0_sel:WORD_1
	v_cvt_f32_f16_sdwa v51, v36 dst_sel:DWORD dst_unused:UNUSED_PAD src0_sel:WORD_1
	v_pk_mul_f32 v[36:37], v[60:61], v[52:53]
	v_pk_mul_f32 v[46:47], v[54:55], v[58:59]
	v_pk_mul_f32 v[52:53], v[42:43], v[56:57]
	v_pk_mul_f32 v[42:43], v[42:43], v[50:51]
	v_pk_mul_f32 v[50:51], v[40:41], v[36:37]
	v_pk_mul_f32 v[56:57], v[40:41], v[46:47]
	v_cvt_pk_f16_f32 v36, v36, v37
	v_cvt_pk_f16_f32 v37, v46, v47
	v_pk_mul_f32 v[58:59], v[38:39], v[52:53]
	v_pk_mul_f32 v[60:61], v[38:39], v[42:43]
	ds_write2st64_b32 v193, v36, v37 offset1:18
	v_cvt_pk_f16_f32 v36, v50, v51
	v_cvt_pk_f16_f32 v37, v56, v57
	v_pk_mul_f32 v[52:53], v[0:1], v[52:53]
	ds_write2st64_b32 v193, v36, v37 offset0:36 offset1:54
	v_cvt_pk_f16_f32 v36, v58, v59
	v_cvt_pk_f16_f32 v37, v60, v61
	v_lshl_add_u32 v251, v196, 1, v2
	ds_read_b32 v60, v250 offset:32768
	ds_read2st64_b32 v[132:133], v251 offset0:64 offset1:80
	ds_read2st64_b32 v[134:135], v251 offset0:96 offset1:112
	ds_write2st64_b32 v193, v36, v37 offset0:72 offset1:90
	v_cvt_f16_f32_e32 v36, v52
	v_pk_mul_f32 v[42:43], v[0:1], v[42:43]
	v_cvt_f16_f32_e32 v37, v53
	v_cvt_f16_f32_e32 v42, v42
	v_cvt_f16_f32_e32 v43, v43
	ds_write_b16 v180, v36 offset:8
	ds_write_b16 v180, v37 offset:48
	ds_write_b16 v180, v42 offset:5128
	ds_write_b16 v180, v43 offset:5168
	s_waitcnt lgkmcnt(12)
	ds_write_b16 v180, v62 offset:10248
	v_lshl_add_u32 v50, v194, 1, v2
	v_rcp_f32_e32 v42, v48
	v_rcp_f32_e32 v43, v49
	s_waitcnt lgkmcnt(12)
	v_cvt_f32_f16_e32 v52, v129
	v_cvt_f32_f16_sdwa v53, v129 dst_sel:DWORD dst_unused:UNUSED_PAD src0_sel:WORD_1
	s_waitcnt lgkmcnt(11)
	v_cvt_f32_f16_e32 v58, v131
	v_cvt_f32_f16_sdwa v59, v131 dst_sel:DWORD dst_unused:UNUSED_PAD src0_sel:WORD_1
	v_cvt_f32_f16_e32 v50, v128
	v_cvt_f32_f16_e32 v56, v130
	v_cvt_f32_f16_sdwa v57, v130 dst_sel:DWORD dst_unused:UNUSED_PAD src0_sel:WORD_1
	v_cvt_f32_f16_sdwa v51, v128 dst_sel:DWORD dst_unused:UNUSED_PAD src0_sel:WORD_1
	v_pk_mul_f32 v[36:37], v[54:55], v[52:53]
	v_pk_mul_f32 v[46:47], v[48:49], v[58:59]
	v_pk_mul_f32 v[52:53], v[42:43], v[56:57]
	v_pk_mul_f32 v[42:43], v[42:43], v[50:51]
	v_pk_mul_f32 v[50:51], v[40:41], v[36:37]
	v_pk_mul_f32 v[54:55], v[40:41], v[46:47]
	v_cvt_pk_f16_f32 v36, v36, v37
	v_cvt_pk_f16_f32 v37, v46, v47
	v_pk_mul_f32 v[56:57], v[38:39], v[52:53]
	v_pk_mul_f32 v[58:59], v[38:39], v[42:43]
	ds_write2st64_b32 v195, v36, v37 offset1:18
	v_cvt_pk_f16_f32 v36, v50, v51
	v_cvt_pk_f16_f32 v37, v54, v55
	v_pk_mul_f32 v[52:53], v[0:1], v[52:53]
	ds_write2st64_b32 v195, v36, v37 offset0:36 offset1:54
	v_cvt_pk_f16_f32 v36, v56, v57
	v_cvt_pk_f16_f32 v37, v58, v59
	v_lshl_add_u32 v250, v198, 1, v2
	ds_read_b32 v58, v251 offset:32768
	ds_read2st64_b32 v[136:137], v250 offset0:64 offset1:80
	s_waitcnt lgkmcnt(14)
	ds_read2st64_b32 v[138:139], v250 offset0:96 offset1:112
	s_waitcnt lgkmcnt(14)
	ds_write2st64_b32 v195, v36, v37 offset0:72 offset1:90
	v_cvt_f16_f32_e32 v36, v52
	v_pk_mul_f32 v[42:43], v[0:1], v[42:43]
	v_cvt_f16_f32_e32 v37, v53
	v_cvt_f16_f32_e32 v42, v42
	v_cvt_f16_f32_e32 v43, v43
	s_waitcnt lgkmcnt(14)
	ds_write_b16 v180, v36 offset:10
	s_waitcnt lgkmcnt(14)
	ds_write_b16 v180, v37 offset:50
	s_waitcnt lgkmcnt(14)
	ds_write_b16 v180, v42 offset:5130
	s_waitcnt lgkmcnt(14)
	ds_write_b16 v180, v43 offset:5170
	s_waitcnt lgkmcnt(14)
	ds_write_b16 v180, v60 offset:10250
	v_lshl_add_u32 v50, v196, 1, v2
	v_rcp_f32_e32 v42, v44
	v_rcp_f32_e32 v43, v45
	v_lshl_add_u32 v2, v198, 1, v2
	v_cvt_f32_f16_e32 v52, v133
	v_cvt_f32_f16_sdwa v53, v133 dst_sel:DWORD dst_unused:UNUSED_PAD src0_sel:WORD_1
	v_cvt_f32_f16_e32 v56, v135
	v_cvt_f32_f16_sdwa v57, v135 dst_sel:DWORD dst_unused:UNUSED_PAD src0_sel:WORD_1
	v_cvt_f32_f16_e32 v50, v132
	v_cvt_f32_f16_e32 v54, v134
	v_cvt_f32_f16_sdwa v55, v134 dst_sel:DWORD dst_unused:UNUSED_PAD src0_sel:WORD_1
	v_cvt_f32_f16_sdwa v51, v132 dst_sel:DWORD dst_unused:UNUSED_PAD src0_sel:WORD_1
	v_pk_mul_f32 v[36:37], v[48:49], v[52:53]
	v_pk_mul_f32 v[46:47], v[44:45], v[56:57]
	v_pk_mul_f32 v[48:49], v[42:43], v[54:55]
	v_pk_mul_f32 v[42:43], v[42:43], v[50:51]
	v_pk_mul_f32 v[50:51], v[40:41], v[36:37]
	v_pk_mul_f32 v[52:53], v[40:41], v[46:47]
	v_cvt_pk_f16_f32 v36, v36, v37
	v_cvt_pk_f16_f32 v37, v46, v47
	v_pk_mul_f32 v[54:55], v[38:39], v[48:49]
	v_pk_mul_f32 v[56:57], v[38:39], v[42:43]
	s_waitcnt lgkmcnt(14)
	ds_write2st64_b32 v197, v36, v37 offset1:18
	v_cvt_pk_f16_f32 v36, v50, v51
	v_cvt_pk_f16_f32 v37, v52, v53
	v_pk_mul_f32 v[48:49], v[0:1], v[48:49]
	s_waitcnt lgkmcnt(14)
	ds_write2st64_b32 v197, v36, v37 offset0:36 offset1:54
	v_cvt_pk_f16_f32 v36, v54, v55
	v_cvt_pk_f16_f32 v37, v56, v57
	s_waitcnt lgkmcnt(14)
	ds_write2st64_b32 v197, v36, v37 offset0:72 offset1:90
	v_cvt_f16_f32_e32 v36, v48
	v_pk_mul_f32 v[42:43], v[0:1], v[42:43]
	v_cvt_f16_f32_e32 v37, v49
	v_cvt_f16_f32_e32 v42, v42
	v_cvt_f16_f32_e32 v43, v43
	s_waitcnt lgkmcnt(14)
	ds_write_b16 v180, v36 offset:12
	s_waitcnt lgkmcnt(14)
	ds_write_b16 v180, v37 offset:52
	s_waitcnt lgkmcnt(14)
	ds_write_b16 v180, v42 offset:5132
	s_waitcnt lgkmcnt(14)
	ds_write_b16 v180, v43 offset:5172
	s_waitcnt lgkmcnt(14)
	ds_write_b16 v180, v58 offset:10252
	s_waitcnt lgkmcnt(14)
	ds_read_b32 v2, v250 offset:32768
	v_cvt_f32_f16_e32 v48, v137
	v_cvt_f32_f16_sdwa v49, v137 dst_sel:DWORD dst_unused:UNUSED_PAD src0_sel:WORD_1
	v_cvt_f32_f16_e32 v52, v139
	v_cvt_f32_f16_sdwa v53, v139 dst_sel:DWORD dst_unused:UNUSED_PAD src0_sel:WORD_1
	v_cvt_f32_f16_e32 v46, v136
	v_cvt_f32_f16_e32 v50, v138
	v_cvt_f32_f16_sdwa v51, v138 dst_sel:DWORD dst_unused:UNUSED_PAD src0_sel:WORD_1
	v_cvt_f32_f16_sdwa v47, v136 dst_sel:DWORD dst_unused:UNUSED_PAD src0_sel:WORD_1
	v_pk_mul_f32 v[36:37], v[44:45], v[48:49]
	v_pk_mul_f32 v[42:43], v[38:39], v[52:53]
	v_pk_mul_f32 v[44:45], v[40:41], v[50:51]
	v_pk_mul_f32 v[46:47], v[40:41], v[46:47]
	v_pk_mul_f32 v[48:49], v[40:41], v[36:37]
	v_pk_mul_f32 v[40:41], v[40:41], v[42:43]
	v_cvt_pk_f16_f32 v36, v36, v37
	v_cvt_pk_f16_f32 v37, v42, v43
	v_pk_mul_f32 v[50:51], v[38:39], v[44:45]
	v_pk_mul_f32 v[38:39], v[38:39], v[46:47]
	s_waitcnt lgkmcnt(14)
	ds_write2st64_b32 v199, v36, v37 offset1:18
	v_cvt_pk_f16_f32 v36, v48, v49
	v_cvt_pk_f16_f32 v37, v40, v41
	v_pk_mul_f32 v[44:45], v[0:1], v[44:45]
	s_waitcnt lgkmcnt(14)
	ds_write2st64_b32 v199, v36, v37 offset0:36 offset1:54
	v_cvt_pk_f16_f32 v36, v50, v51
	v_cvt_pk_f16_f32 v37, v38, v39
	s_waitcnt lgkmcnt(14)
	ds_write2st64_b32 v199, v36, v37 offset0:72 offset1:90
	v_cvt_f16_f32_e32 v36, v44
	v_pk_mul_f32 v[46:47], v[0:1], v[46:47]
	v_cvt_f16_f32_e32 v37, v45
	v_cvt_f16_f32_e32 v38, v46
	v_cvt_f16_f32_e32 v39, v47
	s_waitcnt lgkmcnt(14)
	ds_write_b16 v180, v36 offset:14
	s_waitcnt lgkmcnt(14)
	ds_write_b16 v180, v37 offset:54
	s_waitcnt lgkmcnt(14)
	ds_write_b16 v180, v38 offset:5134
	s_waitcnt lgkmcnt(14)
	ds_write_b16 v180, v39 offset:5174
	s_nop 0
	s_waitcnt lgkmcnt(7)
	ds_write_b16 v180, v2 offset:10254
	v_perm_b32 v36, v60, v62, s35
	v_perm_b32 v37, v2, v58, s35
	ds_write_b64 v180, v[36:37] offset:10288

.LBB0_1028:
	s_andn2_b64 vcc, exec, s[24:25]
	s_mov_b64 s[26:27], -1
	s_cbranch_vccnz .LBB0_1036
	s_and_b32 s26, s76, 1
	v_lshl_add_u32 v0, s26, 13, v229
	ds_read2_b64 v[36:39], v0 offset1:32
	v_mad_u32_u24 v2, s26, v167, v230
	s_waitcnt lgkmcnt(0)
	v_pk_mul_f32 v[66:67], v[36:37], v[38:39]
	v_xor_b32_e32 v90, 16, v0
	ds_read2_b64 v[38:41], v90 offset0:64 offset1:96
	s_waitcnt lgkmcnt(0)
	v_pk_mul_f32 v[64:65], v[66:67], v[38:39]
	s_nop 0
	v_pk_mul_f32 v[60:61], v[64:65], v[40:41]
	v_xor_b32_e32 v91, 32, v0
	ds_read2_b64 v[38:41], v91 offset0:128 offset1:160
	s_waitcnt lgkmcnt(0)
	v_pk_mul_f32 v[54:55], v[60:61], v[38:39]
	s_nop 0
	v_pk_mul_f32 v[48:49], v[54:55], v[40:41]
	v_xor_b32_e32 v92, 48, v0
	ds_read2_b64 v[38:41], v92 offset0:192 offset1:224
	v_add_u32_e32 v0, 0x800, v0
	v_xor_b32_e32 v91, 32, v0
	ds_read2_b64 v[68:71], v91 offset0:128 offset1:160
	s_waitcnt lgkmcnt(1)
	v_pk_mul_f32 v[44:45], v[48:49], v[38:39]
	s_nop 0
	v_pk_mul_f32 v[38:39], v[44:45], v[40:41]
	ds_read2_b64 v[40:43], v0 offset1:32
	s_waitcnt lgkmcnt(0)
	v_pk_mul_f32 v[58:59], v[38:39], v[40:41]
	s_nop 0
	v_pk_mul_f32 v[50:51], v[58:59], v[42:43]
	v_xor_b32_e32 v90, 16, v0
	ds_read2_b64 v[40:43], v90 offset0:64 offset1:96
	s_waitcnt lgkmcnt(0)
	v_pk_mul_f32 v[46:47], v[50:51], v[40:41]
	s_nop 0
	v_pk_mul_f32 v[42:43], v[46:47], v[42:43]
	v_rcp_f32_e32 v40, v38
	v_pk_mul_f32 v[62:63], v[42:43], v[68:69]
	v_rcp_f32_e32 v41, v39
	v_pk_mul_f32 v[56:57], v[62:63], v[70:71]
	v_xor_b32_e32 v92, 48, v0
	ds_read2_b64 v[68:71], v92 offset0:192 offset1:224
	s_waitcnt lgkmcnt(0)
	v_pk_mul_f32 v[52:53], v[56:57], v[68:69]
	s_nop 0
	v_pk_mul_f32 v[0:1], v[52:53], v[70:71]
	s_and_saveexec_b64 s[26:27], s[4:5]
	s_cbranch_execz .LBB0_1031
	v_lshl_add_u32 v251, v175, 1, v2
	v_lshl_add_u32 v250, v182, 1, v2
	ds_read2st64_b32 v[72:73], v251 offset0:96 offset1:112
	ds_read2st64_b32 v[68:69], v251 offset0:64 offset1:80
	ds_read_b32 v84, v251 offset:32768
	ds_read2st64_b32 v[126:127], v250 offset0:64 offset1:80
	ds_read2st64_b32 v[128:129], v250 offset0:96 offset1:112
	v_lshl_add_u32 v74, v175, 1, v2
	s_nop 0
	s_nop 0
	v_rcp_f32_e32 v70, v36
	v_rcp_f32_e32 v71, v37
	s_waitcnt lgkmcnt(4)
	v_cvt_f32_f16_e32 v78, v73
	v_cvt_f32_f16_sdwa v79, v73 dst_sel:DWORD dst_unused:UNUSED_PAD src0_sel:WORD_1
	s_waitcnt lgkmcnt(3)
	v_cvt_f32_f16_e32 v74, v68
	v_cvt_f32_f16_sdwa v75, v68 dst_sel:DWORD dst_unused:UNUSED_PAD src0_sel:WORD_1
	v_cvt_f32_f16_e32 v76, v72
	v_cvt_f32_f16_sdwa v77, v72 dst_sel:DWORD dst_unused:UNUSED_PAD src0_sel:WORD_1
	v_cvt_f32_f16_e32 v72, v69
	v_cvt_f32_f16_sdwa v73, v69 dst_sel:DWORD dst_unused:UNUSED_PAD src0_sel:WORD_1
	v_pk_mul_f32 v[78:79], v[36:37], v[78:79]
	v_pk_mul_f32 v[76:77], v[70:71], v[76:77]
	v_pk_mul_f32 v[70:71], v[70:71], v[74:75]
	v_pk_mul_f32 v[72:73], v[40:41], v[72:73]
	v_pk_mul_f32 v[74:75], v[40:41], v[78:79]
	v_cvt_pk_f16_f32 v68, v78, v79
	v_pk_mul_f32 v[80:81], v[38:39], v[76:77]
	v_pk_mul_f32 v[82:83], v[38:39], v[70:71]
	ds_write2st64_b32 v181, v69, v68 offset1:18
	v_cvt_pk_f16_f32 v68, v72, v73
	v_cvt_pk_f16_f32 v69, v74, v75
	v_pk_mul_f32 v[76:77], v[0:1], v[76:77]
	ds_write2st64_b32 v181, v68, v69 offset0:36 offset1:54
	v_cvt_pk_f16_f32 v68, v80, v81
	v_cvt_pk_f16_f32 v69, v82, v83
	v_lshl_add_u32 v251, v184, 1, v2
	ds_read_b32 v82, v250 offset:32768
	ds_read2st64_b32 v[130:131], v251 offset0:64 offset1:80
	ds_read2st64_b32 v[132:133], v251 offset0:96 offset1:112
	ds_write2st64_b32 v181, v68, v69 offset0:72 offset1:90
	v_cvt_f16_f32_e32 v68, v76
	v_pk_mul_f32 v[70:71], v[0:1], v[70:71]
	v_cvt_f16_f32_e32 v69, v77
	v_cvt_f16_f32_e32 v70, v70
	v_cvt_f16_f32_e32 v71, v71
	ds_write_b16 v176, v68
	ds_write_b16 v176, v69 offset:40
	ds_write_b16 v176, v70 offset:5120
	ds_write_b16 v176, v71 offset:5160
	s_waitcnt lgkmcnt(12)
	ds_write_b16 v176, v84 offset:10240
	v_lshl_add_u32 v74, v182, 1, v2
	v_rcp_f32_e32 v70, v66
	v_rcp_f32_e32 v71, v67
	s_waitcnt lgkmcnt(12)
	v_cvt_f32_f16_e32 v76, v127
	v_cvt_f32_f16_sdwa v77, v127 dst_sel:DWORD dst_unused:UNUSED_PAD src0_sel:WORD_1
	s_waitcnt lgkmcnt(11)
	v_cvt_f32_f16_e32 v80, v129
	v_cvt_f32_f16_sdwa v81, v129 dst_sel:DWORD dst_unused:UNUSED_PAD src0_sel:WORD_1
	v_cvt_f32_f16_e32 v74, v126
	v_cvt_f32_f16_e32 v78, v128
	v_cvt_f32_f16_sdwa v79, v128 dst_sel:DWORD dst_unused:UNUSED_PAD src0_sel:WORD_1
	v_cvt_f32_f16_sdwa v75, v126 dst_sel:DWORD dst_unused:UNUSED_PAD src0_sel:WORD_1
	v_pk_mul_f32 v[36:37], v[36:37], v[76:77]
	v_pk_mul_f32 v[68:69], v[66:67], v[80:81]
	v_pk_mul_f32 v[72:73], v[70:71], v[78:79]
	v_pk_mul_f32 v[70:71], v[70:71], v[74:75]
	v_pk_mul_f32 v[74:75], v[40:41], v[36:37]
	v_pk_mul_f32 v[76:77], v[40:41], v[68:69]
	v_cvt_pk_f16_f32 v36, v36, v37
	v_cvt_pk_f16_f32 v37, v68, v69
	v_pk_mul_f32 v[78:79], v[38:39], v[72:73]
	v_pk_mul_f32 v[80:81], v[38:39], v[70:71]
	ds_write2st64_b32 v183, v36, v37 offset1:18
	v_cvt_pk_f16_f32 v36, v74, v75
	v_cvt_pk_f16_f32 v37, v76, v77
	v_pk_mul_f32 v[72:73], v[0:1], v[72:73]
	ds_write2st64_b32 v183, v36, v37 offset0:36 offset1:54
	v_cvt_pk_f16_f32 v36, v78, v79
	v_cvt_pk_f16_f32 v37, v80, v81
	v_lshl_add_u32 v250, v186, 1, v2
	ds_read_b32 v80, v251 offset:32768
	ds_read2st64_b32 v[134:135], v250 offset0:64 offset1:80
	s_waitcnt lgkmcnt(14)
	ds_read2st64_b32 v[136:137], v250 offset0:96 offset1:112
	s_waitcnt lgkmcnt(14)
	ds_write2st64_b32 v183, v36, v37 offset0:72 offset1:90
	v_cvt_f16_f32_e32 v36, v72
	v_pk_mul_f32 v[70:71], v[0:1], v[70:71]
	v_cvt_f16_f32_e32 v37, v73
	v_cvt_f16_f32_e32 v68, v70
	v_cvt_f16_f32_e32 v69, v71
	s_waitcnt lgkmcnt(14)
	ds_write_b16 v176, v36 offset:2
	s_waitcnt lgkmcnt(14)
	ds_write_b16 v176, v37 offset:42
	s_waitcnt lgkmcnt(14)
	ds_write_b16 v176, v68 offset:5122
	s_waitcnt lgkmcnt(14)
	ds_write_b16 v176, v69 offset:5162
	s_waitcnt lgkmcnt(14)
	ds_write_b16 v176, v82 offset:10242
	v_lshl_add_u32 v72, v184, 1, v2
	v_rcp_f32_e32 v68, v64
	v_rcp_f32_e32 v69, v65
	v_cvt_f32_f16_e32 v74, v131
	v_cvt_f32_f16_sdwa v75, v131 dst_sel:DWORD dst_unused:UNUSED_PAD src0_sel:WORD_1
	v_cvt_f32_f16_e32 v78, v133
	v_cvt_f32_f16_sdwa v79, v133 dst_sel:DWORD dst_unused:UNUSED_PAD src0_sel:WORD_1
	v_cvt_f32_f16_e32 v72, v130
	v_cvt_f32_f16_e32 v76, v132
	v_cvt_f32_f16_sdwa v77, v132 dst_sel:DWORD dst_unused:UNUSED_PAD src0_sel:WORD_1
	v_cvt_f32_f16_sdwa v73, v130 dst_sel:DWORD dst_unused:UNUSED_PAD src0_sel:WORD_1
	v_pk_mul_f32 v[36:37], v[66:67], v[74:75]
	v_pk_mul_f32 v[66:67], v[64:65], v[78:79]
	v_pk_mul_f32 v[70:71], v[68:69], v[76:77]
	v_pk_mul_f32 v[68:69], v[68:69], v[72:73]
	v_pk_mul_f32 v[72:73], v[40:41], v[36:37]
	v_pk_mul_f32 v[74:75], v[40:41], v[66:67]
	v_cvt_pk_f16_f32 v36, v36, v37
	v_cvt_pk_f16_f32 v37, v66, v67
	v_pk_mul_f32 v[76:77], v[38:39], v[70:71]
	v_pk_mul_f32 v[78:79], v[38:39], v[68:69]
	s_waitcnt lgkmcnt(14)
	ds_write2st64_b32 v185, v36, v37 offset1:18
	v_cvt_pk_f16_f32 v36, v72, v73
	v_cvt_pk_f16_f32 v37, v74, v75
	v_pk_mul_f32 v[70:71], v[0:1], v[70:71]
	s_waitcnt lgkmcnt(14)
	ds_write2st64_b32 v185, v36, v37 offset0:36 offset1:54
	v_cvt_pk_f16_f32 v36, v76, v77
	v_cvt_pk_f16_f32 v37, v78, v79
	s_waitcnt lgkmcnt(14)
	ds_read_b32 v78, v250 offset:32768
	s_waitcnt lgkmcnt(14)
	ds_write2st64_b32 v185, v36, v37 offset0:72 offset1:90
	v_cvt_f16_f32_e32 v36, v70
	v_pk_mul_f32 v[68:69], v[0:1], v[68:69]
	v_cvt_f16_f32_e32 v37, v71
	v_cvt_f16_f32_e32 v66, v68
	v_cvt_f16_f32_e32 v67, v69
	s_waitcnt lgkmcnt(14)
	ds_write_b16 v176, v36 offset:4
	s_waitcnt lgkmcnt(14)
	ds_write_b16 v176, v37 offset:44
	s_waitcnt lgkmcnt(14)
	ds_write_b16 v176, v66 offset:5124
	s_waitcnt lgkmcnt(14)
	ds_write_b16 v176, v67 offset:5164
	s_waitcnt lgkmcnt(14)
	ds_write_b16 v176, v80 offset:10244
	v_lshl_add_u32 v70, v186, 1, v2
	v_rcp_f32_e32 v66, v60
	v_rcp_f32_e32 v67, v61
	v_cvt_f32_f16_e32 v72, v135
	v_cvt_f32_f16_sdwa v73, v135 dst_sel:DWORD dst_unused:UNUSED_PAD src0_sel:WORD_1
	v_cvt_f32_f16_e32 v76, v137
	v_cvt_f32_f16_sdwa v77, v137 dst_sel:DWORD dst_unused:UNUSED_PAD src0_sel:WORD_1
	v_cvt_f32_f16_e32 v70, v134
	v_cvt_f32_f16_e32 v74, v136
	v_cvt_f32_f16_sdwa v75, v136 dst_sel:DWORD dst_unused:UNUSED_PAD src0_sel:WORD_1
	v_cvt_f32_f16_sdwa v71, v134 dst_sel:DWORD dst_unused:UNUSED_PAD src0_sel:WORD_1
	v_pk_mul_f32 v[36:37], v[64:65], v[72:73]
	v_pk_mul_f32 v[64:65], v[60:61], v[76:77]
	v_pk_mul_f32 v[68:69], v[66:67], v[74:75]
	v_pk_mul_f32 v[66:67], v[66:67], v[70:71]
	v_pk_mul_f32 v[70:71], v[40:41], v[36:37]
	v_pk_mul_f32 v[72:73], v[40:41], v[64:65]
	v_cvt_pk_f16_f32 v36, v36, v37
	v_cvt_pk_f16_f32 v37, v64, v65
	v_pk_mul_f32 v[74:75], v[38:39], v[68:69]
	v_pk_mul_f32 v[76:77], v[38:39], v[66:67]
	s_waitcnt lgkmcnt(14)
	ds_write2st64_b32 v187, v36, v37 offset1:18
	v_cvt_pk_f16_f32 v36, v70, v71
	v_cvt_pk_f16_f32 v37, v72, v73
	v_pk_mul_f32 v[68:69], v[0:1], v[68:69]
	s_waitcnt lgkmcnt(14)
	ds_write2st64_b32 v187, v36, v37 offset0:36 offset1:54
	v_cvt_pk_f16_f32 v36, v74, v75
	v_cvt_pk_f16_f32 v37, v76, v77
	s_waitcnt lgkmcnt(14)
	ds_write2st64_b32 v187, v36, v37 offset0:72 offset1:90
	v_cvt_f16_f32_e32 v36, v68
	v_pk_mul_f32 v[66:67], v[0:1], v[66:67]
	v_cvt_f16_f32_e32 v37, v69
	v_cvt_f16_f32_e32 v64, v66
	v_cvt_f16_f32_e32 v65, v67
	s_waitcnt lgkmcnt(14)
	ds_write_b16 v176, v36 offset:6
	s_waitcnt lgkmcnt(14)
	ds_write_b16 v176, v37 offset:46
	s_waitcnt lgkmcnt(14)
	ds_write_b16 v176, v64 offset:5126
	s_waitcnt lgkmcnt(14)
	ds_write_b16 v176, v65 offset:5166
	s_nop 0
	s_waitcnt lgkmcnt(13)
	ds_write_b16 v176, v78 offset:10246
	v_perm_b32 v36, v82, v84, s35
	v_perm_b32 v37, v78, v80, s35
	ds_write_b64 v176, v[36:37] offset:10280

.LBB0_1035:
	s_or_b64 exec, exec, s[26:27]
	s_waitcnt lgkmcnt(0)
	s_barrier
	ds_read_b128 v[36:39], v212 offset:18432
	ds_read_b128 v[40:43], v212 offset:9216
	ds_read_b128 v[48:51], v212 offset:18496
	s_waitcnt lgkmcnt(1)
	v_mfma_f32_16x16x32_f16 v[52:55], v[40:43], v[36:39], 0
	ds_read_b128 v[56:59], v212 offset:9280
	ds_read_b128 v[60:63], v212 offset:23040
	ds_read_b128 v[64:67], v212 offset:13824
	ds_read_b128 v[68:71], v212 offset:13888
	ds_read_b128 v[72:75], v212 offset:23104
	v_add_u32_e32 v80, 0x1000, v217
	s_waitcnt lgkmcnt(4)
	v_mfma_f32_16x16x32_f16 v[52:55], v[56:59], v[48:51], v[52:55]
	s_nop 0
	s_nop 0
	s_nop 0
	v_mfma_f32_16x16x32_f16 v[44:47], v[36:39], v[40:43], 0
	s_nop 3
	v_cvt_f16_f32_e32 v0, v52
	v_cvt_f16_f32_e32 v1, v54
	v_cvt_f16_f32_e32 v2, v55
	v_mfma_f32_16x16x32_f16 v[44:47], v[48:51], v[56:59], v[44:47]
	v_cndmask_b32_e64 v79, 0, v0, s[12:13]
	v_cvt_f16_f32_e32 v0, v53
	v_cndmask_b32_e64 v54, 0, v1, s[18:19]
	s_waitcnt lgkmcnt(3)
	v_mfma_f32_16x16x32_f16 v[40:43], v[60:63], v[40:43], 0
	v_cndmask_b32_e64 v55, 0, v2, s[22:23]
	s_nop 1
	v_cndmask_b32_e64 v76, 0, v44, s[10:11]
	v_cndmask_b32_e64 v77, 0, v45, s[14:15]
	s_waitcnt lgkmcnt(2)
	v_mfma_f32_16x16x32_f16 v[36:39], v[36:39], v[64:67], 0
	v_cndmask_b32_e64 v52, 0, v46, s[16:17]
	v_cndmask_b32_e64 v78, 0, v47, s[20:21]
	v_cndmask_b32_e64 v53, v0, 0, s[10:11]
	v_mfma_f32_16x16x32_f16 v[44:47], v[60:63], v[64:67], 0
	v_cvt_pk_f16_f32 v1, v52, v78
	v_cvt_pk_f16_f32 v0, v76, v77
	s_nop 0
	s_waitcnt lgkmcnt(0)
	v_mfma_f32_16x16x32_f16 v[60:63], v[72:75], v[56:59], v[40:43]
	v_add_f32_e32 v56, v213, v76
	v_add_f32_e32 v57, v214, v77
	v_add_f32_e32 v58, v215, v52
	v_mfma_f32_16x16x32_f16 v[40:43], v[48:51], v[68:71], v[36:39]
	v_add_f32_e32 v59, v216, v78
	v_cvt_pk_f16_f32 v67, v18, v19
	v_cvt_pk_f16_f32 v66, v16, v17
	v_pack_b32_f16 v37, v54, v55
	v_pack_b32_f16 v36, v79, v53
	s_nop 0
	s_nop 0
	v_mfma_f32_16x16x32_f16 v[52:55], v[72:75], v[68:71], v[44:47]
	ds_read2_b64 v[68:71], v217 offset0:8 offset1:12
	v_cvt_pk_f16_f32 v65, v14, v15
	v_cvt_pk_f16_f32 v64, v12, v13
	v_mfma_f32_16x16x16_f16 v[48:51], v[0:1], v[36:37], 0
	v_cvt_pk_f16_f32 v45, v58, v59
	v_cvt_pk_f16_f32 v44, v56, v57
	s_nop 0
	v_mfma_f32_16x16x16_f16 v[36:39], v[36:37], v[0:1], 0
	s_nop 0
	s_nop 2
	v_cvt_pk_f16_f32 v1, v50, v51
	v_cvt_pk_f16_f32 v0, v48, v49
	s_nop 0
	s_nop 0
	v_cvt_pk_f16_f32 v49, v38, v39
	v_cvt_pk_f16_f32 v48, v36, v37
	v_mfma_f32_16x16x16_f16 v[44:47], v[0:1], v[44:45], v[56:59]
	s_nop 0
	s_nop 0
	s_nop 0
	v_mfma_f32_16x16x16_f16 v[36:39], v[48:49], v[0:1], 0
	v_cvt_pk_f16_f32 v59, v10, v11
	v_cvt_pk_f16_f32 v58, v8, v9
	v_cvt_pk_f16_f32 v57, v6, v7
	v_mfma_f32_16x16x16_f16 v[48:51], v[0:1], v[48:49], 0
	v_cvt_pk_f16_f32 v56, v4, v5
	s_nop 2
	v_cvt_pk_f16_f32 v1, v38, v39
	v_cvt_pk_f16_f32 v0, v36, v37
	v_cvt_pk_f16_f32 v37, v46, v47
	v_cvt_pk_f16_f32 v36, v44, v45
	s_nop 0
	s_nop 0
	v_cvt_f16_f32_e32 v52, v52
	s_add_i32 s28, s76, 1
	v_mfma_f32_16x16x16_f16 v[44:47], v[0:1], v[36:37], v[44:47]
	v_cvt_pk_f16_f32 v37, v50, v51
	v_cvt_pk_f16_f32 v36, v48, v49
	s_nop 0
	s_nop 0
	v_mfma_f32_16x16x16_f16 v[36:39], v[36:37], v[0:1], 0
	s_nop 2
	v_cvt_pk_f16_f32 v1, v46, v47
	v_cvt_pk_f16_f32 v0, v44, v45
	s_nop 2
	v_cvt_pk_f16_f32 v49, v38, v39
	v_cvt_pk_f16_f32 v48, v36, v37
	ds_read2_b64 v[36:39], v217 offset1:4
	s_waitcnt lgkmcnt(0)
	v_mfma_f32_16x16x32_f16 v[36:39], v[36:39], v[56:59], 0
	v_mfma_f32_16x16x16_f16 v[44:47], v[48:49], v[0:1], v[44:47]
	v_cvt_f16_f32_e32 v0, v60
	v_cvt_f16_f32_e32 v1, v61
	v_cvt_f16_f32_e32 v2, v62
	v_cvt_f16_f32_e32 v48, v63
	v_mfma_f32_16x16x32_f16 v[76:79], v[68:71], v[64:67], v[36:39]
	ds_read2_b64 v[72:75], v80 offset0:64 offset1:68
	ds_read2_b64 v[68:71], v80 offset0:72 offset1:76
	s_nop 0
	ds_read2st64_b64 v[36:39], v218 offset0:20 offset1:25
	v_cndmask_b32_e64 v0, 0, v0, s[10:11]
	v_cndmask_b32_e64 v49, 0, v1, s[14:15]
	v_cndmask_b32_e64 v1, 0, v2, s[16:17]
	v_cndmask_b32_e64 v2, 0, v48, s[20:21]
	v_pack_b32_f16 v1, v1, v2
	v_pack_b32_f16 v0, v0, v49
	s_nop 0
	s_waitcnt lgkmcnt(0)
	v_mov_b32_e32 v60, v36
	v_mov_b32_e32 v61, v37
	s_nop 0
	s_nop 0
	v_cvt_f16_f32_e32 v36, v40
	v_cvt_f16_f32_e32 v40, v42
	v_mfma_f32_16x16x16_f16 v[48:51], v[0:1], v[60:61], v[76:79]
	v_cvt_pk_f16_f32 v1, v46, v47
	v_cvt_pk_f16_f32 v0, v44, v45
	v_cvt_f16_f32_e32 v37, v41
	s_nop 0
	s_nop 0
	s_nop 2
	v_cvt_pk_f16_f32 v77, v50, v51
	v_cvt_pk_f16_f32 v76, v48, v49
	v_cndmask_b32_e64 v88, v40, 0, s[18:19]
	v_mfma_f32_16x16x32_f16 v[56:59], v[72:75], v[56:59], 0
	v_cndmask_b32_e64 v36, v36, 0, s[12:13]
	v_cndmask_b32_e64 v37, 0, v37, s[10:11]
	s_nop 0
	v_mfma_f32_16x16x16_f16 v[44:47], v[0:1], v[76:77], 0
	s_nop 0
	v_mfma_f32_16x16x32_f16 v[56:59], v[68:71], v[64:67], v[56:59]
	s_nop 5
	v_cvt_pk_f16_f32 v1, v46, v47
	v_cvt_pk_f16_f32 v0, v44, v45
	ds_read2_b64 v[44:47], v233 offset1:80
	ds_read_b128 v[48:51], v178
	ds_read_b64 v[76:77], v219 offset:5120
	s_waitcnt lgkmcnt(2)
	v_mov_b32_e32 v80, v44
	v_mov_b32_e32 v81, v45
	s_waitcnt lgkmcnt(1)
	v_pk_mul_f32 v[50:51], v[6:7], v[50:51]
	v_pk_mul_f32 v[48:49], v[4:5], v[48:49]
	s_nop 1
	v_mfma_f32_16x16x16_f16 v[48:51], v[80:81], v[0:1], v[48:51]
	v_cvt_f16_f32_e32 v80, v43
	v_cndmask_b32_e64 v89, v80, 0, s[22:23]
	s_waitcnt lgkmcnt(0)
	v_mfma_f32_16x16x16_f16 v[40:43], v[76:77], v[60:61], v[48:51]
	s_nop 3
	ds_read_b128 v[48:51], v178 offset:64
	ds_read_b64 v[44:45], v220 offset:5120
	v_mov_b32_e32 v76, v46
	v_mov_b32_e32 v77, v47
	s_nop 0
	s_waitcnt lgkmcnt(1)
	v_pk_mul_f32 v[50:51], v[10:11], v[50:51]
	v_pk_mul_f32 v[48:49], v[8:9], v[48:49]
	s_nop 0
	s_nop 0
	v_mfma_f32_16x16x16_f16 v[48:51], v[76:77], v[0:1], v[48:51]
	ds_read2_b64 v[76:79], v233 offset0:160 offset1:240
	s_waitcnt lgkmcnt(0)
	v_mov_b32_e32 v84, v76
	v_mfma_f32_16x16x16_f16 v[48:51], v[44:45], v[60:61], v[48:51]
	ds_read_b128 v[44:47], v178 offset:128
	ds_read_b64 v[80:81], v221 offset:5120
	v_mov_b32_e32 v85, v77
	v_pack_b32_f16 v77, v88, v89
	v_mov_b32_e32 v88, v78
	s_waitcnt lgkmcnt(1)
	v_pk_mul_f32 v[46:47], v[14:15], v[46:47]
	v_pk_mul_f32 v[44:45], v[12:13], v[44:45]
	v_mov_b32_e32 v89, v79
	v_pack_b32_f16 v76, v36, v37
	v_mfma_f32_16x16x16_f16 v[44:47], v[84:85], v[0:1], v[44:47]
	v_cndmask_b32_e64 v36, v52, 0, s[12:13]
	v_cvt_f16_f32_e32 v37, v53
	v_cndmask_b32_e64 v37, 0, v37, s[10:11]
	s_waitcnt lgkmcnt(0)
	v_mfma_f32_16x16x16_f16 v[44:47], v[80:81], v[60:61], v[44:47]
	ds_read_b128 v[80:83], v178 offset:192
	ds_read_b64 v[84:85], v222 offset:5120
	v_pack_b32_f16 v72, v36, v37
	ds_read_b128 v[68:71], v223 offset:9216
	ds_read_b128 v[94:97], v223 offset:9280
	s_waitcnt lgkmcnt(3)
	v_pk_mul_f32 v[82:83], v[18:19], v[82:83]
	v_pk_mul_f32 v[80:81], v[16:17], v[80:81]
	ds_read_b128 v[64:67], v223 offset:18432
	ds_read_b128 v[98:101], v223 offset:23104
	v_mfma_f32_16x16x16_f16 v[78:81], v[88:89], v[0:1], v[80:83]
	ds_read_b128 v[90:93], v223 offset:18496
	s_nop 1
	v_cvt_f16_f32_e32 v82, v54
	v_cvt_f16_f32_e32 v83, v55
	s_waitcnt lgkmcnt(5)
	v_mfma_f32_16x16x16_f16 v[52:55], v[84:85], v[60:61], v[78:81]
	ds_read_b128 v[86:89], v223 offset:13824
	s_nop 1
	v_cndmask_b32_e64 v78, v82, 0, s[18:19]
	v_cndmask_b32_e64 v79, v83, 0, s[22:23]
	v_pack_b32_f16 v73, v78, v79
	s_nop 0
	s_nop 0
	v_add_u32_e32 v80, s69, v153
	v_add_u32_e32 v81, s68, v232
	v_mfma_f32_16x16x16_f16 v[56:59], v[76:77], v[0:1], v[56:59]
	ds_read_b128 v[76:79], v223 offset:23040
	v_subrev_u32_e32 v102, 64, v80
	v_add_u32_e32 v0, 0x7ff, v81
	v_mfma_f32_16x16x16_f16 v[58:61], v[72:73], v[60:61], v[56:59]
	v_cndmask_b32_e64 v0, v0, v102, s[2:3]
	v_add_u32_e32 v0, v0, v151
	v_mad_i64_i32 v[0:1], s[26:27], v0, s88, v[122:123]
	s_waitcnt lgkmcnt(4)
	v_mfma_f32_16x16x32_f16 v[82:85], v[68:71], v[64:67], 0
	s_nop 2
	v_cvt_f16_f32_e32 v2, v58
	v_cvt_f16_f32_e32 v60, v60
	global_store_short v[0:1], v2, off
	v_subrev_u32_e32 v0, 63, v80
	v_xad_u32 v1, v102, -2, v172
	v_cvt_f16_f32_e32 v2, v59
	ds_read_b128 v[56:59], v223 offset:13888
	v_mfma_f32_16x16x32_f16 v[72:75], v[64:67], v[68:71], 0
	v_cndmask_b32_e64 v0, v1, v0, s[2:3]
	v_add_u32_e32 v0, v0, v151
	v_mad_i64_i32 v[0:1], s[26:27], v0, s88, v[122:123]
	s_waitcnt lgkmcnt(2)
	v_mfma_f32_16x16x32_f16 v[62:65], v[64:67], v[86:89], 0
	global_store_short v[0:1], v2, off
	v_subrev_u32_e32 v0, 62, v80
	v_xad_u32 v1, v102, -3, v172
	v_mfma_f32_16x16x32_f16 v[82:85], v[94:97], v[90:93], v[82:85]
	v_cndmask_b32_e64 v36, v1, v0, s[2:3]
	v_add_u32_e32 v36, v36, v151
	s_waitcnt lgkmcnt(1)
	v_mfma_f32_16x16x32_f16 v[68:71], v[76:79], v[68:71], 0
	v_mfma_f32_16x16x32_f16 v[86:89], v[76:79], v[86:89], 0
	s_nop 2
	v_cvt_f16_f32_e32 v1, v82
	v_cvt_f16_f32_e32 v2, v83
	v_cvt_f16_f32_e32 v66, v85
	v_mfma_f32_16x16x32_f16 v[72:75], v[90:93], v[94:97], v[72:75]
	s_nop 0
	v_cndmask_b32_e64 v66, 0, v66, s[22:23]
	s_waitcnt lgkmcnt(0)
	v_mfma_f32_16x16x32_f16 v[76:79], v[90:93], v[56:59], v[62:65]
	s_nop 0
	s_nop 2
	v_cndmask_b32_e64 v0, 0, v72, s[10:11]
	v_cndmask_b32_e64 v37, 0, v73, s[14:15]
	v_cvt_f16_f32_e32 v63, v84
	v_mfma_f32_16x16x32_f16 v[94:97], v[98:101], v[94:97], v[68:71]
	v_cndmask_b32_e64 v64, 0, v74, s[16:17]
	v_cndmask_b32_e64 v65, 0, v75, s[20:21]
	v_cndmask_b32_e64 v63, 0, v63, s[18:19]
	v_cndmask_b32_e64 v68, 0, v1, s[12:13]
	v_cndmask_b32_e64 v69, v2, 0, s[10:11]
	v_add_f32_e32 v62, v213, v0
	v_cvt_pk_f16_f32 v1, v64, v65
	v_cvt_pk_f16_f32 v0, v0, v37
	s_nop 0
	v_pack_b32_f16 v67, v63, v66
	v_pack_b32_f16 v66, v68, v69
	s_nop 0
	s_nop 0
	v_add_f32_e32 v63, v214, v37
	v_add_f32_e32 v64, v215, v64
	v_mfma_f32_16x16x16_f16 v[70:73], v[0:1], v[66:67], 0
	v_add_f32_e32 v65, v216, v65
	v_cvt_pk_f16_f32 v83, v64, v65
	v_cvt_pk_f16_f32 v82, v62, v63
	v_mfma_f32_16x16x16_f16 v[66:69], v[66:67], v[0:1], 0
	s_nop 0
	s_nop 2
	v_cvt_pk_f16_f32 v0, v70, v71
	s_nop 0
	s_nop 0
	v_cvt_pk_f16_f32 v1, v72, v73
	v_cvt_pk_f16_f32 v69, v68, v69
	v_cvt_pk_f16_f32 v68, v66, v67
	v_mfma_f32_16x16x16_f16 v[62:65], v[0:1], v[82:83], v[62:65]
	v_mad_i64_i32 v[36:37], s[26:27], v36, s88, v[122:123]
	global_store_short v[36:37], v60, off
	v_mfma_f32_16x16x16_f16 v[72:75], v[68:69], v[0:1], 0
	v_cvt_f16_f32_e32 v82, v61
	v_subrev_u32_e32 v36, 61, v80
	v_xad_u32 v37, v102, -4, v172
	v_mfma_f32_16x16x16_f16 v[66:69], v[0:1], v[68:69], 0
	s_nop 0
	v_cvt_pk_f16_f32 v71, v64, v65
	s_nop 1
	v_cvt_pk_f16_f32 v1, v74, v75
	v_cvt_pk_f16_f32 v0, v72, v73
	v_mfma_f32_16x16x32_f16 v[56:59], v[98:101], v[56:59], v[86:89]
	v_cvt_pk_f16_f32 v70, v62, v63
	s_nop 0
	s_nop 0
	v_cvt_pk_f16_f32 v85, v68, v69
	v_cvt_pk_f16_f32 v84, v66, v67
	s_nop 0
	s_nop 0
	v_mfma_f32_16x16x16_f16 v[88:91], v[0:1], v[70:71], v[62:65]
	ds_read2_b64 v[68:71], v224 offset1:4
	ds_read2_b64 v[72:75], v224 offset0:8 offset1:12
	v_cndmask_b32_e64 v36, v37, v36, s[2:3]
	v_mfma_f32_16x16x16_f16 v[60:63], v[84:85], v[0:1], 0
	v_add_u32_e32 v83, v36, v151
	s_nop 2
	v_cvt_pk_f16_f32 v1, v90, v91
	v_cvt_pk_f16_f32 v0, v88, v89
	v_cvt_pk_f16_f32 v67, v54, v55
	v_cvt_pk_f16_f32 v66, v52, v53
	v_cvt_pk_f16_f32 v85, v62, v63
	v_cvt_pk_f16_f32 v84, v60, v61
	v_cvt_pk_f16_f32 v63, v50, v51
	v_cvt_pk_f16_f32 v62, v48, v49
	v_cvt_pk_f16_f32 v61, v42, v43
	v_cvt_pk_f16_f32 v60, v40, v41
	v_cvt_pk_f16_f32 v65, v46, v47
	v_cvt_pk_f16_f32 v64, v44, v45
	s_waitcnt lgkmcnt(1)
	v_mfma_f32_16x16x32_f16 v[68:71], v[68:71], v[60:63], 0
	v_add_u32_e32 v36, 0x1000, v224
	s_nop 0
	v_cvt_f16_f32_e32 v76, v76
	s_waitcnt lgkmcnt(0)
	v_mfma_f32_16x16x32_f16 v[98:101], v[72:75], v[64:67], v[68:71]
	ds_read2_b64 v[72:75], v36 offset0:64 offset1:68
	s_nop 1
	ds_read2_b64 v[68:71], v36 offset0:72 offset1:76
	v_cvt_f16_f32_e32 v36, v97
	v_cvt_f16_f32_e32 v97, v77
	v_mfma_f32_16x16x16_f16 v[84:87], v[84:85], v[0:1], v[88:91]
	v_cvt_f16_f32_e32 v0, v94
	v_cvt_f16_f32_e32 v1, v95
	v_cvt_f16_f32_e32 v2, v96
	v_cndmask_b32_e64 v96, v76, 0, s[12:13]
	v_cndmask_b32_e64 v0, 0, v0, s[10:11]
	v_cndmask_b32_e64 v37, 0, v1, s[14:15]
	v_cndmask_b32_e64 v1, 0, v2, s[16:17]
	v_cndmask_b32_e64 v2, 0, v36, s[20:21]
	v_pack_b32_f16 v1, v1, v2
	v_pack_b32_f16 v0, v0, v37
	s_nop 0
	v_mov_b32_e32 v36, v38
	v_mov_b32_e32 v37, v39
	s_nop 0
	s_nop 0
	v_mov_b32_e32 v94, v3
	v_mov_b32_e32 v95, v3
	v_mfma_f32_16x16x16_f16 v[88:91], v[0:1], v[36:37], v[98:101]
	v_cvt_pk_f16_f32 v1, v86, v87
	v_cvt_pk_f16_f32 v0, v84, v85
	v_cvt_f16_f32_e32 v56, v56
	v_cvt_f16_f32_e32 v98, v78
	v_cvt_f16_f32_e32 v99, v79
	s_nop 2
	v_cvt_pk_f16_f32 v91, v90, v91
	v_cvt_pk_f16_f32 v90, v88, v89
	v_cndmask_b32_e64 v97, 0, v97, s[10:11]
	v_cndmask_b32_e64 v98, v98, 0, s[18:19]
	v_mfma_f32_16x16x16_f16 v[84:87], v[0:1], v[90:91], 0
	v_add_u32_e32 v2, 0x800, v233
	v_mov_b32_e32 v90, v3
	v_mov_b32_e32 v91, v3
	v_cndmask_b32_e64 v99, v99, 0, s[22:23]
	s_nop 3
	v_cvt_pk_f16_f32 v1, v86, v87
	v_cvt_pk_f16_f32 v0, v84, v85
	ds_read2_b64 v[84:87], v2 offset0:64 offset1:144
	ds_read_b128 v[76:79], v178 offset:256
	ds_read_b64 v[88:89], v225 offset:5120
	s_nop 0
	s_waitcnt lgkmcnt(2)
	v_mov_b32_e32 v92, v84
	v_mov_b32_e32 v93, v85
	s_waitcnt lgkmcnt(1)
	v_pk_mul_f32 v[42:43], v[42:43], v[78:79]
	v_pk_mul_f32 v[40:41], v[40:41], v[76:77]
	ds_read_b128 v[76:79], v178 offset:320
	ds_read_b64 v[84:85], v226 offset:5120
	v_mfma_f32_16x16x16_f16 v[40:43], v[92:93], v[0:1], v[40:43]
	s_waitcnt lgkmcnt(1)
	v_pk_mul_f32 v[48:49], v[48:49], v[76:77]
	v_add_u32_e32 v76, 0xc00, v233
	v_mfma_f32_16x16x16_f16 v[40:43], v[88:89], v[36:37], v[40:43]
	v_mov_b32_e32 v88, v86
	v_mov_b32_e32 v89, v87
	v_pk_mul_f32 v[50:51], v[50:51], v[78:79]
	s_nop 0
	s_nop 0
	ds_read2_b64 v[76:79], v76 offset0:96 offset1:176
	v_mfma_f32_16x16x16_f16 v[48:51], v[88:89], v[0:1], v[48:51]
	s_waitcnt lgkmcnt(0)
	v_mov_b32_e32 v92, v76
	v_mfma_f32_16x16x16_f16 v[48:51], v[84:85], v[36:37], v[48:51]
	ds_read_b128 v[84:87], v178 offset:384
	ds_read_b64 v[88:89], v227 offset:5120
	v_mov_b32_e32 v93, v77
	v_pack_b32_f16 v76, v96, v97
	v_cndmask_b32_e64 v96, v56, 0, s[12:13]
	s_waitcnt lgkmcnt(1)
	v_pk_mul_f32 v[46:47], v[46:47], v[86:87]
	v_pk_mul_f32 v[44:45], v[44:45], v[84:85]
	v_cvt_f16_f32_e32 v56, v57
	v_cvt_f16_f32_e32 v57, v58
	v_mfma_f32_16x16x16_f16 v[44:47], v[92:93], v[0:1], v[44:47]
	v_cvt_f16_f32_e32 v58, v59
	v_mov_b32_e32 v92, v78
	v_mov_b32_e32 v93, v79
	s_waitcnt lgkmcnt(0)
	v_mfma_f32_16x16x16_f16 v[44:47], v[88:89], v[36:37], v[44:47]
	ds_read_b128 v[84:87], v178 offset:448
	ds_read_b64 v[88:89], v228 offset:5120
	v_cndmask_b32_e64 v78, v57, 0, s[18:19]
	v_cndmask_b32_e64 v79, v58, 0, s[22:23]
	v_pack_b32_f16 v77, v98, v99
	s_waitcnt lgkmcnt(1)
	v_pk_mul_f32 v[52:53], v[52:53], v[84:85]
	v_cndmask_b32_e64 v84, 0, v56, s[10:11]
	v_mfma_f32_16x16x32_f16 v[56:59], v[72:75], v[60:63], 0
	v_pack_b32_f16 v61, v78, v79
	v_mov_b32_e32 v78, v3
	v_mov_b32_e32 v79, v3
	v_mfma_f32_16x16x32_f16 v[56:59], v[68:71], v[64:67], v[56:59]
	v_mul_f32_e64 v54, v54, v86
	v_mul_f32_e64 v55, v55, v87
	v_pack_b32_f16 v60, v96, v84
	v_mov_b32_e32 v62, v3
	v_mov_b32_e32 v63, v3
	v_mfma_f32_16x16x16_f16 v[52:55], v[92:93], v[0:1], v[52:55]
	v_mfma_f32_16x16x16_f16 v[56:59], v[76:77], v[0:1], v[56:59]
	v_mad_i64_i32 v[0:1], s[26:27], v83, s88, v[122:123]
	global_store_short v[0:1], v82, off
	s_waitcnt lgkmcnt(0)
	v_mfma_f32_16x16x16_f16 v[52:55], v[88:89], v[36:37], v[52:55]
	v_subrev_u32_e32 v0, 48, v80
	v_add_u32_e32 v1, 0x7ef, v81
	v_cndmask_b32_e64 v0, v1, v0, s[2:3]
	v_mfma_f32_16x16x16_f16 v[36:39], v[60:61], v[36:37], v[56:59]
	v_add_u32_e32 v0, v0, v151
	v_mad_i64_i32 v[0:1], s[26:27], v0, s88, v[122:123]
	s_nop 5
	v_cvt_f16_f32_e32 v2, v36
	global_store_short v[0:1], v2, off
	v_subrev_u32_e32 v0, 47, v80
	v_add_u32_e32 v1, 0x7ee, v81
	v_cvt_f16_f32_e32 v2, v37
	v_cndmask_b32_e64 v0, v1, v0, s[2:3]
	v_add_u32_e32 v0, v0, v151
	v_mad_i64_i32 v[0:1], s[26:27], v0, s88, v[122:123]
	global_store_short v[0:1], v2, off
	v_subrev_u32_e32 v0, 46, v80
	v_add_u32_e32 v1, 0x7ed, v81
	v_cvt_f16_f32_e32 v2, v38
	v_cndmask_b32_e64 v0, v1, v0, s[2:3]
	v_add_u32_e32 v0, v0, v151
	v_mad_i64_i32 v[0:1], s[26:27], v0, s88, v[122:123]
	global_store_short v[0:1], v2, off
	v_subrev_u32_e32 v0, 45, v80
	v_add_u32_e32 v1, 0x7ec, v81
	v_cndmask_b32_e64 v0, v1, v0, s[2:3]
	v_cvt_f16_f32_e32 v2, v39
	v_add_u32_e32 v0, v0, v151
	v_mad_i64_i32 v[0:1], s[26:27], v0, s88, v[122:123]
	s_mov_b64 s[26:27], 0
	global_store_short v[0:1], v2, off

.LBB0_1041:
	v_cmp_lt_i32_e32 vcc, 2, v174
	s_and_saveexec_b64 s[28:29], vcc
	s_xor_b64 s[28:29], exec, s[28:29]
	s_cbranch_execz .LBB0_1043
	v_lshl_add_u32 v251, v204, 1, v2
	v_lshl_add_u32 v250, v206, 1, v2
	ds_read2st64_b32 v[36:37], v251 offset0:64 offset1:80
	ds_read2st64_b32 v[46:47], v251 offset0:96 offset1:112
	ds_read_b32 v60, v251 offset:32768
	ds_read2st64_b32 v[126:127], v250 offset0:64 offset1:80
	ds_read2st64_b32 v[128:129], v250 offset0:96 offset1:112
	ds_read_b32 v61, v250 offset:32768
	v_lshl_add_u32 v48, v204, 1, v2
	s_nop 0
	s_nop 0
	v_rcp_f32_e32 v44, v62
	v_rcp_f32_e32 v45, v63
	v_lshl_add_u32 v251, v208, 1, v2
	ds_read2st64_b32 v[130:131], v251 offset0:64 offset1:80
	s_waitcnt lgkmcnt(5)
	v_cvt_f32_f16_e32 v58, v47
	v_cvt_f32_f16_e32 v50, v37
	v_cvt_f32_f16_sdwa v51, v37 dst_sel:DWORD dst_unused:UNUSED_PAD src0_sel:WORD_1
	ds_read2st64_b32 v[132:133], v251 offset0:96 offset1:112
	v_cvt_f32_f16_sdwa v59, v47 dst_sel:DWORD dst_unused:UNUSED_PAD src0_sel:WORD_1
	v_cvt_f32_f16_e32 v48, v36
	v_cvt_f32_f16_e32 v54, v46
	v_cvt_f32_f16_sdwa v55, v46 dst_sel:DWORD dst_unused:UNUSED_PAD src0_sel:WORD_1
	v_cvt_f32_f16_sdwa v49, v36 dst_sel:DWORD dst_unused:UNUSED_PAD src0_sel:WORD_1
	v_pk_mul_f32 v[36:37], v[42:43], v[50:51]
	v_pk_mul_f32 v[42:43], v[62:63], v[58:59]
	v_pk_mul_f32 v[46:47], v[44:45], v[54:55]
	v_pk_mul_f32 v[44:45], v[44:45], v[48:49]
	v_pk_mul_f32 v[48:49], v[40:41], v[36:37]
	v_pk_mul_f32 v[50:51], v[40:41], v[42:43]
	v_cvt_pk_f16_f32 v36, v36, v37
	v_cvt_pk_f16_f32 v37, v42, v43
	v_pk_mul_f32 v[54:55], v[38:39], v[46:47]
	v_pk_mul_f32 v[58:59], v[38:39], v[44:45]
	ds_write2st64_b32 v205, v36, v37 offset1:18
	v_cvt_pk_f16_f32 v36, v48, v49
	v_cvt_pk_f16_f32 v37, v50, v51
	v_pk_mul_f32 v[46:47], v[0:1], v[46:47]
	ds_write2st64_b32 v205, v36, v37 offset0:36 offset1:54
	v_cvt_pk_f16_f32 v36, v54, v55
	v_cvt_pk_f16_f32 v37, v58, v59
	ds_write2st64_b32 v205, v36, v37 offset0:72 offset1:90
	v_cvt_f16_f32_e32 v36, v46
	v_pk_mul_f32 v[44:45], v[0:1], v[44:45]
	v_cvt_f16_f32_e32 v37, v47
	v_cvt_f16_f32_e32 v42, v44
	v_cvt_f16_f32_e32 v43, v45
	ds_write_b16 v176, v36 offset:24
	ds_write_b16 v176, v37 offset:64
	ds_write_b16 v176, v42 offset:5144
	ds_write_b16 v176, v43 offset:5184
	s_waitcnt lgkmcnt(12)
	ds_write_b16 v176, v60 offset:10264
	v_lshl_add_u32 v46, v206, 1, v2
	v_rcp_f32_e32 v42, v56
	v_rcp_f32_e32 v43, v57
	s_waitcnt lgkmcnt(12)
	v_cvt_f32_f16_e32 v48, v127
	v_cvt_f32_f16_sdwa v49, v127 dst_sel:DWORD dst_unused:UNUSED_PAD src0_sel:WORD_1
	s_waitcnt lgkmcnt(11)
	v_cvt_f32_f16_e32 v54, v129
	v_cvt_f32_f16_sdwa v55, v129 dst_sel:DWORD dst_unused:UNUSED_PAD src0_sel:WORD_1
	v_cvt_f32_f16_e32 v46, v126
	v_cvt_f32_f16_e32 v50, v128
	v_cvt_f32_f16_sdwa v51, v128 dst_sel:DWORD dst_unused:UNUSED_PAD src0_sel:WORD_1
	v_cvt_f32_f16_sdwa v47, v126 dst_sel:DWORD dst_unused:UNUSED_PAD src0_sel:WORD_1
	v_pk_mul_f32 v[36:37], v[62:63], v[48:49]
	v_pk_mul_f32 v[44:45], v[56:57], v[54:55]
	v_pk_mul_f32 v[48:49], v[42:43], v[50:51]
	v_pk_mul_f32 v[42:43], v[42:43], v[46:47]
	v_pk_mul_f32 v[46:47], v[40:41], v[36:37]
	v_pk_mul_f32 v[50:51], v[40:41], v[44:45]
	v_cvt_pk_f16_f32 v36, v36, v37
	v_cvt_pk_f16_f32 v37, v44, v45
	v_pk_mul_f32 v[54:55], v[38:39], v[48:49]
	v_pk_mul_f32 v[58:59], v[38:39], v[42:43]
	ds_write2st64_b32 v207, v36, v37 offset1:18
	v_cvt_pk_f16_f32 v36, v46, v47
	v_cvt_pk_f16_f32 v37, v50, v51
	v_pk_mul_f32 v[48:49], v[0:1], v[48:49]
	ds_write2st64_b32 v207, v36, v37 offset0:36 offset1:54
	v_cvt_pk_f16_f32 v36, v54, v55
	v_cvt_pk_f16_f32 v37, v58, v59
	v_lshl_add_u32 v250, v210, 1, v2
	ds_read_b32 v58, v251 offset:32768
	ds_read2st64_b32 v[134:135], v250 offset0:64 offset1:80
	s_waitcnt lgkmcnt(14)
	ds_read2st64_b32 v[136:137], v250 offset0:96 offset1:112
	s_waitcnt lgkmcnt(14)
	ds_write2st64_b32 v207, v36, v37 offset0:72 offset1:90
	v_cvt_f16_f32_e32 v36, v48
	v_pk_mul_f32 v[42:43], v[0:1], v[42:43]
	v_cvt_f16_f32_e32 v37, v49
	v_cvt_f16_f32_e32 v42, v42
	v_cvt_f16_f32_e32 v43, v43
	s_waitcnt lgkmcnt(14)
	ds_write_b16 v176, v36 offset:26
	s_waitcnt lgkmcnt(14)
	ds_write_b16 v176, v37 offset:66
	s_waitcnt lgkmcnt(14)
	ds_write_b16 v176, v42 offset:5146
	s_waitcnt lgkmcnt(14)
	ds_write_b16 v176, v43 offset:5186
	s_waitcnt lgkmcnt(14)
	ds_write_b16 v176, v61 offset:10266
	v_lshl_add_u32 v46, v208, 1, v2
	v_rcp_f32_e32 v42, v52
	v_rcp_f32_e32 v43, v53
	v_lshl_add_u32 v2, v210, 1, v2
	v_cvt_f32_f16_e32 v48, v131
	v_cvt_f32_f16_sdwa v49, v131 dst_sel:DWORD dst_unused:UNUSED_PAD src0_sel:WORD_1
	v_cvt_f32_f16_e32 v54, v133
	v_cvt_f32_f16_sdwa v55, v133 dst_sel:DWORD dst_unused:UNUSED_PAD src0_sel:WORD_1
	v_cvt_f32_f16_e32 v46, v130
	v_cvt_f32_f16_e32 v50, v132
	v_cvt_f32_f16_sdwa v51, v132 dst_sel:DWORD dst_unused:UNUSED_PAD src0_sel:WORD_1
	v_cvt_f32_f16_sdwa v47, v130 dst_sel:DWORD dst_unused:UNUSED_PAD src0_sel:WORD_1
	v_pk_mul_f32 v[36:37], v[56:57], v[48:49]
	v_pk_mul_f32 v[44:45], v[52:53], v[54:55]
	v_pk_mul_f32 v[48:49], v[42:43], v[50:51]
	v_pk_mul_f32 v[42:43], v[42:43], v[46:47]
	v_pk_mul_f32 v[46:47], v[40:41], v[36:37]
	v_pk_mul_f32 v[50:51], v[40:41], v[44:45]
	v_cvt_pk_f16_f32 v36, v36, v37
	v_cvt_pk_f16_f32 v37, v44, v45
	v_pk_mul_f32 v[54:55], v[38:39], v[48:49]
	v_pk_mul_f32 v[56:57], v[38:39], v[42:43]
	s_waitcnt lgkmcnt(14)
	ds_write2st64_b32 v209, v36, v37 offset1:18
	v_cvt_pk_f16_f32 v36, v46, v47
	v_cvt_pk_f16_f32 v37, v50, v51
	v_pk_mul_f32 v[48:49], v[0:1], v[48:49]
	s_waitcnt lgkmcnt(14)
	ds_write2st64_b32 v209, v36, v37 offset0:36 offset1:54
	v_cvt_pk_f16_f32 v36, v54, v55
	v_cvt_pk_f16_f32 v37, v56, v57
	s_waitcnt lgkmcnt(14)
	ds_write2st64_b32 v209, v36, v37 offset0:72 offset1:90
	v_cvt_f16_f32_e32 v36, v48
	v_pk_mul_f32 v[42:43], v[0:1], v[42:43]
	v_cvt_f16_f32_e32 v37, v49
	v_cvt_f16_f32_e32 v42, v42
	v_cvt_f16_f32_e32 v43, v43
	s_waitcnt lgkmcnt(14)
	ds_write_b16 v176, v36 offset:28
	s_waitcnt lgkmcnt(14)
	ds_write_b16 v176, v37 offset:68
	s_waitcnt lgkmcnt(14)
	ds_write_b16 v176, v42 offset:5148
	s_waitcnt lgkmcnt(14)
	ds_write_b16 v176, v43 offset:5188
	s_waitcnt lgkmcnt(14)
	ds_write_b16 v176, v58 offset:10268
	s_waitcnt lgkmcnt(14)
	ds_read_b32 v2, v250 offset:32768
	v_rcp_f32_e32 v42, v0
	v_rcp_f32_e32 v43, v1
	v_cvt_f32_f16_e32 v48, v135
	v_cvt_f32_f16_sdwa v49, v135 dst_sel:DWORD dst_unused:UNUSED_PAD src0_sel:WORD_1
	v_cvt_f32_f16_e32 v54, v137
	v_cvt_f32_f16_sdwa v55, v137 dst_sel:DWORD dst_unused:UNUSED_PAD src0_sel:WORD_1
	v_cvt_f32_f16_e32 v46, v134
	v_cvt_f32_f16_e32 v50, v136
	v_cvt_f32_f16_sdwa v51, v136 dst_sel:DWORD dst_unused:UNUSED_PAD src0_sel:WORD_1
	v_cvt_f32_f16_sdwa v47, v134 dst_sel:DWORD dst_unused:UNUSED_PAD src0_sel:WORD_1
	v_pk_mul_f32 v[36:37], v[52:53], v[48:49]
	v_pk_mul_f32 v[44:45], v[0:1], v[54:55]
	v_pk_mul_f32 v[48:49], v[42:43], v[50:51]
	v_pk_mul_f32 v[42:43], v[42:43], v[46:47]
	v_pk_mul_f32 v[46:47], v[40:41], v[36:37]
	v_pk_mul_f32 v[40:41], v[40:41], v[44:45]
	v_cvt_pk_f16_f32 v36, v36, v37
	v_cvt_pk_f16_f32 v37, v44, v45
	v_pk_mul_f32 v[50:51], v[38:39], v[48:49]
	v_pk_mul_f32 v[38:39], v[38:39], v[42:43]
	s_waitcnt lgkmcnt(14)
	ds_write2st64_b32 v211, v36, v37 offset1:18
	v_cvt_pk_f16_f32 v36, v46, v47
	v_cvt_pk_f16_f32 v37, v40, v41
	v_pk_mul_f32 v[48:49], v[0:1], v[48:49]
	s_waitcnt lgkmcnt(14)
	ds_write2st64_b32 v211, v36, v37 offset0:36 offset1:54
	v_cvt_pk_f16_f32 v36, v50, v51
	v_cvt_pk_f16_f32 v37, v38, v39
	s_waitcnt lgkmcnt(14)
	ds_write2st64_b32 v211, v36, v37 offset0:72 offset1:90
	v_cvt_f16_f32_e32 v36, v48
	v_pk_mul_f32 v[42:43], v[0:1], v[42:43]
	v_cvt_f16_f32_e32 v37, v49
	v_cvt_f16_f32_e32 v38, v42
	v_cvt_f16_f32_e32 v39, v43
	s_waitcnt lgkmcnt(14)
	ds_write_b16 v176, v36 offset:30
	s_waitcnt lgkmcnt(14)
	ds_write_b16 v176, v37 offset:70
	s_waitcnt lgkmcnt(14)
	ds_write_b16 v176, v38 offset:5150
	s_waitcnt lgkmcnt(14)
	ds_write_b16 v176, v39 offset:5190
	s_nop 0
	s_waitcnt lgkmcnt(7)
	ds_write_b16 v176, v2 offset:10270
	v_perm_b32 v36, v61, v60, s35
	v_perm_b32 v37, v2, v58, s35
	ds_write_b64 v176, v[36:37] offset:10304
.LBB0_1043:
	s_andn2_saveexec_b64 s[28:29], s[28:29]
	s_cbranch_execz .LBB0_1045
	v_lshl_add_u32 v251, v196, 1, v2
	v_lshl_add_u32 v250, v198, 1, v2
	ds_read2st64_b32 v[36:37], v251 offset0:64 offset1:80
	ds_read2st64_b32 v[48:49], v251 offset0:96 offset1:112
	ds_read_b32 v64, v251 offset:32768
	ds_read2st64_b32 v[126:127], v250 offset0:64 offset1:80
	ds_read2st64_b32 v[128:129], v250 offset0:96 offset1:112
	v_lshl_add_u32 v52, v196, 1, v2
	s_nop 0
	s_nop 0
	s_nop 0
	v_rcp_f32_e32 v44, v58
	v_rcp_f32_e32 v45, v59
	s_waitcnt lgkmcnt(3)
	v_cvt_f32_f16_e32 v60, v49
	v_cvt_f32_f16_e32 v54, v37
	v_cvt_f32_f16_sdwa v55, v37 dst_sel:DWORD dst_unused:UNUSED_PAD src0_sel:WORD_1
	v_cvt_f32_f16_sdwa v61, v49 dst_sel:DWORD dst_unused:UNUSED_PAD src0_sel:WORD_1
	v_cvt_f32_f16_e32 v52, v36
	v_cvt_f32_f16_e32 v56, v48
	v_cvt_f32_f16_sdwa v57, v48 dst_sel:DWORD dst_unused:UNUSED_PAD src0_sel:WORD_1
	v_cvt_f32_f16_sdwa v53, v36 dst_sel:DWORD dst_unused:UNUSED_PAD src0_sel:WORD_1
	v_pk_mul_f32 v[36:37], v[38:39], v[54:55]
	v_pk_mul_f32 v[48:49], v[58:59], v[60:61]
	v_pk_mul_f32 v[54:55], v[44:45], v[56:57]
	v_pk_mul_f32 v[44:45], v[44:45], v[52:53]
	v_pk_mul_f32 v[52:53], v[40:41], v[36:37]
	v_pk_mul_f32 v[56:57], v[40:41], v[48:49]
	v_cvt_pk_f16_f32 v36, v36, v37
	v_cvt_pk_f16_f32 v37, v48, v49
	v_pk_mul_f32 v[60:61], v[38:39], v[54:55]
	v_pk_mul_f32 v[62:63], v[38:39], v[44:45]
	ds_write2st64_b32 v197, v36, v37 offset1:18
	v_cvt_pk_f16_f32 v36, v52, v53
	v_cvt_pk_f16_f32 v37, v56, v57
	v_pk_mul_f32 v[54:55], v[0:1], v[54:55]
	ds_write2st64_b32 v197, v36, v37 offset0:36 offset1:54
	v_cvt_pk_f16_f32 v36, v60, v61
	v_cvt_pk_f16_f32 v37, v62, v63
	v_lshl_add_u32 v251, v200, 1, v2
	ds_read_b32 v62, v250 offset:32768
	ds_read2st64_b32 v[130:131], v251 offset0:64 offset1:80
	ds_read2st64_b32 v[132:133], v251 offset0:96 offset1:112
	ds_write2st64_b32 v197, v36, v37 offset0:72 offset1:90
	v_cvt_f16_f32_e32 v36, v54
	v_pk_mul_f32 v[44:45], v[0:1], v[44:45]
	v_cvt_f16_f32_e32 v37, v55
	v_cvt_f16_f32_e32 v44, v44
	v_cvt_f16_f32_e32 v45, v45
	ds_write_b16 v176, v36 offset:16
	ds_write_b16 v176, v37 offset:56
	ds_write_b16 v176, v44 offset:5136
	ds_write_b16 v176, v45 offset:5176
	s_waitcnt lgkmcnt(12)
	ds_write_b16 v176, v64 offset:10256
	v_lshl_add_u32 v52, v198, 1, v2
	v_rcp_f32_e32 v44, v50
	v_rcp_f32_e32 v45, v51
	s_waitcnt lgkmcnt(12)
	v_cvt_f32_f16_e32 v54, v127
	v_cvt_f32_f16_sdwa v55, v127 dst_sel:DWORD dst_unused:UNUSED_PAD src0_sel:WORD_1
	s_waitcnt lgkmcnt(11)
	v_cvt_f32_f16_e32 v60, v129
	v_cvt_f32_f16_sdwa v61, v129 dst_sel:DWORD dst_unused:UNUSED_PAD src0_sel:WORD_1
	v_cvt_f32_f16_e32 v52, v126
	v_cvt_f32_f16_e32 v56, v128
	v_cvt_f32_f16_sdwa v57, v128 dst_sel:DWORD dst_unused:UNUSED_PAD src0_sel:WORD_1
	v_cvt_f32_f16_sdwa v53, v126 dst_sel:DWORD dst_unused:UNUSED_PAD src0_sel:WORD_1
	v_pk_mul_f32 v[36:37], v[58:59], v[54:55]
	v_pk_mul_f32 v[48:49], v[50:51], v[60:61]
	v_pk_mul_f32 v[54:55], v[44:45], v[56:57]
	v_pk_mul_f32 v[44:45], v[44:45], v[52:53]
	v_pk_mul_f32 v[52:53], v[40:41], v[36:37]
	v_pk_mul_f32 v[56:57], v[40:41], v[48:49]
	v_cvt_pk_f16_f32 v36, v36, v37
	v_cvt_pk_f16_f32 v37, v48, v49
	v_pk_mul_f32 v[58:59], v[38:39], v[54:55]
	v_pk_mul_f32 v[60:61], v[38:39], v[44:45]
	ds_write2st64_b32 v199, v36, v37 offset1:18
	v_cvt_pk_f16_f32 v36, v52, v53
	v_cvt_pk_f16_f32 v37, v56, v57
	v_pk_mul_f32 v[54:55], v[0:1], v[54:55]
	ds_write2st64_b32 v199, v36, v37 offset0:36 offset1:54
	v_cvt_pk_f16_f32 v36, v58, v59
	v_cvt_pk_f16_f32 v37, v60, v61
	v_lshl_add_u32 v250, v202, 1, v2
	ds_read_b32 v60, v251 offset:32768
	ds_read2st64_b32 v[134:135], v250 offset0:64 offset1:80
	s_waitcnt lgkmcnt(14)
	ds_read2st64_b32 v[136:137], v250 offset0:96 offset1:112
	s_waitcnt lgkmcnt(14)
	ds_write2st64_b32 v199, v36, v37 offset0:72 offset1:90
	v_cvt_f16_f32_e32 v36, v54
	v_pk_mul_f32 v[44:45], v[0:1], v[44:45]
	v_cvt_f16_f32_e32 v37, v55
	v_cvt_f16_f32_e32 v44, v44
	v_cvt_f16_f32_e32 v45, v45
	s_waitcnt lgkmcnt(14)
	ds_write_b16 v176, v36 offset:18
	s_waitcnt lgkmcnt(14)
	ds_write_b16 v176, v37 offset:58
	s_waitcnt lgkmcnt(14)
	ds_write_b16 v176, v44 offset:5138
	s_waitcnt lgkmcnt(14)
	ds_write_b16 v176, v45 offset:5178
	s_waitcnt lgkmcnt(14)
	ds_write_b16 v176, v62 offset:10258
	v_lshl_add_u32 v52, v200, 1, v2
	v_rcp_f32_e32 v44, v46
	v_rcp_f32_e32 v45, v47
	v_lshl_add_u32 v2, v202, 1, v2
	v_cvt_f32_f16_e32 v54, v131
	v_cvt_f32_f16_sdwa v55, v131 dst_sel:DWORD dst_unused:UNUSED_PAD src0_sel:WORD_1
	v_cvt_f32_f16_e32 v58, v133
	v_cvt_f32_f16_sdwa v59, v133 dst_sel:DWORD dst_unused:UNUSED_PAD src0_sel:WORD_1
	v_cvt_f32_f16_e32 v52, v130
	v_cvt_f32_f16_e32 v56, v132
	v_cvt_f32_f16_sdwa v57, v132 dst_sel:DWORD dst_unused:UNUSED_PAD src0_sel:WORD_1
	v_cvt_f32_f16_sdwa v53, v130 dst_sel:DWORD dst_unused:UNUSED_PAD src0_sel:WORD_1
	v_pk_mul_f32 v[36:37], v[50:51], v[54:55]
	v_pk_mul_f32 v[48:49], v[46:47], v[58:59]
	v_pk_mul_f32 v[50:51], v[44:45], v[56:57]
	v_pk_mul_f32 v[44:45], v[44:45], v[52:53]
	v_pk_mul_f32 v[52:53], v[40:41], v[36:37]
	v_pk_mul_f32 v[54:55], v[40:41], v[48:49]
	v_cvt_pk_f16_f32 v36, v36, v37
	v_cvt_pk_f16_f32 v37, v48, v49
	v_pk_mul_f32 v[56:57], v[38:39], v[50:51]
	v_pk_mul_f32 v[58:59], v[38:39], v[44:45]
	s_waitcnt lgkmcnt(14)
	ds_write2st64_b32 v201, v36, v37 offset1:18
	v_cvt_pk_f16_f32 v36, v52, v53
	v_cvt_pk_f16_f32 v37, v54, v55
	v_pk_mul_f32 v[50:51], v[0:1], v[50:51]
	s_waitcnt lgkmcnt(14)
	ds_write2st64_b32 v201, v36, v37 offset0:36 offset1:54
	v_cvt_pk_f16_f32 v36, v56, v57
	v_cvt_pk_f16_f32 v37, v58, v59
	s_waitcnt lgkmcnt(14)
	ds_write2st64_b32 v201, v36, v37 offset0:72 offset1:90
	v_cvt_f16_f32_e32 v36, v50
	v_pk_mul_f32 v[44:45], v[0:1], v[44:45]
	v_cvt_f16_f32_e32 v37, v51
	v_cvt_f16_f32_e32 v44, v44
	v_cvt_f16_f32_e32 v45, v45
	s_waitcnt lgkmcnt(14)
	ds_write_b16 v176, v36 offset:20
	s_waitcnt lgkmcnt(14)
	ds_write_b16 v176, v37 offset:60
	s_waitcnt lgkmcnt(14)
	ds_write_b16 v176, v44 offset:5140
	s_waitcnt lgkmcnt(14)
	ds_write_b16 v176, v45 offset:5180
	s_waitcnt lgkmcnt(14)
	ds_write_b16 v176, v60 offset:10260
	s_waitcnt lgkmcnt(14)
	ds_read_b32 v2, v250 offset:32768
	v_rcp_f32_e32 v44, v42
	v_rcp_f32_e32 v45, v43
	v_cvt_f32_f16_e32 v52, v135
	v_cvt_f32_f16_sdwa v53, v135 dst_sel:DWORD dst_unused:UNUSED_PAD src0_sel:WORD_1
	v_cvt_f32_f16_e32 v56, v137
	v_cvt_f32_f16_sdwa v57, v137 dst_sel:DWORD dst_unused:UNUSED_PAD src0_sel:WORD_1
	v_cvt_f32_f16_e32 v50, v134
	v_cvt_f32_f16_e32 v54, v136
	v_cvt_f32_f16_sdwa v55, v136 dst_sel:DWORD dst_unused:UNUSED_PAD src0_sel:WORD_1
	v_cvt_f32_f16_sdwa v51, v134 dst_sel:DWORD dst_unused:UNUSED_PAD src0_sel:WORD_1
	v_pk_mul_f32 v[36:37], v[46:47], v[52:53]
	v_pk_mul_f32 v[42:43], v[42:43], v[56:57]
	v_pk_mul_f32 v[46:47], v[44:45], v[54:55]
	v_pk_mul_f32 v[44:45], v[44:45], v[50:51]
	v_pk_mul_f32 v[48:49], v[40:41], v[36:37]
	v_pk_mul_f32 v[40:41], v[40:41], v[42:43]
	v_cvt_pk_f16_f32 v36, v36, v37
	v_cvt_pk_f16_f32 v37, v42, v43
	v_pk_mul_f32 v[50:51], v[38:39], v[46:47]
	v_pk_mul_f32 v[38:39], v[38:39], v[44:45]
	s_waitcnt lgkmcnt(14)
	ds_write2st64_b32 v203, v36, v37 offset1:18
	v_cvt_pk_f16_f32 v36, v48, v49
	v_cvt_pk_f16_f32 v37, v40, v41
	v_pk_mul_f32 v[46:47], v[0:1], v[46:47]
	s_waitcnt lgkmcnt(14)
	ds_write2st64_b32 v203, v36, v37 offset0:36 offset1:54
	v_cvt_pk_f16_f32 v36, v50, v51
	v_cvt_pk_f16_f32 v37, v38, v39
	s_waitcnt lgkmcnt(14)
	ds_write2st64_b32 v203, v36, v37 offset0:72 offset1:90
	v_cvt_f16_f32_e32 v36, v46
	v_pk_mul_f32 v[44:45], v[0:1], v[44:45]
	v_cvt_f16_f32_e32 v37, v47
	v_cvt_f16_f32_e32 v38, v44
	v_cvt_f16_f32_e32 v39, v45
	s_waitcnt lgkmcnt(14)
	ds_write_b16 v176, v36 offset:22
	s_waitcnt lgkmcnt(14)
	ds_write_b16 v176, v37 offset:62
	s_waitcnt lgkmcnt(14)
	ds_write_b16 v176, v38 offset:5142
	s_waitcnt lgkmcnt(14)
	ds_write_b16 v176, v39 offset:5182
	s_nop 0
	s_waitcnt lgkmcnt(7)
	ds_write_b16 v176, v2 offset:10262
	v_perm_b32 v36, v62, v64, s35
	v_perm_b32 v37, v2, v60, s35
	ds_write_b64 v176, v[36:37] offset:10296

.LBB0_1046:
	v_cmp_eq_u32_e32 vcc, 1, v174
	s_and_saveexec_b64 s[28:29], vcc
	s_cbranch_execz .LBB0_1048
	v_lshl_add_u32 v251, v188, 1, v2
	v_lshl_add_u32 v250, v190, 1, v2
	ds_read2st64_b32 v[36:37], v251 offset0:64 offset1:80
	ds_read2st64_b32 v[46:47], v251 offset0:96 offset1:112
	ds_read_b32 v62, v251 offset:32768
	ds_read2st64_b32 v[126:127], v250 offset0:64 offset1:80
	ds_read2st64_b32 v[128:129], v250 offset0:96 offset1:112
	v_lshl_add_u32 v50, v188, 1, v2
	s_nop 0
	s_nop 0
	s_nop 0
	v_rcp_f32_e32 v42, v54
	v_rcp_f32_e32 v43, v55
	s_waitcnt lgkmcnt(3)
	v_cvt_f32_f16_e32 v58, v47
	v_cvt_f32_f16_e32 v52, v37
	v_cvt_f32_f16_sdwa v53, v37 dst_sel:DWORD dst_unused:UNUSED_PAD src0_sel:WORD_1
	v_cvt_f32_f16_sdwa v59, v47 dst_sel:DWORD dst_unused:UNUSED_PAD src0_sel:WORD_1
	v_cvt_f32_f16_e32 v50, v36
	v_cvt_f32_f16_e32 v56, v46
	v_cvt_f32_f16_sdwa v57, v46 dst_sel:DWORD dst_unused:UNUSED_PAD src0_sel:WORD_1
	v_cvt_f32_f16_sdwa v51, v36 dst_sel:DWORD dst_unused:UNUSED_PAD src0_sel:WORD_1
	v_pk_mul_f32 v[36:37], v[60:61], v[52:53]
	v_pk_mul_f32 v[46:47], v[54:55], v[58:59]
	v_pk_mul_f32 v[52:53], v[42:43], v[56:57]
	v_pk_mul_f32 v[42:43], v[42:43], v[50:51]
	v_pk_mul_f32 v[50:51], v[40:41], v[36:37]
	v_pk_mul_f32 v[56:57], v[40:41], v[46:47]
	v_cvt_pk_f16_f32 v36, v36, v37
	v_cvt_pk_f16_f32 v37, v46, v47
	v_pk_mul_f32 v[58:59], v[38:39], v[52:53]
	v_pk_mul_f32 v[60:61], v[38:39], v[42:43]
	ds_write2st64_b32 v189, v36, v37 offset1:18
	v_cvt_pk_f16_f32 v36, v50, v51
	v_cvt_pk_f16_f32 v37, v56, v57
	v_pk_mul_f32 v[52:53], v[0:1], v[52:53]
	ds_write2st64_b32 v189, v36, v37 offset0:36 offset1:54
	v_cvt_pk_f16_f32 v36, v58, v59
	v_cvt_pk_f16_f32 v37, v60, v61
	v_lshl_add_u32 v251, v192, 1, v2
	ds_read_b32 v60, v250 offset:32768
	ds_read2st64_b32 v[130:131], v251 offset0:64 offset1:80
	ds_read2st64_b32 v[132:133], v251 offset0:96 offset1:112
	ds_write2st64_b32 v189, v36, v37 offset0:72 offset1:90
	v_cvt_f16_f32_e32 v36, v52
	v_pk_mul_f32 v[42:43], v[0:1], v[42:43]
	v_cvt_f16_f32_e32 v37, v53
	v_cvt_f16_f32_e32 v42, v42
	v_cvt_f16_f32_e32 v43, v43
	ds_write_b16 v176, v36 offset:8
	ds_write_b16 v176, v37 offset:48
	ds_write_b16 v176, v42 offset:5128
	ds_write_b16 v176, v43 offset:5168
	s_waitcnt lgkmcnt(12)
	ds_write_b16 v176, v62 offset:10248
	v_lshl_add_u32 v50, v190, 1, v2
	v_rcp_f32_e32 v42, v48
	v_rcp_f32_e32 v43, v49
	s_waitcnt lgkmcnt(12)
	v_cvt_f32_f16_e32 v52, v127
	v_cvt_f32_f16_sdwa v53, v127 dst_sel:DWORD dst_unused:UNUSED_PAD src0_sel:WORD_1
	s_waitcnt lgkmcnt(11)
	v_cvt_f32_f16_e32 v58, v129
	v_cvt_f32_f16_sdwa v59, v129 dst_sel:DWORD dst_unused:UNUSED_PAD src0_sel:WORD_1
	v_cvt_f32_f16_e32 v50, v126
	v_cvt_f32_f16_e32 v56, v128
	v_cvt_f32_f16_sdwa v57, v128 dst_sel:DWORD dst_unused:UNUSED_PAD src0_sel:WORD_1
	v_cvt_f32_f16_sdwa v51, v126 dst_sel:DWORD dst_unused:UNUSED_PAD src0_sel:WORD_1
	v_pk_mul_f32 v[36:37], v[54:55], v[52:53]
	v_pk_mul_f32 v[46:47], v[48:49], v[58:59]
	v_pk_mul_f32 v[52:53], v[42:43], v[56:57]
	v_pk_mul_f32 v[42:43], v[42:43], v[50:51]
	v_pk_mul_f32 v[50:51], v[40:41], v[36:37]
	v_pk_mul_f32 v[54:55], v[40:41], v[46:47]
	v_cvt_pk_f16_f32 v36, v36, v37
	v_cvt_pk_f16_f32 v37, v46, v47
	v_pk_mul_f32 v[56:57], v[38:39], v[52:53]
	v_pk_mul_f32 v[58:59], v[38:39], v[42:43]
	ds_write2st64_b32 v191, v36, v37 offset1:18
	v_cvt_pk_f16_f32 v36, v50, v51
	v_cvt_pk_f16_f32 v37, v54, v55
	v_pk_mul_f32 v[52:53], v[0:1], v[52:53]
	ds_write2st64_b32 v191, v36, v37 offset0:36 offset1:54
	v_cvt_pk_f16_f32 v36, v56, v57
	v_cvt_pk_f16_f32 v37, v58, v59
	v_lshl_add_u32 v250, v194, 1, v2
	ds_read_b32 v58, v251 offset:32768
	ds_read2st64_b32 v[134:135], v250 offset0:64 offset1:80
	s_waitcnt lgkmcnt(14)
	ds_read2st64_b32 v[136:137], v250 offset0:96 offset1:112
	s_waitcnt lgkmcnt(14)
	ds_write2st64_b32 v191, v36, v37 offset0:72 offset1:90
	v_cvt_f16_f32_e32 v36, v52
	v_pk_mul_f32 v[42:43], v[0:1], v[42:43]
	v_cvt_f16_f32_e32 v37, v53
	v_cvt_f16_f32_e32 v42, v42
	v_cvt_f16_f32_e32 v43, v43
	s_waitcnt lgkmcnt(14)
	ds_write_b16 v176, v36 offset:10
	s_waitcnt lgkmcnt(14)
	ds_write_b16 v176, v37 offset:50
	s_waitcnt lgkmcnt(14)
	ds_write_b16 v176, v42 offset:5130
	s_waitcnt lgkmcnt(14)
	ds_write_b16 v176, v43 offset:5170
	s_waitcnt lgkmcnt(14)
	ds_write_b16 v176, v60 offset:10250
	v_lshl_add_u32 v50, v192, 1, v2
	v_rcp_f32_e32 v42, v44
	v_rcp_f32_e32 v43, v45
	v_lshl_add_u32 v2, v194, 1, v2
	v_cvt_f32_f16_e32 v52, v131
	v_cvt_f32_f16_sdwa v53, v131 dst_sel:DWORD dst_unused:UNUSED_PAD src0_sel:WORD_1
	v_cvt_f32_f16_e32 v56, v133
	v_cvt_f32_f16_sdwa v57, v133 dst_sel:DWORD dst_unused:UNUSED_PAD src0_sel:WORD_1
	v_cvt_f32_f16_e32 v50, v130
	v_cvt_f32_f16_e32 v54, v132
	v_cvt_f32_f16_sdwa v55, v132 dst_sel:DWORD dst_unused:UNUSED_PAD src0_sel:WORD_1
	v_cvt_f32_f16_sdwa v51, v130 dst_sel:DWORD dst_unused:UNUSED_PAD src0_sel:WORD_1
	v_pk_mul_f32 v[36:37], v[48:49], v[52:53]
	v_pk_mul_f32 v[46:47], v[44:45], v[56:57]
	v_pk_mul_f32 v[48:49], v[42:43], v[54:55]
	v_pk_mul_f32 v[42:43], v[42:43], v[50:51]
	v_pk_mul_f32 v[50:51], v[40:41], v[36:37]
	v_pk_mul_f32 v[52:53], v[40:41], v[46:47]
	v_cvt_pk_f16_f32 v36, v36, v37
	v_cvt_pk_f16_f32 v37, v46, v47
	v_pk_mul_f32 v[54:55], v[38:39], v[48:49]
	v_pk_mul_f32 v[56:57], v[38:39], v[42:43]
	s_waitcnt lgkmcnt(14)
	ds_write2st64_b32 v193, v36, v37 offset1:18
	v_cvt_pk_f16_f32 v36, v50, v51
	v_cvt_pk_f16_f32 v37, v52, v53
	v_pk_mul_f32 v[48:49], v[0:1], v[48:49]
	s_waitcnt lgkmcnt(14)
	ds_write2st64_b32 v193, v36, v37 offset0:36 offset1:54
	v_cvt_pk_f16_f32 v36, v54, v55
	v_cvt_pk_f16_f32 v37, v56, v57
	s_waitcnt lgkmcnt(14)
	ds_write2st64_b32 v193, v36, v37 offset0:72 offset1:90
	v_cvt_f16_f32_e32 v36, v48
	v_pk_mul_f32 v[42:43], v[0:1], v[42:43]
	v_cvt_f16_f32_e32 v37, v49
	v_cvt_f16_f32_e32 v42, v42
	v_cvt_f16_f32_e32 v43, v43
	s_waitcnt lgkmcnt(14)
	ds_write_b16 v176, v36 offset:12
	s_waitcnt lgkmcnt(14)
	ds_write_b16 v176, v37 offset:52
	s_waitcnt lgkmcnt(14)
	ds_write_b16 v176, v42 offset:5132
	s_waitcnt lgkmcnt(14)
	ds_write_b16 v176, v43 offset:5172
	s_waitcnt lgkmcnt(14)
	ds_write_b16 v176, v58 offset:10252
	s_waitcnt lgkmcnt(14)
	ds_read_b32 v2, v250 offset:32768
	v_cvt_f32_f16_e32 v48, v135
	v_cvt_f32_f16_sdwa v49, v135 dst_sel:DWORD dst_unused:UNUSED_PAD src0_sel:WORD_1
	v_cvt_f32_f16_e32 v52, v137
	v_cvt_f32_f16_sdwa v53, v137 dst_sel:DWORD dst_unused:UNUSED_PAD src0_sel:WORD_1
	v_cvt_f32_f16_e32 v46, v134
	v_cvt_f32_f16_e32 v50, v136
	v_cvt_f32_f16_sdwa v51, v136 dst_sel:DWORD dst_unused:UNUSED_PAD src0_sel:WORD_1
	v_cvt_f32_f16_sdwa v47, v134 dst_sel:DWORD dst_unused:UNUSED_PAD src0_sel:WORD_1
	v_pk_mul_f32 v[36:37], v[44:45], v[48:49]
	v_pk_mul_f32 v[42:43], v[38:39], v[52:53]
	v_pk_mul_f32 v[44:45], v[40:41], v[50:51]
	v_pk_mul_f32 v[46:47], v[40:41], v[46:47]
	v_pk_mul_f32 v[48:49], v[40:41], v[36:37]
	v_pk_mul_f32 v[40:41], v[40:41], v[42:43]
	v_cvt_pk_f16_f32 v36, v36, v37
	v_cvt_pk_f16_f32 v37, v42, v43
	v_pk_mul_f32 v[50:51], v[38:39], v[44:45]
	v_pk_mul_f32 v[38:39], v[38:39], v[46:47]
	s_waitcnt lgkmcnt(14)
	ds_write2st64_b32 v195, v36, v37 offset1:18
	v_cvt_pk_f16_f32 v36, v48, v49
	v_cvt_pk_f16_f32 v37, v40, v41
	v_pk_mul_f32 v[44:45], v[0:1], v[44:45]
	s_waitcnt lgkmcnt(14)
	ds_write2st64_b32 v195, v36, v37 offset0:36 offset1:54
	v_cvt_pk_f16_f32 v36, v50, v51
	v_cvt_pk_f16_f32 v37, v38, v39
	s_waitcnt lgkmcnt(14)
	ds_write2st64_b32 v195, v36, v37 offset0:72 offset1:90
	v_cvt_f16_f32_e32 v36, v44
	v_pk_mul_f32 v[46:47], v[0:1], v[46:47]
	v_cvt_f16_f32_e32 v37, v45
	v_cvt_f16_f32_e32 v38, v46
	v_cvt_f16_f32_e32 v39, v47
	s_waitcnt lgkmcnt(14)
	ds_write_b16 v176, v36 offset:14
	s_waitcnt lgkmcnt(14)
	ds_write_b16 v176, v37 offset:54
	s_waitcnt lgkmcnt(14)
	ds_write_b16 v176, v38 offset:5134
	s_waitcnt lgkmcnt(14)
	ds_write_b16 v176, v39 offset:5174
	s_nop 0
	s_waitcnt lgkmcnt(7)
	ds_write_b16 v176, v2 offset:10254
	v_perm_b32 v36, v60, v62, s35
	v_perm_b32 v37, v2, v58, s35
	ds_write_b64 v176, v[36:37] offset:10288
